# radix pass 0 sums packed bin counts as whole dwords; classify pass 2 stores only candidate indices and the refinement fetches keys through them
# speedup vs baseline: 1.0825x; 1.0074x over previous
.LBB0_723:
	s_cmp_lt_i32 s53, 4
	s_cselect_b64 s[14:15], -1, 0
	s_cmp_gt_i32 s53, 3
	v_cmp_ne_u32_e64 s[6:7], 63, v145
	v_cmp_gt_u32_e32 vcc, 32, v145
	s_waitcnt lgkmcnt(0)
	s_barrier
	s_cbranch_scc1 .LBB0_729
	s_lshl_b32 s10, s53, 12
	s_add_i32 s10, s10, 0
	v_lshl_add_u32 v1, v145, 6, s10
	v_add_u32_e32 v1, 0x20000, v1
	ds_read_b128 v[4:7], v1
	ds_read_b128 v[8:11], v1 offset:16
	ds_read_b128 v[12:15], v1 offset:32
	ds_read_b128 v[16:19], v1 offset:48
	s_waitcnt lgkmcnt(3)
	v_add3_u32 v1, v4, v5, v6
	s_waitcnt lgkmcnt(2)
	v_add3_u32 v1, v1, v7, v8
	v_add3_u32 v3, v9, v10, v11
	s_waitcnt lgkmcnt(1)
	v_add3_u32 v1, v1, v12, v13
	v_add3_u32 v3, v3, v14, v15
	s_waitcnt lgkmcnt(0)
	v_add3_u32 v1, v1, v16, v17
	v_add3_u32 v3, v3, v18, v19
	v_and_b32_e32 v5, 63, v147
	v_add_u32_e32 v1, v1, v3
	v_cmp_ne_u32_e64 s[10:11], 63, v5
	v_add_u32_sdwa v8, v1, v1 dst_sel:DWORD dst_unused:UNUSED_PAD src0_sel:WORD_1 src1_sel:WORD_0
	s_nop 0
	v_addc_co_u32_e64 v1, s[10:11], 0, v147, s[10:11]
	v_lshlrev_b32_e32 v1, 2, v1
	ds_bpermute_b32 v3, v1, v8
	s_waitcnt lgkmcnt(0)
	v_cndmask_b32_e64 v3, 0, v3, s[6:7]
	v_cmp_gt_u32_e64 s[6:7], 62, v5
	v_add_u32_e32 v4, v8, v3
	s_nop 0
	v_cndmask_b32_e64 v3, 0, 2, s[6:7]
	v_add_lshl_u32 v3, v3, v147, 2
	ds_bpermute_b32 v6, v3, v4
	v_cmp_gt_u32_e64 s[6:7], 62, v145
	s_waitcnt lgkmcnt(0)
	s_nop 0
	v_cndmask_b32_e64 v6, 0, v6, s[6:7]
	v_cmp_gt_u32_e64 s[6:7], 60, v5
	v_add_u32_e32 v6, v4, v6
	s_nop 0
	v_cndmask_b32_e64 v4, 0, 4, s[6:7]
	v_add_lshl_u32 v4, v4, v147, 2
	ds_bpermute_b32 v7, v4, v6
	v_cmp_gt_u32_e64 s[6:7], 60, v145
	s_waitcnt lgkmcnt(0)
	s_nop 0
	v_cndmask_b32_e64 v7, 0, v7, s[6:7]
	v_cmp_gt_u32_e64 s[6:7], 56, v5
	v_add_u32_e32 v7, v6, v7
	s_nop 0
	v_cndmask_b32_e64 v6, 0, 8, s[6:7]
	v_add_lshl_u32 v6, v6, v147, 2
	ds_bpermute_b32 v9, v6, v7
	v_cmp_gt_u32_e64 s[6:7], 56, v145
	s_waitcnt lgkmcnt(0)
	s_nop 0
	v_cndmask_b32_e64 v9, 0, v9, s[6:7]
	v_cmp_gt_u32_e64 s[6:7], 48, v5
	v_add_u32_e32 v9, v7, v9
	s_nop 0
	v_cndmask_b32_e64 v5, 0, 16, s[6:7]
	v_add_lshl_u32 v7, v5, v147, 2
	ds_bpermute_b32 v5, v7, v9
	s_lshl_b32 s6, s53, 5
	s_add_i32 s12, s6, 0
	v_cmp_gt_u32_e64 s[6:7], 48, v145
	s_waitcnt lgkmcnt(0)
	s_nop 0
	v_cndmask_b32_e64 v5, 0, v5, s[6:7]
	v_add_u32_e32 v9, v9, v5
	ds_bpermute_b32 v10, v153, v9
	s_add_i32 s6, s12, 0x25804
	v_mov_b32_e32 v5, s6
	ds_read_b32 v5, v5
	s_waitcnt lgkmcnt(1)
	v_cndmask_b32_e32 v10, 0, v10, vcc
	v_add_u32_e32 v9, v9, v10
	v_sub_u32_e32 v8, v9, v8
	s_waitcnt lgkmcnt(0)
	v_cmp_lt_u32_e64 s[6:7], v8, v5
	v_cmp_le_u32_e64 s[10:11], v5, v9
	s_and_b64 s[6:7], s[10:11], s[6:7]
	v_cndmask_b32_e64 v9, 0, 1, s[6:7]
	v_cmp_ne_u32_e64 s[6:7], 0, v9
	s_ff1_i32_b64 s10, s[6:7]
	s_cmp_lg_u64 s[6:7], 0
	s_cselect_b32 s16, s10, 0
	v_and_or_b32 v9, v147, 64, s16
	v_lshlrev_b32_e32 v9, 2, v9
	ds_bpermute_b32 v9, v9, v8
	v_cmp_lt_u32_e64 s[6:7], 31, v145
	v_mov_b32_e32 v8, 0
	s_and_saveexec_b64 s[10:11], vcc
	s_cbranch_execz .LBB0_726
	s_lshl_b32 s17, s53, 10
	s_lshl_b32 s18, s16, 6
	s_add_i32 s18, s18, 0
	s_lshl_b32 s17, s17, 2
	v_lshlrev_b32_e32 v8, 1, v145
	s_add_i32 s18, s18, s17
	v_and_b32_e32 v8, 0x7c, v8
	v_add_u32_e32 v8, s18, v8
	v_add_u32_e32 v8, 0x20000, v8
	ds_read_b32 v8, v8
	v_and_b32_e32 v10, 1, v144
	v_cmp_eq_u32_e32 vcc, 0, v10
	s_waitcnt lgkmcnt(0)
	s_nop 0
	v_cndmask_b32_sdwa v8, v8, v8, vcc dst_sel:DWORD dst_unused:UNUSED_PAD src0_sel:WORD_1 src1_sel:WORD_0

.Lcls_A_hi_done:
.Lcls_C_lo:
	v_cmp_ne_u32_e32 vcc, 0, v178
	s_cbranch_vccz .Lcls_C_lo_done
	s_and_saveexec_b64 s[18:19], vcc
	v_ffbh_u32_e32 v191, v178
	v_lshrrev_b32_e32 v193, v191, v189
	v_xor_b32_e32 v178, v178, v193
	v_and_b32_e32 v193, 60, v191
	v_lshl_add_u32 v192, v193, 7, v190
	v_and_b32_e32 v193, 3, v191
	v_add_u32_e32 v192, v192, v193
	v_cmp_gt_u32_e32 vcc, s69, v9
	v_or_b32_e32 v196, s92, v9
	v_lshl_add_u32 v198, v196, 1, s68
	v_add_u32_e32 v9, 1, v9
	s_and_b64 exec, exec, vcc
	ds_write_b16 v198, v192 offset:8192
	s_mov_b64 exec, s[18:19]
	s_branch .Lcls_C_lo
.Lcls_C_lo_done:
.Lcls_C_hi:
	v_cmp_ne_u32_e32 vcc, 0, v179
	s_cbranch_vccz .Lcls_C_hi_done
	s_and_saveexec_b64 s[18:19], vcc
	v_ffbh_u32_e32 v191, v179
	v_lshrrev_b32_e32 v193, v191, v189
	v_xor_b32_e32 v179, v179, v193
	v_and_b32_e32 v193, 60, v191
	v_lshl_add_u32 v192, v193, 7, v190
	v_and_b32_e32 v193, 3, v191
	v_add3_u32 v192, v192, v193, v199
	v_cmp_gt_u32_e32 vcc, s69, v9
	v_or_b32_e32 v196, s92, v9
	v_lshl_add_u32 v198, v196, 1, s68
	v_add_u32_e32 v9, 1, v9
	s_and_b64 exec, exec, vcc
	ds_write_b16 v198, v192 offset:8192
	s_mov_b64 exec, s[18:19]
	s_branch .Lcls_C_hi

.LBB0_875:
	v_cndmask_b32_e64 v3, 0, 1, s[14:15]
	s_and_b64 vcc, exec, s[16:17]
	v_cmp_ne_u32_e64 s[4:5], 1, v3
	s_cbranch_vccz .LBB0_907
	s_and_b64 vcc, exec, s[4:5]
	s_cbranch_vccnz .LBB0_907
	s_lshl_b32 s57, s53, 5
	s_add_i32 s92, s57, 0x25800
	v_mov_b32_e32 v232, s92
	ds_read2_b32 v[234:235], v232 offset0:1 offset1:5
	ds_read2_b32 v[236:237], v232 offset0:0 offset1:2
	s_lshl_b32 s89, s53, 15
	s_lshl_b32 s90, s53, 10
	v_lshl_add_u32 v238, v145, 2, s89
	v_lshl_add_u32 v245, v145, 1, s90
	v_add_u32_e32 v238, 0x20000, v238
	v_add_u32_e32 v245, 0x22000, v245
	s_lshl_b32 s60, s53, 9
	s_add_i32 s60, s60, 0x24000
	v_mov_b32_e32 v246, s60
	s_add_i32 s60, s90, 0x24800
	v_mov_b32_e32 v244, s60
	s_waitcnt lgkmcnt(0)
	v_readfirstlane_b32 s91, v234
	v_readfirstlane_b32 s93, v235
	v_readfirstlane_b32 s33, v236
	v_readfirstlane_b32 s90, v237
	s_lshl_b32 s33, s33, 21
	s_add_i32 s60, s93, 63
	s_lshr_b32 s60, s60, 6
	s_cmp_le_u32 s60, 1
	s_cbranch_scc1 .Lref_v1
	s_cmp_le_u32 s60, 2
	s_cbranch_scc1 .Lref_v2
	s_cmp_le_u32 s60, 3
	s_cbranch_scc1 .Lref_v3
	s_cmp_le_u32 s60, 4
	s_cbranch_scc1 .Lref_v4
	s_cmp_le_u32 s60, 5
	s_cbranch_scc1 .Lref_v5
	s_cmp_le_u32 s60, 6
	s_cbranch_scc1 .Lref_v6
	s_cmp_le_u32 s60, 7
	s_cbranch_scc1 .Lref_v7
.Lref_v8:
	ds_read_u16 v224, v245
	ds_read_u16 v225, v245 offset:128
	ds_read_u16 v226, v245 offset:256
	ds_read_u16 v227, v245 offset:384
	ds_read_u16 v228, v245 offset:512
	ds_read_u16 v229, v245 offset:640
	ds_read_u16 v230, v245 offset:768
	ds_read_u16 v231, v245 offset:896
	v_cmp_gt_u32_e64 s[8:9], s93, v145
	v_add_u32_e32 v241, 64, v145
	v_cmp_gt_u32_e64 s[12:13], s93, v241
	v_add_u32_e32 v241, 128, v145
	v_cmp_gt_u32_e64 s[14:15], s93, v241
	v_add_u32_e32 v241, 192, v145
	v_cmp_gt_u32_e64 s[16:17], s93, v241
	v_add_u32_e32 v241, 256, v145
	v_cmp_gt_u32_e64 s[18:19], s93, v241
	v_add_u32_e32 v241, 320, v145
	v_cmp_gt_u32_e64 s[22:23], s93, v241
	v_add_u32_e32 v241, 384, v145
	v_cmp_gt_u32_e64 s[24:25], s93, v241
	v_add_u32_e32 v241, 448, v145
	v_cmp_gt_u32_e64 s[58:59], s93, v241
	s_waitcnt lgkmcnt(0)
	v_cndmask_b32_e64 v248, 0, v224, s[8:9]
	v_cndmask_b32_e64 v249, 0, v225, s[12:13]
	v_cndmask_b32_e64 v250, 0, v226, s[14:15]
	v_cndmask_b32_e64 v251, 0, v227, s[16:17]
	v_cndmask_b32_e64 v252, 0, v228, s[18:19]
	v_cndmask_b32_e64 v253, 0, v229, s[22:23]
	v_cndmask_b32_e64 v254, 0, v230, s[24:25]
	v_cndmask_b32_e64 v255, 0, v231, s[58:59]
	v_lshl_add_u32 v248, v248, 2, s89
	v_lshl_add_u32 v249, v249, 2, s89
	v_lshl_add_u32 v250, v250, 2, s89
	v_lshl_add_u32 v251, v251, 2, s89
	v_lshl_add_u32 v252, v252, 2, s89
	v_lshl_add_u32 v253, v253, 2, s89
	v_lshl_add_u32 v254, v254, 2, s89
	v_lshl_add_u32 v255, v255, 2, s89
	ds_read_b32 v216, v248
	ds_read_b32 v217, v249
	ds_read_b32 v218, v250
	ds_read_b32 v219, v251
	ds_read_b32 v220, v252
	ds_read_b32 v221, v253
	ds_read_b32 v222, v254
	ds_read_b32 v223, v255
	s_waitcnt lgkmcnt(0)
	v_cndmask_b32_e64 v216, 0, v216, s[8:9]
	v_cndmask_b32_e64 v217, 0, v217, s[12:13]
	v_cndmask_b32_e64 v218, 0, v218, s[14:15]
	v_cndmask_b32_e64 v219, 0, v219, s[16:17]
	v_cndmask_b32_e64 v220, 0, v220, s[18:19]
	v_cndmask_b32_e64 v221, 0, v221, s[22:23]
	v_cndmask_b32_e64 v222, 0, v222, s[24:25]
	v_cndmask_b32_e64 v223, 0, v223, s[58:59]
	s_or_b32 s57, s33, 0x100000
	v_cmp_ge_u32_e64 s[8:9], v216, s57
	v_cmp_ge_u32_e64 s[12:13], v217, s57
	v_cmp_ge_u32_e64 s[14:15], v218, s57
	v_cmp_ge_u32_e64 s[16:17], v219, s57
	v_cmp_ge_u32_e64 s[18:19], v220, s57
	v_cmp_ge_u32_e64 s[22:23], v221, s57
	v_cmp_ge_u32_e64 s[24:25], v222, s57
	v_cmp_ge_u32_e64 s[58:59], v223, s57
	s_bcnt1_i32_b64 s89, s[8:9]
	s_bcnt1_i32_b64 s61, s[12:13]
	s_add_u32 s89, s89, s61
	s_bcnt1_i32_b64 s61, s[14:15]
	s_add_u32 s89, s89, s61
	s_bcnt1_i32_b64 s61, s[16:17]
	s_add_u32 s89, s89, s61
	s_bcnt1_i32_b64 s61, s[18:19]
	s_add_u32 s89, s89, s61
	s_bcnt1_i32_b64 s61, s[22:23]
	s_add_u32 s89, s89, s61
	s_bcnt1_i32_b64 s61, s[24:25]
	s_add_u32 s89, s89, s61
	s_bcnt1_i32_b64 s61, s[58:59]
	s_add_u32 s89, s89, s61
	s_cmp_ge_u32 s89, s91
	s_cselect_b32 s33, s57, s33
	s_cmp_eq_u32 s89, s91
	s_cbranch_scc1 .Lref_e8
	s_or_b32 s57, s33, 0x80000
	v_cmp_ge_u32_e64 s[8:9], v216, s57
	v_cmp_ge_u32_e64 s[12:13], v217, s57
	v_cmp_ge_u32_e64 s[14:15], v218, s57
	v_cmp_ge_u32_e64 s[16:17], v219, s57
	v_cmp_ge_u32_e64 s[18:19], v220, s57
	v_cmp_ge_u32_e64 s[22:23], v221, s57
	v_cmp_ge_u32_e64 s[24:25], v222, s57
	v_cmp_ge_u32_e64 s[58:59], v223, s57
	s_bcnt1_i32_b64 s89, s[8:9]
	s_bcnt1_i32_b64 s61, s[12:13]
	s_add_u32 s89, s89, s61
	s_bcnt1_i32_b64 s61, s[14:15]
	s_add_u32 s89, s89, s61
	s_bcnt1_i32_b64 s61, s[16:17]
	s_add_u32 s89, s89, s61
	s_bcnt1_i32_b64 s61, s[18:19]
	s_add_u32 s89, s89, s61
	s_bcnt1_i32_b64 s61, s[22:23]
	s_add_u32 s89, s89, s61
	s_bcnt1_i32_b64 s61, s[24:25]
	s_add_u32 s89, s89, s61
	s_bcnt1_i32_b64 s61, s[58:59]
	s_add_u32 s89, s89, s61
	s_cmp_ge_u32 s89, s91
	s_cselect_b32 s33, s57, s33
	s_cmp_eq_u32 s89, s91
	s_cbranch_scc1 .Lref_e8
	s_or_b32 s57, s33, 0x40000
	v_cmp_ge_u32_e64 s[8:9], v216, s57
	v_cmp_ge_u32_e64 s[12:13], v217, s57
	v_cmp_ge_u32_e64 s[14:15], v218, s57
	v_cmp_ge_u32_e64 s[16:17], v219, s57
	v_cmp_ge_u32_e64 s[18:19], v220, s57
	v_cmp_ge_u32_e64 s[22:23], v221, s57
	v_cmp_ge_u32_e64 s[24:25], v222, s57
	v_cmp_ge_u32_e64 s[58:59], v223, s57
	s_bcnt1_i32_b64 s89, s[8:9]
	s_bcnt1_i32_b64 s61, s[12:13]
	s_add_u32 s89, s89, s61
	s_bcnt1_i32_b64 s61, s[14:15]
	s_add_u32 s89, s89, s61
	s_bcnt1_i32_b64 s61, s[16:17]
	s_add_u32 s89, s89, s61
	s_bcnt1_i32_b64 s61, s[18:19]
	s_add_u32 s89, s89, s61
	s_bcnt1_i32_b64 s61, s[22:23]
	s_add_u32 s89, s89, s61
	s_bcnt1_i32_b64 s61, s[24:25]
	s_add_u32 s89, s89, s61
	s_bcnt1_i32_b64 s61, s[58:59]
	s_add_u32 s89, s89, s61
	s_cmp_ge_u32 s89, s91
	s_cselect_b32 s33, s57, s33
	s_cmp_eq_u32 s89, s91
	s_cbranch_scc1 .Lref_e8
	s_or_b32 s57, s33, 0x20000
	v_cmp_ge_u32_e64 s[8:9], v216, s57
	v_cmp_ge_u32_e64 s[12:13], v217, s57
	v_cmp_ge_u32_e64 s[14:15], v218, s57
	v_cmp_ge_u32_e64 s[16:17], v219, s57
	v_cmp_ge_u32_e64 s[18:19], v220, s57
	v_cmp_ge_u32_e64 s[22:23], v221, s57
	v_cmp_ge_u32_e64 s[24:25], v222, s57
	v_cmp_ge_u32_e64 s[58:59], v223, s57
	s_bcnt1_i32_b64 s89, s[8:9]
	s_bcnt1_i32_b64 s61, s[12:13]
	s_add_u32 s89, s89, s61
	s_bcnt1_i32_b64 s61, s[14:15]
	s_add_u32 s89, s89, s61
	s_bcnt1_i32_b64 s61, s[16:17]
	s_add_u32 s89, s89, s61
	s_bcnt1_i32_b64 s61, s[18:19]
	s_add_u32 s89, s89, s61
	s_bcnt1_i32_b64 s61, s[22:23]
	s_add_u32 s89, s89, s61
	s_bcnt1_i32_b64 s61, s[24:25]
	s_add_u32 s89, s89, s61
	s_bcnt1_i32_b64 s61, s[58:59]
	s_add_u32 s89, s89, s61
	s_cmp_ge_u32 s89, s91
	s_cselect_b32 s33, s57, s33
	s_cmp_eq_u32 s89, s91
	s_cbranch_scc1 .Lref_e8
	s_or_b32 s57, s33, 0x10000
	v_cmp_ge_u32_e64 s[8:9], v216, s57
	v_cmp_ge_u32_e64 s[12:13], v217, s57
	v_cmp_ge_u32_e64 s[14:15], v218, s57
	v_cmp_ge_u32_e64 s[16:17], v219, s57
	v_cmp_ge_u32_e64 s[18:19], v220, s57
	v_cmp_ge_u32_e64 s[22:23], v221, s57
	v_cmp_ge_u32_e64 s[24:25], v222, s57
	v_cmp_ge_u32_e64 s[58:59], v223, s57
	s_bcnt1_i32_b64 s89, s[8:9]
	s_bcnt1_i32_b64 s61, s[12:13]
	s_add_u32 s89, s89, s61
	s_bcnt1_i32_b64 s61, s[14:15]
	s_add_u32 s89, s89, s61
	s_bcnt1_i32_b64 s61, s[16:17]
	s_add_u32 s89, s89, s61
	s_bcnt1_i32_b64 s61, s[18:19]
	s_add_u32 s89, s89, s61
	s_bcnt1_i32_b64 s61, s[22:23]
	s_add_u32 s89, s89, s61
	s_bcnt1_i32_b64 s61, s[24:25]
	s_add_u32 s89, s89, s61
	s_bcnt1_i32_b64 s61, s[58:59]
	s_add_u32 s89, s89, s61
	s_cmp_ge_u32 s89, s91
	s_cselect_b32 s33, s57, s33
	s_cmp_eq_u32 s89, s91
	s_cbranch_scc1 .Lref_e8
	s_or_b32 s57, s33, 0x8000
	v_cmp_ge_u32_e64 s[8:9], v216, s57
	v_cmp_ge_u32_e64 s[12:13], v217, s57
	v_cmp_ge_u32_e64 s[14:15], v218, s57
	v_cmp_ge_u32_e64 s[16:17], v219, s57
	v_cmp_ge_u32_e64 s[18:19], v220, s57
	v_cmp_ge_u32_e64 s[22:23], v221, s57
	v_cmp_ge_u32_e64 s[24:25], v222, s57
	v_cmp_ge_u32_e64 s[58:59], v223, s57
	s_bcnt1_i32_b64 s89, s[8:9]
	s_bcnt1_i32_b64 s61, s[12:13]
	s_add_u32 s89, s89, s61
	s_bcnt1_i32_b64 s61, s[14:15]
	s_add_u32 s89, s89, s61
	s_bcnt1_i32_b64 s61, s[16:17]
	s_add_u32 s89, s89, s61
	s_bcnt1_i32_b64 s61, s[18:19]
	s_add_u32 s89, s89, s61
	s_bcnt1_i32_b64 s61, s[22:23]
	s_add_u32 s89, s89, s61
	s_bcnt1_i32_b64 s61, s[24:25]
	s_add_u32 s89, s89, s61
	s_bcnt1_i32_b64 s61, s[58:59]
	s_add_u32 s89, s89, s61
	s_cmp_ge_u32 s89, s91
	s_cselect_b32 s33, s57, s33
	s_cmp_eq_u32 s89, s91
	s_cbranch_scc1 .Lref_e8
	s_or_b32 s57, s33, 0x4000
	v_cmp_ge_u32_e64 s[8:9], v216, s57
	v_cmp_ge_u32_e64 s[12:13], v217, s57
	v_cmp_ge_u32_e64 s[14:15], v218, s57
	v_cmp_ge_u32_e64 s[16:17], v219, s57
	v_cmp_ge_u32_e64 s[18:19], v220, s57
	v_cmp_ge_u32_e64 s[22:23], v221, s57
	v_cmp_ge_u32_e64 s[24:25], v222, s57
	v_cmp_ge_u32_e64 s[58:59], v223, s57
	s_bcnt1_i32_b64 s89, s[8:9]
	s_bcnt1_i32_b64 s61, s[12:13]
	s_add_u32 s89, s89, s61
	s_bcnt1_i32_b64 s61, s[14:15]
	s_add_u32 s89, s89, s61
	s_bcnt1_i32_b64 s61, s[16:17]
	s_add_u32 s89, s89, s61
	s_bcnt1_i32_b64 s61, s[18:19]
	s_add_u32 s89, s89, s61
	s_bcnt1_i32_b64 s61, s[22:23]
	s_add_u32 s89, s89, s61
	s_bcnt1_i32_b64 s61, s[24:25]
	s_add_u32 s89, s89, s61
	s_bcnt1_i32_b64 s61, s[58:59]
	s_add_u32 s89, s89, s61
	s_cmp_ge_u32 s89, s91
	s_cselect_b32 s33, s57, s33
	s_cmp_eq_u32 s89, s91
	s_cbranch_scc1 .Lref_e8
	s_or_b32 s57, s33, 0x2000
	v_cmp_ge_u32_e64 s[8:9], v216, s57
	v_cmp_ge_u32_e64 s[12:13], v217, s57
	v_cmp_ge_u32_e64 s[14:15], v218, s57
	v_cmp_ge_u32_e64 s[16:17], v219, s57
	v_cmp_ge_u32_e64 s[18:19], v220, s57
	v_cmp_ge_u32_e64 s[22:23], v221, s57
	v_cmp_ge_u32_e64 s[24:25], v222, s57
	v_cmp_ge_u32_e64 s[58:59], v223, s57
	s_bcnt1_i32_b64 s89, s[8:9]
	s_bcnt1_i32_b64 s61, s[12:13]
	s_add_u32 s89, s89, s61
	s_bcnt1_i32_b64 s61, s[14:15]
	s_add_u32 s89, s89, s61
	s_bcnt1_i32_b64 s61, s[16:17]
	s_add_u32 s89, s89, s61
	s_bcnt1_i32_b64 s61, s[18:19]
	s_add_u32 s89, s89, s61
	s_bcnt1_i32_b64 s61, s[22:23]
	s_add_u32 s89, s89, s61
	s_bcnt1_i32_b64 s61, s[24:25]
	s_add_u32 s89, s89, s61
	s_bcnt1_i32_b64 s61, s[58:59]
	s_add_u32 s89, s89, s61
	s_cmp_ge_u32 s89, s91
	s_cselect_b32 s33, s57, s33
	s_cmp_eq_u32 s89, s91
	s_cbranch_scc1 .Lref_e8
	s_or_b32 s57, s33, 0x1000
	v_cmp_ge_u32_e64 s[8:9], v216, s57
	v_cmp_ge_u32_e64 s[12:13], v217, s57
	v_cmp_ge_u32_e64 s[14:15], v218, s57
	v_cmp_ge_u32_e64 s[16:17], v219, s57
	v_cmp_ge_u32_e64 s[18:19], v220, s57
	v_cmp_ge_u32_e64 s[22:23], v221, s57
	v_cmp_ge_u32_e64 s[24:25], v222, s57
	v_cmp_ge_u32_e64 s[58:59], v223, s57
	s_bcnt1_i32_b64 s89, s[8:9]
	s_bcnt1_i32_b64 s61, s[12:13]
	s_add_u32 s89, s89, s61
	s_bcnt1_i32_b64 s61, s[14:15]
	s_add_u32 s89, s89, s61
	s_bcnt1_i32_b64 s61, s[16:17]
	s_add_u32 s89, s89, s61
	s_bcnt1_i32_b64 s61, s[18:19]
	s_add_u32 s89, s89, s61
	s_bcnt1_i32_b64 s61, s[22:23]
	s_add_u32 s89, s89, s61
	s_bcnt1_i32_b64 s61, s[24:25]
	s_add_u32 s89, s89, s61
	s_bcnt1_i32_b64 s61, s[58:59]
	s_add_u32 s89, s89, s61
	s_cmp_ge_u32 s89, s91
	s_cselect_b32 s33, s57, s33
	s_cmp_eq_u32 s89, s91
	s_cbranch_scc1 .Lref_e8
	s_or_b32 s57, s33, 0x800
	v_cmp_ge_u32_e64 s[8:9], v216, s57
	v_cmp_ge_u32_e64 s[12:13], v217, s57
	v_cmp_ge_u32_e64 s[14:15], v218, s57
	v_cmp_ge_u32_e64 s[16:17], v219, s57
	v_cmp_ge_u32_e64 s[18:19], v220, s57
	v_cmp_ge_u32_e64 s[22:23], v221, s57
	v_cmp_ge_u32_e64 s[24:25], v222, s57
	v_cmp_ge_u32_e64 s[58:59], v223, s57
	s_bcnt1_i32_b64 s89, s[8:9]
	s_bcnt1_i32_b64 s61, s[12:13]
	s_add_u32 s89, s89, s61
	s_bcnt1_i32_b64 s61, s[14:15]
	s_add_u32 s89, s89, s61
	s_bcnt1_i32_b64 s61, s[16:17]
	s_add_u32 s89, s89, s61
	s_bcnt1_i32_b64 s61, s[18:19]
	s_add_u32 s89, s89, s61
	s_bcnt1_i32_b64 s61, s[22:23]
	s_add_u32 s89, s89, s61
	s_bcnt1_i32_b64 s61, s[24:25]
	s_add_u32 s89, s89, s61
	s_bcnt1_i32_b64 s61, s[58:59]
	s_add_u32 s89, s89, s61
	s_cmp_ge_u32 s89, s91
	s_cselect_b32 s33, s57, s33
	s_cmp_eq_u32 s89, s91
	s_cbranch_scc1 .Lref_e8
	s_or_b32 s57, s33, 0x400
	v_cmp_ge_u32_e64 s[8:9], v216, s57
	v_cmp_ge_u32_e64 s[12:13], v217, s57
	v_cmp_ge_u32_e64 s[14:15], v218, s57
	v_cmp_ge_u32_e64 s[16:17], v219, s57
	v_cmp_ge_u32_e64 s[18:19], v220, s57
	v_cmp_ge_u32_e64 s[22:23], v221, s57
	v_cmp_ge_u32_e64 s[24:25], v222, s57
	v_cmp_ge_u32_e64 s[58:59], v223, s57
	s_bcnt1_i32_b64 s89, s[8:9]
	s_bcnt1_i32_b64 s61, s[12:13]
	s_add_u32 s89, s89, s61
	s_bcnt1_i32_b64 s61, s[14:15]
	s_add_u32 s89, s89, s61
	s_bcnt1_i32_b64 s61, s[16:17]
	s_add_u32 s89, s89, s61
	s_bcnt1_i32_b64 s61, s[18:19]
	s_add_u32 s89, s89, s61
	s_bcnt1_i32_b64 s61, s[22:23]
	s_add_u32 s89, s89, s61
	s_bcnt1_i32_b64 s61, s[24:25]
	s_add_u32 s89, s89, s61
	s_bcnt1_i32_b64 s61, s[58:59]
	s_add_u32 s89, s89, s61
	s_cmp_ge_u32 s89, s91
	s_cselect_b32 s33, s57, s33
	s_cmp_eq_u32 s89, s91
	s_cbranch_scc1 .Lref_e8
	s_or_b32 s57, s33, 0x200
	v_cmp_ge_u32_e64 s[8:9], v216, s57
	v_cmp_ge_u32_e64 s[12:13], v217, s57
	v_cmp_ge_u32_e64 s[14:15], v218, s57
	v_cmp_ge_u32_e64 s[16:17], v219, s57
	v_cmp_ge_u32_e64 s[18:19], v220, s57
	v_cmp_ge_u32_e64 s[22:23], v221, s57
	v_cmp_ge_u32_e64 s[24:25], v222, s57
	v_cmp_ge_u32_e64 s[58:59], v223, s57
	s_bcnt1_i32_b64 s89, s[8:9]
	s_bcnt1_i32_b64 s61, s[12:13]
	s_add_u32 s89, s89, s61
	s_bcnt1_i32_b64 s61, s[14:15]
	s_add_u32 s89, s89, s61
	s_bcnt1_i32_b64 s61, s[16:17]
	s_add_u32 s89, s89, s61
	s_bcnt1_i32_b64 s61, s[18:19]
	s_add_u32 s89, s89, s61
	s_bcnt1_i32_b64 s61, s[22:23]
	s_add_u32 s89, s89, s61
	s_bcnt1_i32_b64 s61, s[24:25]
	s_add_u32 s89, s89, s61
	s_bcnt1_i32_b64 s61, s[58:59]
	s_add_u32 s89, s89, s61
	s_cmp_ge_u32 s89, s91
	s_cselect_b32 s33, s57, s33
	s_cmp_eq_u32 s89, s91
	s_cbranch_scc1 .Lref_e8
	s_or_b32 s57, s33, 0x100
	v_cmp_ge_u32_e64 s[8:9], v216, s57
	v_cmp_ge_u32_e64 s[12:13], v217, s57
	v_cmp_ge_u32_e64 s[14:15], v218, s57
	v_cmp_ge_u32_e64 s[16:17], v219, s57
	v_cmp_ge_u32_e64 s[18:19], v220, s57
	v_cmp_ge_u32_e64 s[22:23], v221, s57
	v_cmp_ge_u32_e64 s[24:25], v222, s57
	v_cmp_ge_u32_e64 s[58:59], v223, s57
	s_bcnt1_i32_b64 s89, s[8:9]
	s_bcnt1_i32_b64 s61, s[12:13]
	s_add_u32 s89, s89, s61
	s_bcnt1_i32_b64 s61, s[14:15]
	s_add_u32 s89, s89, s61
	s_bcnt1_i32_b64 s61, s[16:17]
	s_add_u32 s89, s89, s61
	s_bcnt1_i32_b64 s61, s[18:19]
	s_add_u32 s89, s89, s61
	s_bcnt1_i32_b64 s61, s[22:23]
	s_add_u32 s89, s89, s61
	s_bcnt1_i32_b64 s61, s[24:25]
	s_add_u32 s89, s89, s61
	s_bcnt1_i32_b64 s61, s[58:59]
	s_add_u32 s89, s89, s61
	s_cmp_ge_u32 s89, s91
	s_cselect_b32 s33, s57, s33
	s_cmp_eq_u32 s89, s91
	s_cbranch_scc1 .Lref_e8
	s_or_b32 s57, s33, 0x80
	v_cmp_ge_u32_e64 s[8:9], v216, s57
	v_cmp_ge_u32_e64 s[12:13], v217, s57
	v_cmp_ge_u32_e64 s[14:15], v218, s57
	v_cmp_ge_u32_e64 s[16:17], v219, s57
	v_cmp_ge_u32_e64 s[18:19], v220, s57
	v_cmp_ge_u32_e64 s[22:23], v221, s57
	v_cmp_ge_u32_e64 s[24:25], v222, s57
	v_cmp_ge_u32_e64 s[58:59], v223, s57
	s_bcnt1_i32_b64 s89, s[8:9]
	s_bcnt1_i32_b64 s61, s[12:13]
	s_add_u32 s89, s89, s61
	s_bcnt1_i32_b64 s61, s[14:15]
	s_add_u32 s89, s89, s61
	s_bcnt1_i32_b64 s61, s[16:17]
	s_add_u32 s89, s89, s61
	s_bcnt1_i32_b64 s61, s[18:19]
	s_add_u32 s89, s89, s61
	s_bcnt1_i32_b64 s61, s[22:23]
	s_add_u32 s89, s89, s61
	s_bcnt1_i32_b64 s61, s[24:25]
	s_add_u32 s89, s89, s61
	s_bcnt1_i32_b64 s61, s[58:59]
	s_add_u32 s89, s89, s61
	s_cmp_ge_u32 s89, s91
	s_cselect_b32 s33, s57, s33
	s_cmp_eq_u32 s89, s91
	s_cbranch_scc1 .Lref_e8
	s_or_b32 s57, s33, 0x40
	v_cmp_ge_u32_e64 s[8:9], v216, s57
	v_cmp_ge_u32_e64 s[12:13], v217, s57
	v_cmp_ge_u32_e64 s[14:15], v218, s57
	v_cmp_ge_u32_e64 s[16:17], v219, s57
	v_cmp_ge_u32_e64 s[18:19], v220, s57
	v_cmp_ge_u32_e64 s[22:23], v221, s57
	v_cmp_ge_u32_e64 s[24:25], v222, s57
	v_cmp_ge_u32_e64 s[58:59], v223, s57
	s_bcnt1_i32_b64 s89, s[8:9]
	s_bcnt1_i32_b64 s61, s[12:13]
	s_add_u32 s89, s89, s61
	s_bcnt1_i32_b64 s61, s[14:15]
	s_add_u32 s89, s89, s61
	s_bcnt1_i32_b64 s61, s[16:17]
	s_add_u32 s89, s89, s61
	s_bcnt1_i32_b64 s61, s[18:19]
	s_add_u32 s89, s89, s61
	s_bcnt1_i32_b64 s61, s[22:23]
	s_add_u32 s89, s89, s61
	s_bcnt1_i32_b64 s61, s[24:25]
	s_add_u32 s89, s89, s61
	s_bcnt1_i32_b64 s61, s[58:59]
	s_add_u32 s89, s89, s61
	s_cmp_ge_u32 s89, s91
	s_cselect_b32 s33, s57, s33
	s_cmp_eq_u32 s89, s91
	s_cbranch_scc1 .Lref_e8
	s_or_b32 s57, s33, 0x20
	v_cmp_ge_u32_e64 s[8:9], v216, s57
	v_cmp_ge_u32_e64 s[12:13], v217, s57
	v_cmp_ge_u32_e64 s[14:15], v218, s57
	v_cmp_ge_u32_e64 s[16:17], v219, s57
	v_cmp_ge_u32_e64 s[18:19], v220, s57
	v_cmp_ge_u32_e64 s[22:23], v221, s57
	v_cmp_ge_u32_e64 s[24:25], v222, s57
	v_cmp_ge_u32_e64 s[58:59], v223, s57
	s_bcnt1_i32_b64 s89, s[8:9]
	s_bcnt1_i32_b64 s61, s[12:13]
	s_add_u32 s89, s89, s61
	s_bcnt1_i32_b64 s61, s[14:15]
	s_add_u32 s89, s89, s61
	s_bcnt1_i32_b64 s61, s[16:17]
	s_add_u32 s89, s89, s61
	s_bcnt1_i32_b64 s61, s[18:19]
	s_add_u32 s89, s89, s61
	s_bcnt1_i32_b64 s61, s[22:23]
	s_add_u32 s89, s89, s61
	s_bcnt1_i32_b64 s61, s[24:25]
	s_add_u32 s89, s89, s61
	s_bcnt1_i32_b64 s61, s[58:59]
	s_add_u32 s89, s89, s61
	s_cmp_ge_u32 s89, s91
	s_cselect_b32 s33, s57, s33
	s_cmp_eq_u32 s89, s91
	s_cbranch_scc1 .Lref_e8
	s_or_b32 s57, s33, 0x10
	v_cmp_ge_u32_e64 s[8:9], v216, s57
	v_cmp_ge_u32_e64 s[12:13], v217, s57
	v_cmp_ge_u32_e64 s[14:15], v218, s57
	v_cmp_ge_u32_e64 s[16:17], v219, s57
	v_cmp_ge_u32_e64 s[18:19], v220, s57
	v_cmp_ge_u32_e64 s[22:23], v221, s57
	v_cmp_ge_u32_e64 s[24:25], v222, s57
	v_cmp_ge_u32_e64 s[58:59], v223, s57
	s_bcnt1_i32_b64 s89, s[8:9]
	s_bcnt1_i32_b64 s61, s[12:13]
	s_add_u32 s89, s89, s61
	s_bcnt1_i32_b64 s61, s[14:15]
	s_add_u32 s89, s89, s61
	s_bcnt1_i32_b64 s61, s[16:17]
	s_add_u32 s89, s89, s61
	s_bcnt1_i32_b64 s61, s[18:19]
	s_add_u32 s89, s89, s61
	s_bcnt1_i32_b64 s61, s[22:23]
	s_add_u32 s89, s89, s61
	s_bcnt1_i32_b64 s61, s[24:25]
	s_add_u32 s89, s89, s61
	s_bcnt1_i32_b64 s61, s[58:59]
	s_add_u32 s89, s89, s61
	s_cmp_ge_u32 s89, s91
	s_cselect_b32 s33, s57, s33
	s_cmp_eq_u32 s89, s91
	s_cbranch_scc1 .Lref_e8
	s_or_b32 s57, s33, 0x8
	v_cmp_ge_u32_e64 s[8:9], v216, s57
	v_cmp_ge_u32_e64 s[12:13], v217, s57
	v_cmp_ge_u32_e64 s[14:15], v218, s57
	v_cmp_ge_u32_e64 s[16:17], v219, s57
	v_cmp_ge_u32_e64 s[18:19], v220, s57
	v_cmp_ge_u32_e64 s[22:23], v221, s57
	v_cmp_ge_u32_e64 s[24:25], v222, s57
	v_cmp_ge_u32_e64 s[58:59], v223, s57
	s_bcnt1_i32_b64 s89, s[8:9]
	s_bcnt1_i32_b64 s61, s[12:13]
	s_add_u32 s89, s89, s61
	s_bcnt1_i32_b64 s61, s[14:15]
	s_add_u32 s89, s89, s61
	s_bcnt1_i32_b64 s61, s[16:17]
	s_add_u32 s89, s89, s61
	s_bcnt1_i32_b64 s61, s[18:19]
	s_add_u32 s89, s89, s61
	s_bcnt1_i32_b64 s61, s[22:23]
	s_add_u32 s89, s89, s61
	s_bcnt1_i32_b64 s61, s[24:25]
	s_add_u32 s89, s89, s61
	s_bcnt1_i32_b64 s61, s[58:59]
	s_add_u32 s89, s89, s61
	s_cmp_ge_u32 s89, s91
	s_cselect_b32 s33, s57, s33
	s_cmp_eq_u32 s89, s91
	s_cbranch_scc1 .Lref_e8
	s_or_b32 s57, s33, 0x4
	v_cmp_ge_u32_e64 s[8:9], v216, s57
	v_cmp_ge_u32_e64 s[12:13], v217, s57
	v_cmp_ge_u32_e64 s[14:15], v218, s57
	v_cmp_ge_u32_e64 s[16:17], v219, s57
	v_cmp_ge_u32_e64 s[18:19], v220, s57
	v_cmp_ge_u32_e64 s[22:23], v221, s57
	v_cmp_ge_u32_e64 s[24:25], v222, s57
	v_cmp_ge_u32_e64 s[58:59], v223, s57
	s_bcnt1_i32_b64 s89, s[8:9]
	s_bcnt1_i32_b64 s61, s[12:13]
	s_add_u32 s89, s89, s61
	s_bcnt1_i32_b64 s61, s[14:15]
	s_add_u32 s89, s89, s61
	s_bcnt1_i32_b64 s61, s[16:17]
	s_add_u32 s89, s89, s61
	s_bcnt1_i32_b64 s61, s[18:19]
	s_add_u32 s89, s89, s61
	s_bcnt1_i32_b64 s61, s[22:23]
	s_add_u32 s89, s89, s61
	s_bcnt1_i32_b64 s61, s[24:25]
	s_add_u32 s89, s89, s61
	s_bcnt1_i32_b64 s61, s[58:59]
	s_add_u32 s89, s89, s61
	s_cmp_ge_u32 s89, s91
	s_cselect_b32 s33, s57, s33
	s_cmp_eq_u32 s89, s91
	s_cbranch_scc1 .Lref_e8
	s_or_b32 s57, s33, 0x2
	v_cmp_ge_u32_e64 s[8:9], v216, s57
	v_cmp_ge_u32_e64 s[12:13], v217, s57
	v_cmp_ge_u32_e64 s[14:15], v218, s57
	v_cmp_ge_u32_e64 s[16:17], v219, s57
	v_cmp_ge_u32_e64 s[18:19], v220, s57
	v_cmp_ge_u32_e64 s[22:23], v221, s57
	v_cmp_ge_u32_e64 s[24:25], v222, s57
	v_cmp_ge_u32_e64 s[58:59], v223, s57
	s_bcnt1_i32_b64 s89, s[8:9]
	s_bcnt1_i32_b64 s61, s[12:13]
	s_add_u32 s89, s89, s61
	s_bcnt1_i32_b64 s61, s[14:15]
	s_add_u32 s89, s89, s61
	s_bcnt1_i32_b64 s61, s[16:17]
	s_add_u32 s89, s89, s61
	s_bcnt1_i32_b64 s61, s[18:19]
	s_add_u32 s89, s89, s61
	s_bcnt1_i32_b64 s61, s[22:23]
	s_add_u32 s89, s89, s61
	s_bcnt1_i32_b64 s61, s[24:25]
	s_add_u32 s89, s89, s61
	s_bcnt1_i32_b64 s61, s[58:59]
	s_add_u32 s89, s89, s61
	s_cmp_ge_u32 s89, s91
	s_cselect_b32 s33, s57, s33
	s_cmp_eq_u32 s89, s91
	s_cbranch_scc1 .Lref_e8
	s_or_b32 s57, s33, 0x1
	v_cmp_ge_u32_e64 s[8:9], v216, s57
	v_cmp_ge_u32_e64 s[12:13], v217, s57
	v_cmp_ge_u32_e64 s[14:15], v218, s57
	v_cmp_ge_u32_e64 s[16:17], v219, s57
	v_cmp_ge_u32_e64 s[18:19], v220, s57
	v_cmp_ge_u32_e64 s[22:23], v221, s57
	v_cmp_ge_u32_e64 s[24:25], v222, s57
	v_cmp_ge_u32_e64 s[58:59], v223, s57
	s_bcnt1_i32_b64 s89, s[8:9]
	s_bcnt1_i32_b64 s61, s[12:13]
	s_add_u32 s89, s89, s61
	s_bcnt1_i32_b64 s61, s[14:15]
	s_add_u32 s89, s89, s61
	s_bcnt1_i32_b64 s61, s[16:17]
	s_add_u32 s89, s89, s61
	s_bcnt1_i32_b64 s61, s[18:19]
	s_add_u32 s89, s89, s61
	s_bcnt1_i32_b64 s61, s[22:23]
	s_add_u32 s89, s89, s61
	s_bcnt1_i32_b64 s61, s[24:25]
	s_add_u32 s89, s89, s61
	s_bcnt1_i32_b64 s61, s[58:59]
	s_add_u32 s89, s89, s61
	s_cmp_ge_u32 s89, s91
	s_cselect_b32 s33, s57, s33
	s_cmp_eq_u32 s89, s91
	s_cbranch_scc1 .Lref_e8
	v_cmp_gt_u32_e64 s[8:9], v216, s33
	v_cmp_gt_u32_e64 s[12:13], v217, s33
	v_cmp_gt_u32_e64 s[14:15], v218, s33
	v_cmp_gt_u32_e64 s[16:17], v219, s33
	v_cmp_gt_u32_e64 s[18:19], v220, s33
	v_cmp_gt_u32_e64 s[22:23], v221, s33
	v_cmp_gt_u32_e64 s[24:25], v222, s33
	v_cmp_gt_u32_e64 s[58:59], v223, s33
	s_bcnt1_i32_b64 s89, s[8:9]
	s_bcnt1_i32_b64 s61, s[12:13]
	s_add_u32 s89, s89, s61
	s_bcnt1_i32_b64 s61, s[14:15]
	s_add_u32 s89, s89, s61
	s_bcnt1_i32_b64 s61, s[16:17]
	s_add_u32 s89, s89, s61
	s_bcnt1_i32_b64 s61, s[18:19]
	s_add_u32 s89, s89, s61
	s_bcnt1_i32_b64 s61, s[22:23]
	s_add_u32 s89, s89, s61
	s_bcnt1_i32_b64 s61, s[24:25]
	s_add_u32 s89, s89, s61
	s_bcnt1_i32_b64 s61, s[58:59]
	s_add_u32 s89, s89, s61
	s_sub_u32 s91, s91, s89
	v_cmp_eq_u32_e64 s[8:9], v216, s33
	v_cmp_eq_u32_e64 s[12:13], v217, s33
	v_cmp_eq_u32_e64 s[14:15], v218, s33
	v_cmp_eq_u32_e64 s[16:17], v219, s33
	v_cmp_eq_u32_e64 s[18:19], v220, s33
	v_cmp_eq_u32_e64 s[22:23], v221, s33
	v_cmp_eq_u32_e64 s[24:25], v222, s33
	v_cmp_eq_u32_e64 s[58:59], v223, s33
	s_bcnt1_i32_b64 s89, s[8:9]
	s_bcnt1_i32_b64 s61, s[12:13]
	s_add_u32 s89, s89, s61
	s_bcnt1_i32_b64 s61, s[14:15]
	s_add_u32 s89, s89, s61
	s_bcnt1_i32_b64 s61, s[16:17]
	s_add_u32 s89, s89, s61
	s_bcnt1_i32_b64 s61, s[18:19]
	s_add_u32 s89, s89, s61
	s_bcnt1_i32_b64 s61, s[22:23]
	s_add_u32 s89, s89, s61
	s_bcnt1_i32_b64 s61, s[24:25]
	s_add_u32 s89, s89, s61
	s_bcnt1_i32_b64 s61, s[58:59]
	s_add_u32 s89, s89, s61
	s_add_u32 s57, s33, 1
	s_cmp_eq_u32 s91, s89
	s_cselect_b32 s57, s33, s57
	s_cselect_b32 s60, 1, 0
	s_branch .Lref_emit8

.Lref_v7:
	ds_read_u16 v224, v245
	ds_read_u16 v225, v245 offset:128
	ds_read_u16 v226, v245 offset:256
	ds_read_u16 v227, v245 offset:384
	ds_read_u16 v228, v245 offset:512
	ds_read_u16 v229, v245 offset:640
	ds_read_u16 v230, v245 offset:768
	v_cmp_gt_u32_e64 s[8:9], s93, v145
	v_add_u32_e32 v241, 64, v145
	v_cmp_gt_u32_e64 s[12:13], s93, v241
	v_add_u32_e32 v241, 128, v145
	v_cmp_gt_u32_e64 s[14:15], s93, v241
	v_add_u32_e32 v241, 192, v145
	v_cmp_gt_u32_e64 s[16:17], s93, v241
	v_add_u32_e32 v241, 256, v145
	v_cmp_gt_u32_e64 s[18:19], s93, v241
	v_add_u32_e32 v241, 320, v145
	v_cmp_gt_u32_e64 s[22:23], s93, v241
	v_add_u32_e32 v241, 384, v145
	v_cmp_gt_u32_e64 s[24:25], s93, v241
	s_waitcnt lgkmcnt(0)
	v_cndmask_b32_e64 v248, 0, v224, s[8:9]
	v_cndmask_b32_e64 v249, 0, v225, s[12:13]
	v_cndmask_b32_e64 v250, 0, v226, s[14:15]
	v_cndmask_b32_e64 v251, 0, v227, s[16:17]
	v_cndmask_b32_e64 v252, 0, v228, s[18:19]
	v_cndmask_b32_e64 v253, 0, v229, s[22:23]
	v_cndmask_b32_e64 v254, 0, v230, s[24:25]
	v_lshl_add_u32 v248, v248, 2, s89
	v_lshl_add_u32 v249, v249, 2, s89
	v_lshl_add_u32 v250, v250, 2, s89
	v_lshl_add_u32 v251, v251, 2, s89
	v_lshl_add_u32 v252, v252, 2, s89
	v_lshl_add_u32 v253, v253, 2, s89
	v_lshl_add_u32 v254, v254, 2, s89
	ds_read_b32 v216, v248
	ds_read_b32 v217, v249
	ds_read_b32 v218, v250
	ds_read_b32 v219, v251
	ds_read_b32 v220, v252
	ds_read_b32 v221, v253
	ds_read_b32 v222, v254
	s_waitcnt lgkmcnt(0)
	v_cndmask_b32_e64 v216, 0, v216, s[8:9]
	v_cndmask_b32_e64 v217, 0, v217, s[12:13]
	v_cndmask_b32_e64 v218, 0, v218, s[14:15]
	v_cndmask_b32_e64 v219, 0, v219, s[16:17]
	v_cndmask_b32_e64 v220, 0, v220, s[18:19]
	v_cndmask_b32_e64 v221, 0, v221, s[22:23]
	v_cndmask_b32_e64 v222, 0, v222, s[24:25]
	s_or_b32 s57, s33, 0x100000
	v_cmp_ge_u32_e64 s[8:9], v216, s57
	v_cmp_ge_u32_e64 s[12:13], v217, s57
	v_cmp_ge_u32_e64 s[14:15], v218, s57
	v_cmp_ge_u32_e64 s[16:17], v219, s57
	v_cmp_ge_u32_e64 s[18:19], v220, s57
	v_cmp_ge_u32_e64 s[22:23], v221, s57
	v_cmp_ge_u32_e64 s[24:25], v222, s57
	s_bcnt1_i32_b64 s89, s[8:9]
	s_bcnt1_i32_b64 s61, s[12:13]
	s_add_u32 s89, s89, s61
	s_bcnt1_i32_b64 s61, s[14:15]
	s_add_u32 s89, s89, s61
	s_bcnt1_i32_b64 s61, s[16:17]
	s_add_u32 s89, s89, s61
	s_bcnt1_i32_b64 s61, s[18:19]
	s_add_u32 s89, s89, s61
	s_bcnt1_i32_b64 s61, s[22:23]
	s_add_u32 s89, s89, s61
	s_bcnt1_i32_b64 s61, s[24:25]
	s_add_u32 s89, s89, s61
	s_cmp_ge_u32 s89, s91
	s_cselect_b32 s33, s57, s33
	s_cmp_eq_u32 s89, s91
	s_cbranch_scc1 .Lref_e7
	s_or_b32 s57, s33, 0x80000
	v_cmp_ge_u32_e64 s[8:9], v216, s57
	v_cmp_ge_u32_e64 s[12:13], v217, s57
	v_cmp_ge_u32_e64 s[14:15], v218, s57
	v_cmp_ge_u32_e64 s[16:17], v219, s57
	v_cmp_ge_u32_e64 s[18:19], v220, s57
	v_cmp_ge_u32_e64 s[22:23], v221, s57
	v_cmp_ge_u32_e64 s[24:25], v222, s57
	s_bcnt1_i32_b64 s89, s[8:9]
	s_bcnt1_i32_b64 s61, s[12:13]
	s_add_u32 s89, s89, s61
	s_bcnt1_i32_b64 s61, s[14:15]
	s_add_u32 s89, s89, s61
	s_bcnt1_i32_b64 s61, s[16:17]
	s_add_u32 s89, s89, s61
	s_bcnt1_i32_b64 s61, s[18:19]
	s_add_u32 s89, s89, s61
	s_bcnt1_i32_b64 s61, s[22:23]
	s_add_u32 s89, s89, s61
	s_bcnt1_i32_b64 s61, s[24:25]
	s_add_u32 s89, s89, s61
	s_cmp_ge_u32 s89, s91
	s_cselect_b32 s33, s57, s33
	s_cmp_eq_u32 s89, s91
	s_cbranch_scc1 .Lref_e7
	s_or_b32 s57, s33, 0x40000
	v_cmp_ge_u32_e64 s[8:9], v216, s57
	v_cmp_ge_u32_e64 s[12:13], v217, s57
	v_cmp_ge_u32_e64 s[14:15], v218, s57
	v_cmp_ge_u32_e64 s[16:17], v219, s57
	v_cmp_ge_u32_e64 s[18:19], v220, s57
	v_cmp_ge_u32_e64 s[22:23], v221, s57
	v_cmp_ge_u32_e64 s[24:25], v222, s57
	s_bcnt1_i32_b64 s89, s[8:9]
	s_bcnt1_i32_b64 s61, s[12:13]
	s_add_u32 s89, s89, s61
	s_bcnt1_i32_b64 s61, s[14:15]
	s_add_u32 s89, s89, s61
	s_bcnt1_i32_b64 s61, s[16:17]
	s_add_u32 s89, s89, s61
	s_bcnt1_i32_b64 s61, s[18:19]
	s_add_u32 s89, s89, s61
	s_bcnt1_i32_b64 s61, s[22:23]
	s_add_u32 s89, s89, s61
	s_bcnt1_i32_b64 s61, s[24:25]
	s_add_u32 s89, s89, s61
	s_cmp_ge_u32 s89, s91
	s_cselect_b32 s33, s57, s33
	s_cmp_eq_u32 s89, s91
	s_cbranch_scc1 .Lref_e7
	s_or_b32 s57, s33, 0x20000
	v_cmp_ge_u32_e64 s[8:9], v216, s57
	v_cmp_ge_u32_e64 s[12:13], v217, s57
	v_cmp_ge_u32_e64 s[14:15], v218, s57
	v_cmp_ge_u32_e64 s[16:17], v219, s57
	v_cmp_ge_u32_e64 s[18:19], v220, s57
	v_cmp_ge_u32_e64 s[22:23], v221, s57
	v_cmp_ge_u32_e64 s[24:25], v222, s57
	s_bcnt1_i32_b64 s89, s[8:9]
	s_bcnt1_i32_b64 s61, s[12:13]
	s_add_u32 s89, s89, s61
	s_bcnt1_i32_b64 s61, s[14:15]
	s_add_u32 s89, s89, s61
	s_bcnt1_i32_b64 s61, s[16:17]
	s_add_u32 s89, s89, s61
	s_bcnt1_i32_b64 s61, s[18:19]
	s_add_u32 s89, s89, s61
	s_bcnt1_i32_b64 s61, s[22:23]
	s_add_u32 s89, s89, s61
	s_bcnt1_i32_b64 s61, s[24:25]
	s_add_u32 s89, s89, s61
	s_cmp_ge_u32 s89, s91
	s_cselect_b32 s33, s57, s33
	s_cmp_eq_u32 s89, s91
	s_cbranch_scc1 .Lref_e7
	s_or_b32 s57, s33, 0x10000
	v_cmp_ge_u32_e64 s[8:9], v216, s57
	v_cmp_ge_u32_e64 s[12:13], v217, s57
	v_cmp_ge_u32_e64 s[14:15], v218, s57
	v_cmp_ge_u32_e64 s[16:17], v219, s57
	v_cmp_ge_u32_e64 s[18:19], v220, s57
	v_cmp_ge_u32_e64 s[22:23], v221, s57
	v_cmp_ge_u32_e64 s[24:25], v222, s57
	s_bcnt1_i32_b64 s89, s[8:9]
	s_bcnt1_i32_b64 s61, s[12:13]
	s_add_u32 s89, s89, s61
	s_bcnt1_i32_b64 s61, s[14:15]
	s_add_u32 s89, s89, s61
	s_bcnt1_i32_b64 s61, s[16:17]
	s_add_u32 s89, s89, s61
	s_bcnt1_i32_b64 s61, s[18:19]
	s_add_u32 s89, s89, s61
	s_bcnt1_i32_b64 s61, s[22:23]
	s_add_u32 s89, s89, s61
	s_bcnt1_i32_b64 s61, s[24:25]
	s_add_u32 s89, s89, s61
	s_cmp_ge_u32 s89, s91
	s_cselect_b32 s33, s57, s33
	s_cmp_eq_u32 s89, s91
	s_cbranch_scc1 .Lref_e7
	s_or_b32 s57, s33, 0x8000
	v_cmp_ge_u32_e64 s[8:9], v216, s57
	v_cmp_ge_u32_e64 s[12:13], v217, s57
	v_cmp_ge_u32_e64 s[14:15], v218, s57
	v_cmp_ge_u32_e64 s[16:17], v219, s57
	v_cmp_ge_u32_e64 s[18:19], v220, s57
	v_cmp_ge_u32_e64 s[22:23], v221, s57
	v_cmp_ge_u32_e64 s[24:25], v222, s57
	s_bcnt1_i32_b64 s89, s[8:9]
	s_bcnt1_i32_b64 s61, s[12:13]
	s_add_u32 s89, s89, s61
	s_bcnt1_i32_b64 s61, s[14:15]
	s_add_u32 s89, s89, s61
	s_bcnt1_i32_b64 s61, s[16:17]
	s_add_u32 s89, s89, s61
	s_bcnt1_i32_b64 s61, s[18:19]
	s_add_u32 s89, s89, s61
	s_bcnt1_i32_b64 s61, s[22:23]
	s_add_u32 s89, s89, s61
	s_bcnt1_i32_b64 s61, s[24:25]
	s_add_u32 s89, s89, s61
	s_cmp_ge_u32 s89, s91
	s_cselect_b32 s33, s57, s33
	s_cmp_eq_u32 s89, s91
	s_cbranch_scc1 .Lref_e7
	s_or_b32 s57, s33, 0x4000
	v_cmp_ge_u32_e64 s[8:9], v216, s57
	v_cmp_ge_u32_e64 s[12:13], v217, s57
	v_cmp_ge_u32_e64 s[14:15], v218, s57
	v_cmp_ge_u32_e64 s[16:17], v219, s57
	v_cmp_ge_u32_e64 s[18:19], v220, s57
	v_cmp_ge_u32_e64 s[22:23], v221, s57
	v_cmp_ge_u32_e64 s[24:25], v222, s57
	s_bcnt1_i32_b64 s89, s[8:9]
	s_bcnt1_i32_b64 s61, s[12:13]
	s_add_u32 s89, s89, s61
	s_bcnt1_i32_b64 s61, s[14:15]
	s_add_u32 s89, s89, s61
	s_bcnt1_i32_b64 s61, s[16:17]
	s_add_u32 s89, s89, s61
	s_bcnt1_i32_b64 s61, s[18:19]
	s_add_u32 s89, s89, s61
	s_bcnt1_i32_b64 s61, s[22:23]
	s_add_u32 s89, s89, s61
	s_bcnt1_i32_b64 s61, s[24:25]
	s_add_u32 s89, s89, s61
	s_cmp_ge_u32 s89, s91
	s_cselect_b32 s33, s57, s33
	s_cmp_eq_u32 s89, s91
	s_cbranch_scc1 .Lref_e7
	s_or_b32 s57, s33, 0x2000
	v_cmp_ge_u32_e64 s[8:9], v216, s57
	v_cmp_ge_u32_e64 s[12:13], v217, s57
	v_cmp_ge_u32_e64 s[14:15], v218, s57
	v_cmp_ge_u32_e64 s[16:17], v219, s57
	v_cmp_ge_u32_e64 s[18:19], v220, s57
	v_cmp_ge_u32_e64 s[22:23], v221, s57
	v_cmp_ge_u32_e64 s[24:25], v222, s57
	s_bcnt1_i32_b64 s89, s[8:9]
	s_bcnt1_i32_b64 s61, s[12:13]
	s_add_u32 s89, s89, s61
	s_bcnt1_i32_b64 s61, s[14:15]
	s_add_u32 s89, s89, s61
	s_bcnt1_i32_b64 s61, s[16:17]
	s_add_u32 s89, s89, s61
	s_bcnt1_i32_b64 s61, s[18:19]
	s_add_u32 s89, s89, s61
	s_bcnt1_i32_b64 s61, s[22:23]
	s_add_u32 s89, s89, s61
	s_bcnt1_i32_b64 s61, s[24:25]
	s_add_u32 s89, s89, s61
	s_cmp_ge_u32 s89, s91
	s_cselect_b32 s33, s57, s33
	s_cmp_eq_u32 s89, s91
	s_cbranch_scc1 .Lref_e7
	s_or_b32 s57, s33, 0x1000
	v_cmp_ge_u32_e64 s[8:9], v216, s57
	v_cmp_ge_u32_e64 s[12:13], v217, s57
	v_cmp_ge_u32_e64 s[14:15], v218, s57
	v_cmp_ge_u32_e64 s[16:17], v219, s57
	v_cmp_ge_u32_e64 s[18:19], v220, s57
	v_cmp_ge_u32_e64 s[22:23], v221, s57
	v_cmp_ge_u32_e64 s[24:25], v222, s57
	s_bcnt1_i32_b64 s89, s[8:9]
	s_bcnt1_i32_b64 s61, s[12:13]
	s_add_u32 s89, s89, s61
	s_bcnt1_i32_b64 s61, s[14:15]
	s_add_u32 s89, s89, s61
	s_bcnt1_i32_b64 s61, s[16:17]
	s_add_u32 s89, s89, s61
	s_bcnt1_i32_b64 s61, s[18:19]
	s_add_u32 s89, s89, s61
	s_bcnt1_i32_b64 s61, s[22:23]
	s_add_u32 s89, s89, s61
	s_bcnt1_i32_b64 s61, s[24:25]
	s_add_u32 s89, s89, s61
	s_cmp_ge_u32 s89, s91
	s_cselect_b32 s33, s57, s33
	s_cmp_eq_u32 s89, s91
	s_cbranch_scc1 .Lref_e7
	s_or_b32 s57, s33, 0x800
	v_cmp_ge_u32_e64 s[8:9], v216, s57
	v_cmp_ge_u32_e64 s[12:13], v217, s57
	v_cmp_ge_u32_e64 s[14:15], v218, s57
	v_cmp_ge_u32_e64 s[16:17], v219, s57
	v_cmp_ge_u32_e64 s[18:19], v220, s57
	v_cmp_ge_u32_e64 s[22:23], v221, s57
	v_cmp_ge_u32_e64 s[24:25], v222, s57
	s_bcnt1_i32_b64 s89, s[8:9]
	s_bcnt1_i32_b64 s61, s[12:13]
	s_add_u32 s89, s89, s61
	s_bcnt1_i32_b64 s61, s[14:15]
	s_add_u32 s89, s89, s61
	s_bcnt1_i32_b64 s61, s[16:17]
	s_add_u32 s89, s89, s61
	s_bcnt1_i32_b64 s61, s[18:19]
	s_add_u32 s89, s89, s61
	s_bcnt1_i32_b64 s61, s[22:23]
	s_add_u32 s89, s89, s61
	s_bcnt1_i32_b64 s61, s[24:25]
	s_add_u32 s89, s89, s61
	s_cmp_ge_u32 s89, s91
	s_cselect_b32 s33, s57, s33
	s_cmp_eq_u32 s89, s91
	s_cbranch_scc1 .Lref_e7
	s_or_b32 s57, s33, 0x400
	v_cmp_ge_u32_e64 s[8:9], v216, s57
	v_cmp_ge_u32_e64 s[12:13], v217, s57
	v_cmp_ge_u32_e64 s[14:15], v218, s57
	v_cmp_ge_u32_e64 s[16:17], v219, s57
	v_cmp_ge_u32_e64 s[18:19], v220, s57
	v_cmp_ge_u32_e64 s[22:23], v221, s57
	v_cmp_ge_u32_e64 s[24:25], v222, s57
	s_bcnt1_i32_b64 s89, s[8:9]
	s_bcnt1_i32_b64 s61, s[12:13]
	s_add_u32 s89, s89, s61
	s_bcnt1_i32_b64 s61, s[14:15]
	s_add_u32 s89, s89, s61
	s_bcnt1_i32_b64 s61, s[16:17]
	s_add_u32 s89, s89, s61
	s_bcnt1_i32_b64 s61, s[18:19]
	s_add_u32 s89, s89, s61
	s_bcnt1_i32_b64 s61, s[22:23]
	s_add_u32 s89, s89, s61
	s_bcnt1_i32_b64 s61, s[24:25]
	s_add_u32 s89, s89, s61
	s_cmp_ge_u32 s89, s91
	s_cselect_b32 s33, s57, s33
	s_cmp_eq_u32 s89, s91
	s_cbranch_scc1 .Lref_e7
	s_or_b32 s57, s33, 0x200
	v_cmp_ge_u32_e64 s[8:9], v216, s57
	v_cmp_ge_u32_e64 s[12:13], v217, s57
	v_cmp_ge_u32_e64 s[14:15], v218, s57
	v_cmp_ge_u32_e64 s[16:17], v219, s57
	v_cmp_ge_u32_e64 s[18:19], v220, s57
	v_cmp_ge_u32_e64 s[22:23], v221, s57
	v_cmp_ge_u32_e64 s[24:25], v222, s57
	s_bcnt1_i32_b64 s89, s[8:9]
	s_bcnt1_i32_b64 s61, s[12:13]
	s_add_u32 s89, s89, s61
	s_bcnt1_i32_b64 s61, s[14:15]
	s_add_u32 s89, s89, s61
	s_bcnt1_i32_b64 s61, s[16:17]
	s_add_u32 s89, s89, s61
	s_bcnt1_i32_b64 s61, s[18:19]
	s_add_u32 s89, s89, s61
	s_bcnt1_i32_b64 s61, s[22:23]
	s_add_u32 s89, s89, s61
	s_bcnt1_i32_b64 s61, s[24:25]
	s_add_u32 s89, s89, s61
	s_cmp_ge_u32 s89, s91
	s_cselect_b32 s33, s57, s33
	s_cmp_eq_u32 s89, s91
	s_cbranch_scc1 .Lref_e7
	s_or_b32 s57, s33, 0x100
	v_cmp_ge_u32_e64 s[8:9], v216, s57
	v_cmp_ge_u32_e64 s[12:13], v217, s57
	v_cmp_ge_u32_e64 s[14:15], v218, s57
	v_cmp_ge_u32_e64 s[16:17], v219, s57
	v_cmp_ge_u32_e64 s[18:19], v220, s57
	v_cmp_ge_u32_e64 s[22:23], v221, s57
	v_cmp_ge_u32_e64 s[24:25], v222, s57
	s_bcnt1_i32_b64 s89, s[8:9]
	s_bcnt1_i32_b64 s61, s[12:13]
	s_add_u32 s89, s89, s61
	s_bcnt1_i32_b64 s61, s[14:15]
	s_add_u32 s89, s89, s61
	s_bcnt1_i32_b64 s61, s[16:17]
	s_add_u32 s89, s89, s61
	s_bcnt1_i32_b64 s61, s[18:19]
	s_add_u32 s89, s89, s61
	s_bcnt1_i32_b64 s61, s[22:23]
	s_add_u32 s89, s89, s61
	s_bcnt1_i32_b64 s61, s[24:25]
	s_add_u32 s89, s89, s61
	s_cmp_ge_u32 s89, s91
	s_cselect_b32 s33, s57, s33
	s_cmp_eq_u32 s89, s91
	s_cbranch_scc1 .Lref_e7
	s_or_b32 s57, s33, 0x80
	v_cmp_ge_u32_e64 s[8:9], v216, s57
	v_cmp_ge_u32_e64 s[12:13], v217, s57
	v_cmp_ge_u32_e64 s[14:15], v218, s57
	v_cmp_ge_u32_e64 s[16:17], v219, s57
	v_cmp_ge_u32_e64 s[18:19], v220, s57
	v_cmp_ge_u32_e64 s[22:23], v221, s57
	v_cmp_ge_u32_e64 s[24:25], v222, s57
	s_bcnt1_i32_b64 s89, s[8:9]
	s_bcnt1_i32_b64 s61, s[12:13]
	s_add_u32 s89, s89, s61
	s_bcnt1_i32_b64 s61, s[14:15]
	s_add_u32 s89, s89, s61
	s_bcnt1_i32_b64 s61, s[16:17]
	s_add_u32 s89, s89, s61
	s_bcnt1_i32_b64 s61, s[18:19]
	s_add_u32 s89, s89, s61
	s_bcnt1_i32_b64 s61, s[22:23]
	s_add_u32 s89, s89, s61
	s_bcnt1_i32_b64 s61, s[24:25]
	s_add_u32 s89, s89, s61
	s_cmp_ge_u32 s89, s91
	s_cselect_b32 s33, s57, s33
	s_cmp_eq_u32 s89, s91
	s_cbranch_scc1 .Lref_e7
	s_or_b32 s57, s33, 0x40
	v_cmp_ge_u32_e64 s[8:9], v216, s57
	v_cmp_ge_u32_e64 s[12:13], v217, s57
	v_cmp_ge_u32_e64 s[14:15], v218, s57
	v_cmp_ge_u32_e64 s[16:17], v219, s57
	v_cmp_ge_u32_e64 s[18:19], v220, s57
	v_cmp_ge_u32_e64 s[22:23], v221, s57
	v_cmp_ge_u32_e64 s[24:25], v222, s57
	s_bcnt1_i32_b64 s89, s[8:9]
	s_bcnt1_i32_b64 s61, s[12:13]
	s_add_u32 s89, s89, s61
	s_bcnt1_i32_b64 s61, s[14:15]
	s_add_u32 s89, s89, s61
	s_bcnt1_i32_b64 s61, s[16:17]
	s_add_u32 s89, s89, s61
	s_bcnt1_i32_b64 s61, s[18:19]
	s_add_u32 s89, s89, s61
	s_bcnt1_i32_b64 s61, s[22:23]
	s_add_u32 s89, s89, s61
	s_bcnt1_i32_b64 s61, s[24:25]
	s_add_u32 s89, s89, s61
	s_cmp_ge_u32 s89, s91
	s_cselect_b32 s33, s57, s33
	s_cmp_eq_u32 s89, s91
	s_cbranch_scc1 .Lref_e7
	s_or_b32 s57, s33, 0x20
	v_cmp_ge_u32_e64 s[8:9], v216, s57
	v_cmp_ge_u32_e64 s[12:13], v217, s57
	v_cmp_ge_u32_e64 s[14:15], v218, s57
	v_cmp_ge_u32_e64 s[16:17], v219, s57
	v_cmp_ge_u32_e64 s[18:19], v220, s57
	v_cmp_ge_u32_e64 s[22:23], v221, s57
	v_cmp_ge_u32_e64 s[24:25], v222, s57
	s_bcnt1_i32_b64 s89, s[8:9]
	s_bcnt1_i32_b64 s61, s[12:13]
	s_add_u32 s89, s89, s61
	s_bcnt1_i32_b64 s61, s[14:15]
	s_add_u32 s89, s89, s61
	s_bcnt1_i32_b64 s61, s[16:17]
	s_add_u32 s89, s89, s61
	s_bcnt1_i32_b64 s61, s[18:19]
	s_add_u32 s89, s89, s61
	s_bcnt1_i32_b64 s61, s[22:23]
	s_add_u32 s89, s89, s61
	s_bcnt1_i32_b64 s61, s[24:25]
	s_add_u32 s89, s89, s61
	s_cmp_ge_u32 s89, s91
	s_cselect_b32 s33, s57, s33
	s_cmp_eq_u32 s89, s91
	s_cbranch_scc1 .Lref_e7
	s_or_b32 s57, s33, 0x10
	v_cmp_ge_u32_e64 s[8:9], v216, s57
	v_cmp_ge_u32_e64 s[12:13], v217, s57
	v_cmp_ge_u32_e64 s[14:15], v218, s57
	v_cmp_ge_u32_e64 s[16:17], v219, s57
	v_cmp_ge_u32_e64 s[18:19], v220, s57
	v_cmp_ge_u32_e64 s[22:23], v221, s57
	v_cmp_ge_u32_e64 s[24:25], v222, s57
	s_bcnt1_i32_b64 s89, s[8:9]
	s_bcnt1_i32_b64 s61, s[12:13]
	s_add_u32 s89, s89, s61
	s_bcnt1_i32_b64 s61, s[14:15]
	s_add_u32 s89, s89, s61
	s_bcnt1_i32_b64 s61, s[16:17]
	s_add_u32 s89, s89, s61
	s_bcnt1_i32_b64 s61, s[18:19]
	s_add_u32 s89, s89, s61
	s_bcnt1_i32_b64 s61, s[22:23]
	s_add_u32 s89, s89, s61
	s_bcnt1_i32_b64 s61, s[24:25]
	s_add_u32 s89, s89, s61
	s_cmp_ge_u32 s89, s91
	s_cselect_b32 s33, s57, s33
	s_cmp_eq_u32 s89, s91
	s_cbranch_scc1 .Lref_e7
	s_or_b32 s57, s33, 0x8
	v_cmp_ge_u32_e64 s[8:9], v216, s57
	v_cmp_ge_u32_e64 s[12:13], v217, s57
	v_cmp_ge_u32_e64 s[14:15], v218, s57
	v_cmp_ge_u32_e64 s[16:17], v219, s57
	v_cmp_ge_u32_e64 s[18:19], v220, s57
	v_cmp_ge_u32_e64 s[22:23], v221, s57
	v_cmp_ge_u32_e64 s[24:25], v222, s57
	s_bcnt1_i32_b64 s89, s[8:9]
	s_bcnt1_i32_b64 s61, s[12:13]
	s_add_u32 s89, s89, s61
	s_bcnt1_i32_b64 s61, s[14:15]
	s_add_u32 s89, s89, s61
	s_bcnt1_i32_b64 s61, s[16:17]
	s_add_u32 s89, s89, s61
	s_bcnt1_i32_b64 s61, s[18:19]
	s_add_u32 s89, s89, s61
	s_bcnt1_i32_b64 s61, s[22:23]
	s_add_u32 s89, s89, s61
	s_bcnt1_i32_b64 s61, s[24:25]
	s_add_u32 s89, s89, s61
	s_cmp_ge_u32 s89, s91
	s_cselect_b32 s33, s57, s33
	s_cmp_eq_u32 s89, s91
	s_cbranch_scc1 .Lref_e7
	s_or_b32 s57, s33, 0x4
	v_cmp_ge_u32_e64 s[8:9], v216, s57
	v_cmp_ge_u32_e64 s[12:13], v217, s57
	v_cmp_ge_u32_e64 s[14:15], v218, s57
	v_cmp_ge_u32_e64 s[16:17], v219, s57
	v_cmp_ge_u32_e64 s[18:19], v220, s57
	v_cmp_ge_u32_e64 s[22:23], v221, s57
	v_cmp_ge_u32_e64 s[24:25], v222, s57
	s_bcnt1_i32_b64 s89, s[8:9]
	s_bcnt1_i32_b64 s61, s[12:13]
	s_add_u32 s89, s89, s61
	s_bcnt1_i32_b64 s61, s[14:15]
	s_add_u32 s89, s89, s61
	s_bcnt1_i32_b64 s61, s[16:17]
	s_add_u32 s89, s89, s61
	s_bcnt1_i32_b64 s61, s[18:19]
	s_add_u32 s89, s89, s61
	s_bcnt1_i32_b64 s61, s[22:23]
	s_add_u32 s89, s89, s61
	s_bcnt1_i32_b64 s61, s[24:25]
	s_add_u32 s89, s89, s61
	s_cmp_ge_u32 s89, s91
	s_cselect_b32 s33, s57, s33
	s_cmp_eq_u32 s89, s91
	s_cbranch_scc1 .Lref_e7
	s_or_b32 s57, s33, 0x2
	v_cmp_ge_u32_e64 s[8:9], v216, s57
	v_cmp_ge_u32_e64 s[12:13], v217, s57
	v_cmp_ge_u32_e64 s[14:15], v218, s57
	v_cmp_ge_u32_e64 s[16:17], v219, s57
	v_cmp_ge_u32_e64 s[18:19], v220, s57
	v_cmp_ge_u32_e64 s[22:23], v221, s57
	v_cmp_ge_u32_e64 s[24:25], v222, s57
	s_bcnt1_i32_b64 s89, s[8:9]
	s_bcnt1_i32_b64 s61, s[12:13]
	s_add_u32 s89, s89, s61
	s_bcnt1_i32_b64 s61, s[14:15]
	s_add_u32 s89, s89, s61
	s_bcnt1_i32_b64 s61, s[16:17]
	s_add_u32 s89, s89, s61
	s_bcnt1_i32_b64 s61, s[18:19]
	s_add_u32 s89, s89, s61
	s_bcnt1_i32_b64 s61, s[22:23]
	s_add_u32 s89, s89, s61
	s_bcnt1_i32_b64 s61, s[24:25]
	s_add_u32 s89, s89, s61
	s_cmp_ge_u32 s89, s91
	s_cselect_b32 s33, s57, s33
	s_cmp_eq_u32 s89, s91
	s_cbranch_scc1 .Lref_e7
	s_or_b32 s57, s33, 0x1
	v_cmp_ge_u32_e64 s[8:9], v216, s57
	v_cmp_ge_u32_e64 s[12:13], v217, s57
	v_cmp_ge_u32_e64 s[14:15], v218, s57
	v_cmp_ge_u32_e64 s[16:17], v219, s57
	v_cmp_ge_u32_e64 s[18:19], v220, s57
	v_cmp_ge_u32_e64 s[22:23], v221, s57
	v_cmp_ge_u32_e64 s[24:25], v222, s57
	s_bcnt1_i32_b64 s89, s[8:9]
	s_bcnt1_i32_b64 s61, s[12:13]
	s_add_u32 s89, s89, s61
	s_bcnt1_i32_b64 s61, s[14:15]
	s_add_u32 s89, s89, s61
	s_bcnt1_i32_b64 s61, s[16:17]
	s_add_u32 s89, s89, s61
	s_bcnt1_i32_b64 s61, s[18:19]
	s_add_u32 s89, s89, s61
	s_bcnt1_i32_b64 s61, s[22:23]
	s_add_u32 s89, s89, s61
	s_bcnt1_i32_b64 s61, s[24:25]
	s_add_u32 s89, s89, s61
	s_cmp_ge_u32 s89, s91
	s_cselect_b32 s33, s57, s33
	s_cmp_eq_u32 s89, s91
	s_cbranch_scc1 .Lref_e7
	v_cmp_gt_u32_e64 s[8:9], v216, s33
	v_cmp_gt_u32_e64 s[12:13], v217, s33
	v_cmp_gt_u32_e64 s[14:15], v218, s33
	v_cmp_gt_u32_e64 s[16:17], v219, s33
	v_cmp_gt_u32_e64 s[18:19], v220, s33
	v_cmp_gt_u32_e64 s[22:23], v221, s33
	v_cmp_gt_u32_e64 s[24:25], v222, s33
	s_bcnt1_i32_b64 s89, s[8:9]
	s_bcnt1_i32_b64 s61, s[12:13]
	s_add_u32 s89, s89, s61
	s_bcnt1_i32_b64 s61, s[14:15]
	s_add_u32 s89, s89, s61
	s_bcnt1_i32_b64 s61, s[16:17]
	s_add_u32 s89, s89, s61
	s_bcnt1_i32_b64 s61, s[18:19]
	s_add_u32 s89, s89, s61
	s_bcnt1_i32_b64 s61, s[22:23]
	s_add_u32 s89, s89, s61
	s_bcnt1_i32_b64 s61, s[24:25]
	s_add_u32 s89, s89, s61
	s_sub_u32 s91, s91, s89
	v_cmp_eq_u32_e64 s[8:9], v216, s33
	v_cmp_eq_u32_e64 s[12:13], v217, s33
	v_cmp_eq_u32_e64 s[14:15], v218, s33
	v_cmp_eq_u32_e64 s[16:17], v219, s33
	v_cmp_eq_u32_e64 s[18:19], v220, s33
	v_cmp_eq_u32_e64 s[22:23], v221, s33
	v_cmp_eq_u32_e64 s[24:25], v222, s33
	s_bcnt1_i32_b64 s89, s[8:9]
	s_bcnt1_i32_b64 s61, s[12:13]
	s_add_u32 s89, s89, s61
	s_bcnt1_i32_b64 s61, s[14:15]
	s_add_u32 s89, s89, s61
	s_bcnt1_i32_b64 s61, s[16:17]
	s_add_u32 s89, s89, s61
	s_bcnt1_i32_b64 s61, s[18:19]
	s_add_u32 s89, s89, s61
	s_bcnt1_i32_b64 s61, s[22:23]
	s_add_u32 s89, s89, s61
	s_bcnt1_i32_b64 s61, s[24:25]
	s_add_u32 s89, s89, s61
	s_add_u32 s57, s33, 1
	s_cmp_eq_u32 s91, s89
	s_cselect_b32 s57, s33, s57
	s_cselect_b32 s60, 1, 0
	s_branch .Lref_emit7

.Lref_v6:
	ds_read_u16 v224, v245
	ds_read_u16 v225, v245 offset:128
	ds_read_u16 v226, v245 offset:256
	ds_read_u16 v227, v245 offset:384
	ds_read_u16 v228, v245 offset:512
	ds_read_u16 v229, v245 offset:640
	v_cmp_gt_u32_e64 s[8:9], s93, v145
	v_add_u32_e32 v241, 64, v145
	v_cmp_gt_u32_e64 s[12:13], s93, v241
	v_add_u32_e32 v241, 128, v145
	v_cmp_gt_u32_e64 s[14:15], s93, v241
	v_add_u32_e32 v241, 192, v145
	v_cmp_gt_u32_e64 s[16:17], s93, v241
	v_add_u32_e32 v241, 256, v145
	v_cmp_gt_u32_e64 s[18:19], s93, v241
	v_add_u32_e32 v241, 320, v145
	v_cmp_gt_u32_e64 s[22:23], s93, v241
	s_waitcnt lgkmcnt(0)
	v_cndmask_b32_e64 v248, 0, v224, s[8:9]
	v_cndmask_b32_e64 v249, 0, v225, s[12:13]
	v_cndmask_b32_e64 v250, 0, v226, s[14:15]
	v_cndmask_b32_e64 v251, 0, v227, s[16:17]
	v_cndmask_b32_e64 v252, 0, v228, s[18:19]
	v_cndmask_b32_e64 v253, 0, v229, s[22:23]
	v_lshl_add_u32 v248, v248, 2, s89
	v_lshl_add_u32 v249, v249, 2, s89
	v_lshl_add_u32 v250, v250, 2, s89
	v_lshl_add_u32 v251, v251, 2, s89
	v_lshl_add_u32 v252, v252, 2, s89
	v_lshl_add_u32 v253, v253, 2, s89
	ds_read_b32 v216, v248
	ds_read_b32 v217, v249
	ds_read_b32 v218, v250
	ds_read_b32 v219, v251
	ds_read_b32 v220, v252
	ds_read_b32 v221, v253
	s_waitcnt lgkmcnt(0)
	v_cndmask_b32_e64 v216, 0, v216, s[8:9]
	v_cndmask_b32_e64 v217, 0, v217, s[12:13]
	v_cndmask_b32_e64 v218, 0, v218, s[14:15]
	v_cndmask_b32_e64 v219, 0, v219, s[16:17]
	v_cndmask_b32_e64 v220, 0, v220, s[18:19]
	v_cndmask_b32_e64 v221, 0, v221, s[22:23]
	s_or_b32 s57, s33, 0x100000
	v_cmp_ge_u32_e64 s[8:9], v216, s57
	v_cmp_ge_u32_e64 s[12:13], v217, s57
	v_cmp_ge_u32_e64 s[14:15], v218, s57
	v_cmp_ge_u32_e64 s[16:17], v219, s57
	v_cmp_ge_u32_e64 s[18:19], v220, s57
	v_cmp_ge_u32_e64 s[22:23], v221, s57
	s_bcnt1_i32_b64 s89, s[8:9]
	s_bcnt1_i32_b64 s61, s[12:13]
	s_add_u32 s89, s89, s61
	s_bcnt1_i32_b64 s61, s[14:15]
	s_add_u32 s89, s89, s61
	s_bcnt1_i32_b64 s61, s[16:17]
	s_add_u32 s89, s89, s61
	s_bcnt1_i32_b64 s61, s[18:19]
	s_add_u32 s89, s89, s61
	s_bcnt1_i32_b64 s61, s[22:23]
	s_add_u32 s89, s89, s61
	s_cmp_ge_u32 s89, s91
	s_cselect_b32 s33, s57, s33
	s_cmp_eq_u32 s89, s91
	s_cbranch_scc1 .Lref_e6
	s_or_b32 s57, s33, 0x80000
	v_cmp_ge_u32_e64 s[8:9], v216, s57
	v_cmp_ge_u32_e64 s[12:13], v217, s57
	v_cmp_ge_u32_e64 s[14:15], v218, s57
	v_cmp_ge_u32_e64 s[16:17], v219, s57
	v_cmp_ge_u32_e64 s[18:19], v220, s57
	v_cmp_ge_u32_e64 s[22:23], v221, s57
	s_bcnt1_i32_b64 s89, s[8:9]
	s_bcnt1_i32_b64 s61, s[12:13]
	s_add_u32 s89, s89, s61
	s_bcnt1_i32_b64 s61, s[14:15]
	s_add_u32 s89, s89, s61
	s_bcnt1_i32_b64 s61, s[16:17]
	s_add_u32 s89, s89, s61
	s_bcnt1_i32_b64 s61, s[18:19]
	s_add_u32 s89, s89, s61
	s_bcnt1_i32_b64 s61, s[22:23]
	s_add_u32 s89, s89, s61
	s_cmp_ge_u32 s89, s91
	s_cselect_b32 s33, s57, s33
	s_cmp_eq_u32 s89, s91
	s_cbranch_scc1 .Lref_e6
	s_or_b32 s57, s33, 0x40000
	v_cmp_ge_u32_e64 s[8:9], v216, s57
	v_cmp_ge_u32_e64 s[12:13], v217, s57
	v_cmp_ge_u32_e64 s[14:15], v218, s57
	v_cmp_ge_u32_e64 s[16:17], v219, s57
	v_cmp_ge_u32_e64 s[18:19], v220, s57
	v_cmp_ge_u32_e64 s[22:23], v221, s57
	s_bcnt1_i32_b64 s89, s[8:9]
	s_bcnt1_i32_b64 s61, s[12:13]
	s_add_u32 s89, s89, s61
	s_bcnt1_i32_b64 s61, s[14:15]
	s_add_u32 s89, s89, s61
	s_bcnt1_i32_b64 s61, s[16:17]
	s_add_u32 s89, s89, s61
	s_bcnt1_i32_b64 s61, s[18:19]
	s_add_u32 s89, s89, s61
	s_bcnt1_i32_b64 s61, s[22:23]
	s_add_u32 s89, s89, s61
	s_cmp_ge_u32 s89, s91
	s_cselect_b32 s33, s57, s33
	s_cmp_eq_u32 s89, s91
	s_cbranch_scc1 .Lref_e6
	s_or_b32 s57, s33, 0x20000
	v_cmp_ge_u32_e64 s[8:9], v216, s57
	v_cmp_ge_u32_e64 s[12:13], v217, s57
	v_cmp_ge_u32_e64 s[14:15], v218, s57
	v_cmp_ge_u32_e64 s[16:17], v219, s57
	v_cmp_ge_u32_e64 s[18:19], v220, s57
	v_cmp_ge_u32_e64 s[22:23], v221, s57
	s_bcnt1_i32_b64 s89, s[8:9]
	s_bcnt1_i32_b64 s61, s[12:13]
	s_add_u32 s89, s89, s61
	s_bcnt1_i32_b64 s61, s[14:15]
	s_add_u32 s89, s89, s61
	s_bcnt1_i32_b64 s61, s[16:17]
	s_add_u32 s89, s89, s61
	s_bcnt1_i32_b64 s61, s[18:19]
	s_add_u32 s89, s89, s61
	s_bcnt1_i32_b64 s61, s[22:23]
	s_add_u32 s89, s89, s61
	s_cmp_ge_u32 s89, s91
	s_cselect_b32 s33, s57, s33
	s_cmp_eq_u32 s89, s91
	s_cbranch_scc1 .Lref_e6
	s_or_b32 s57, s33, 0x10000
	v_cmp_ge_u32_e64 s[8:9], v216, s57
	v_cmp_ge_u32_e64 s[12:13], v217, s57
	v_cmp_ge_u32_e64 s[14:15], v218, s57
	v_cmp_ge_u32_e64 s[16:17], v219, s57
	v_cmp_ge_u32_e64 s[18:19], v220, s57
	v_cmp_ge_u32_e64 s[22:23], v221, s57
	s_bcnt1_i32_b64 s89, s[8:9]
	s_bcnt1_i32_b64 s61, s[12:13]
	s_add_u32 s89, s89, s61
	s_bcnt1_i32_b64 s61, s[14:15]
	s_add_u32 s89, s89, s61
	s_bcnt1_i32_b64 s61, s[16:17]
	s_add_u32 s89, s89, s61
	s_bcnt1_i32_b64 s61, s[18:19]
	s_add_u32 s89, s89, s61
	s_bcnt1_i32_b64 s61, s[22:23]
	s_add_u32 s89, s89, s61
	s_cmp_ge_u32 s89, s91
	s_cselect_b32 s33, s57, s33
	s_cmp_eq_u32 s89, s91
	s_cbranch_scc1 .Lref_e6
	s_or_b32 s57, s33, 0x8000
	v_cmp_ge_u32_e64 s[8:9], v216, s57
	v_cmp_ge_u32_e64 s[12:13], v217, s57
	v_cmp_ge_u32_e64 s[14:15], v218, s57
	v_cmp_ge_u32_e64 s[16:17], v219, s57
	v_cmp_ge_u32_e64 s[18:19], v220, s57
	v_cmp_ge_u32_e64 s[22:23], v221, s57
	s_bcnt1_i32_b64 s89, s[8:9]
	s_bcnt1_i32_b64 s61, s[12:13]
	s_add_u32 s89, s89, s61
	s_bcnt1_i32_b64 s61, s[14:15]
	s_add_u32 s89, s89, s61
	s_bcnt1_i32_b64 s61, s[16:17]
	s_add_u32 s89, s89, s61
	s_bcnt1_i32_b64 s61, s[18:19]
	s_add_u32 s89, s89, s61
	s_bcnt1_i32_b64 s61, s[22:23]
	s_add_u32 s89, s89, s61
	s_cmp_ge_u32 s89, s91
	s_cselect_b32 s33, s57, s33
	s_cmp_eq_u32 s89, s91
	s_cbranch_scc1 .Lref_e6
	s_or_b32 s57, s33, 0x4000
	v_cmp_ge_u32_e64 s[8:9], v216, s57
	v_cmp_ge_u32_e64 s[12:13], v217, s57
	v_cmp_ge_u32_e64 s[14:15], v218, s57
	v_cmp_ge_u32_e64 s[16:17], v219, s57
	v_cmp_ge_u32_e64 s[18:19], v220, s57
	v_cmp_ge_u32_e64 s[22:23], v221, s57
	s_bcnt1_i32_b64 s89, s[8:9]
	s_bcnt1_i32_b64 s61, s[12:13]
	s_add_u32 s89, s89, s61
	s_bcnt1_i32_b64 s61, s[14:15]
	s_add_u32 s89, s89, s61
	s_bcnt1_i32_b64 s61, s[16:17]
	s_add_u32 s89, s89, s61
	s_bcnt1_i32_b64 s61, s[18:19]
	s_add_u32 s89, s89, s61
	s_bcnt1_i32_b64 s61, s[22:23]
	s_add_u32 s89, s89, s61
	s_cmp_ge_u32 s89, s91
	s_cselect_b32 s33, s57, s33
	s_cmp_eq_u32 s89, s91
	s_cbranch_scc1 .Lref_e6
	s_or_b32 s57, s33, 0x2000
	v_cmp_ge_u32_e64 s[8:9], v216, s57
	v_cmp_ge_u32_e64 s[12:13], v217, s57
	v_cmp_ge_u32_e64 s[14:15], v218, s57
	v_cmp_ge_u32_e64 s[16:17], v219, s57
	v_cmp_ge_u32_e64 s[18:19], v220, s57
	v_cmp_ge_u32_e64 s[22:23], v221, s57
	s_bcnt1_i32_b64 s89, s[8:9]
	s_bcnt1_i32_b64 s61, s[12:13]
	s_add_u32 s89, s89, s61
	s_bcnt1_i32_b64 s61, s[14:15]
	s_add_u32 s89, s89, s61
	s_bcnt1_i32_b64 s61, s[16:17]
	s_add_u32 s89, s89, s61
	s_bcnt1_i32_b64 s61, s[18:19]
	s_add_u32 s89, s89, s61
	s_bcnt1_i32_b64 s61, s[22:23]
	s_add_u32 s89, s89, s61
	s_cmp_ge_u32 s89, s91
	s_cselect_b32 s33, s57, s33
	s_cmp_eq_u32 s89, s91
	s_cbranch_scc1 .Lref_e6
	s_or_b32 s57, s33, 0x1000
	v_cmp_ge_u32_e64 s[8:9], v216, s57
	v_cmp_ge_u32_e64 s[12:13], v217, s57
	v_cmp_ge_u32_e64 s[14:15], v218, s57
	v_cmp_ge_u32_e64 s[16:17], v219, s57
	v_cmp_ge_u32_e64 s[18:19], v220, s57
	v_cmp_ge_u32_e64 s[22:23], v221, s57
	s_bcnt1_i32_b64 s89, s[8:9]
	s_bcnt1_i32_b64 s61, s[12:13]
	s_add_u32 s89, s89, s61
	s_bcnt1_i32_b64 s61, s[14:15]
	s_add_u32 s89, s89, s61
	s_bcnt1_i32_b64 s61, s[16:17]
	s_add_u32 s89, s89, s61
	s_bcnt1_i32_b64 s61, s[18:19]
	s_add_u32 s89, s89, s61
	s_bcnt1_i32_b64 s61, s[22:23]
	s_add_u32 s89, s89, s61
	s_cmp_ge_u32 s89, s91
	s_cselect_b32 s33, s57, s33
	s_cmp_eq_u32 s89, s91
	s_cbranch_scc1 .Lref_e6
	s_or_b32 s57, s33, 0x800
	v_cmp_ge_u32_e64 s[8:9], v216, s57
	v_cmp_ge_u32_e64 s[12:13], v217, s57
	v_cmp_ge_u32_e64 s[14:15], v218, s57
	v_cmp_ge_u32_e64 s[16:17], v219, s57
	v_cmp_ge_u32_e64 s[18:19], v220, s57
	v_cmp_ge_u32_e64 s[22:23], v221, s57
	s_bcnt1_i32_b64 s89, s[8:9]
	s_bcnt1_i32_b64 s61, s[12:13]
	s_add_u32 s89, s89, s61
	s_bcnt1_i32_b64 s61, s[14:15]
	s_add_u32 s89, s89, s61
	s_bcnt1_i32_b64 s61, s[16:17]
	s_add_u32 s89, s89, s61
	s_bcnt1_i32_b64 s61, s[18:19]
	s_add_u32 s89, s89, s61
	s_bcnt1_i32_b64 s61, s[22:23]
	s_add_u32 s89, s89, s61
	s_cmp_ge_u32 s89, s91
	s_cselect_b32 s33, s57, s33
	s_cmp_eq_u32 s89, s91
	s_cbranch_scc1 .Lref_e6
	s_or_b32 s57, s33, 0x400
	v_cmp_ge_u32_e64 s[8:9], v216, s57
	v_cmp_ge_u32_e64 s[12:13], v217, s57
	v_cmp_ge_u32_e64 s[14:15], v218, s57
	v_cmp_ge_u32_e64 s[16:17], v219, s57
	v_cmp_ge_u32_e64 s[18:19], v220, s57
	v_cmp_ge_u32_e64 s[22:23], v221, s57
	s_bcnt1_i32_b64 s89, s[8:9]
	s_bcnt1_i32_b64 s61, s[12:13]
	s_add_u32 s89, s89, s61
	s_bcnt1_i32_b64 s61, s[14:15]
	s_add_u32 s89, s89, s61
	s_bcnt1_i32_b64 s61, s[16:17]
	s_add_u32 s89, s89, s61
	s_bcnt1_i32_b64 s61, s[18:19]
	s_add_u32 s89, s89, s61
	s_bcnt1_i32_b64 s61, s[22:23]
	s_add_u32 s89, s89, s61
	s_cmp_ge_u32 s89, s91
	s_cselect_b32 s33, s57, s33
	s_cmp_eq_u32 s89, s91
	s_cbranch_scc1 .Lref_e6
	s_or_b32 s57, s33, 0x200
	v_cmp_ge_u32_e64 s[8:9], v216, s57
	v_cmp_ge_u32_e64 s[12:13], v217, s57
	v_cmp_ge_u32_e64 s[14:15], v218, s57
	v_cmp_ge_u32_e64 s[16:17], v219, s57
	v_cmp_ge_u32_e64 s[18:19], v220, s57
	v_cmp_ge_u32_e64 s[22:23], v221, s57
	s_bcnt1_i32_b64 s89, s[8:9]
	s_bcnt1_i32_b64 s61, s[12:13]
	s_add_u32 s89, s89, s61
	s_bcnt1_i32_b64 s61, s[14:15]
	s_add_u32 s89, s89, s61
	s_bcnt1_i32_b64 s61, s[16:17]
	s_add_u32 s89, s89, s61
	s_bcnt1_i32_b64 s61, s[18:19]
	s_add_u32 s89, s89, s61
	s_bcnt1_i32_b64 s61, s[22:23]
	s_add_u32 s89, s89, s61
	s_cmp_ge_u32 s89, s91
	s_cselect_b32 s33, s57, s33
	s_cmp_eq_u32 s89, s91
	s_cbranch_scc1 .Lref_e6
	s_or_b32 s57, s33, 0x100
	v_cmp_ge_u32_e64 s[8:9], v216, s57
	v_cmp_ge_u32_e64 s[12:13], v217, s57
	v_cmp_ge_u32_e64 s[14:15], v218, s57
	v_cmp_ge_u32_e64 s[16:17], v219, s57
	v_cmp_ge_u32_e64 s[18:19], v220, s57
	v_cmp_ge_u32_e64 s[22:23], v221, s57
	s_bcnt1_i32_b64 s89, s[8:9]
	s_bcnt1_i32_b64 s61, s[12:13]
	s_add_u32 s89, s89, s61
	s_bcnt1_i32_b64 s61, s[14:15]
	s_add_u32 s89, s89, s61
	s_bcnt1_i32_b64 s61, s[16:17]
	s_add_u32 s89, s89, s61
	s_bcnt1_i32_b64 s61, s[18:19]
	s_add_u32 s89, s89, s61
	s_bcnt1_i32_b64 s61, s[22:23]
	s_add_u32 s89, s89, s61
	s_cmp_ge_u32 s89, s91
	s_cselect_b32 s33, s57, s33
	s_cmp_eq_u32 s89, s91
	s_cbranch_scc1 .Lref_e6
	s_or_b32 s57, s33, 0x80
	v_cmp_ge_u32_e64 s[8:9], v216, s57
	v_cmp_ge_u32_e64 s[12:13], v217, s57
	v_cmp_ge_u32_e64 s[14:15], v218, s57
	v_cmp_ge_u32_e64 s[16:17], v219, s57
	v_cmp_ge_u32_e64 s[18:19], v220, s57
	v_cmp_ge_u32_e64 s[22:23], v221, s57
	s_bcnt1_i32_b64 s89, s[8:9]
	s_bcnt1_i32_b64 s61, s[12:13]
	s_add_u32 s89, s89, s61
	s_bcnt1_i32_b64 s61, s[14:15]
	s_add_u32 s89, s89, s61
	s_bcnt1_i32_b64 s61, s[16:17]
	s_add_u32 s89, s89, s61
	s_bcnt1_i32_b64 s61, s[18:19]
	s_add_u32 s89, s89, s61
	s_bcnt1_i32_b64 s61, s[22:23]
	s_add_u32 s89, s89, s61
	s_cmp_ge_u32 s89, s91
	s_cselect_b32 s33, s57, s33
	s_cmp_eq_u32 s89, s91
	s_cbranch_scc1 .Lref_e6
	s_or_b32 s57, s33, 0x40
	v_cmp_ge_u32_e64 s[8:9], v216, s57
	v_cmp_ge_u32_e64 s[12:13], v217, s57
	v_cmp_ge_u32_e64 s[14:15], v218, s57
	v_cmp_ge_u32_e64 s[16:17], v219, s57
	v_cmp_ge_u32_e64 s[18:19], v220, s57
	v_cmp_ge_u32_e64 s[22:23], v221, s57
	s_bcnt1_i32_b64 s89, s[8:9]
	s_bcnt1_i32_b64 s61, s[12:13]
	s_add_u32 s89, s89, s61
	s_bcnt1_i32_b64 s61, s[14:15]
	s_add_u32 s89, s89, s61
	s_bcnt1_i32_b64 s61, s[16:17]
	s_add_u32 s89, s89, s61
	s_bcnt1_i32_b64 s61, s[18:19]
	s_add_u32 s89, s89, s61
	s_bcnt1_i32_b64 s61, s[22:23]
	s_add_u32 s89, s89, s61
	s_cmp_ge_u32 s89, s91
	s_cselect_b32 s33, s57, s33
	s_cmp_eq_u32 s89, s91
	s_cbranch_scc1 .Lref_e6
	s_or_b32 s57, s33, 0x20
	v_cmp_ge_u32_e64 s[8:9], v216, s57
	v_cmp_ge_u32_e64 s[12:13], v217, s57
	v_cmp_ge_u32_e64 s[14:15], v218, s57
	v_cmp_ge_u32_e64 s[16:17], v219, s57
	v_cmp_ge_u32_e64 s[18:19], v220, s57
	v_cmp_ge_u32_e64 s[22:23], v221, s57
	s_bcnt1_i32_b64 s89, s[8:9]
	s_bcnt1_i32_b64 s61, s[12:13]
	s_add_u32 s89, s89, s61
	s_bcnt1_i32_b64 s61, s[14:15]
	s_add_u32 s89, s89, s61
	s_bcnt1_i32_b64 s61, s[16:17]
	s_add_u32 s89, s89, s61
	s_bcnt1_i32_b64 s61, s[18:19]
	s_add_u32 s89, s89, s61
	s_bcnt1_i32_b64 s61, s[22:23]
	s_add_u32 s89, s89, s61
	s_cmp_ge_u32 s89, s91
	s_cselect_b32 s33, s57, s33
	s_cmp_eq_u32 s89, s91
	s_cbranch_scc1 .Lref_e6
	s_or_b32 s57, s33, 0x10
	v_cmp_ge_u32_e64 s[8:9], v216, s57
	v_cmp_ge_u32_e64 s[12:13], v217, s57
	v_cmp_ge_u32_e64 s[14:15], v218, s57
	v_cmp_ge_u32_e64 s[16:17], v219, s57
	v_cmp_ge_u32_e64 s[18:19], v220, s57
	v_cmp_ge_u32_e64 s[22:23], v221, s57
	s_bcnt1_i32_b64 s89, s[8:9]
	s_bcnt1_i32_b64 s61, s[12:13]
	s_add_u32 s89, s89, s61
	s_bcnt1_i32_b64 s61, s[14:15]
	s_add_u32 s89, s89, s61
	s_bcnt1_i32_b64 s61, s[16:17]
	s_add_u32 s89, s89, s61
	s_bcnt1_i32_b64 s61, s[18:19]
	s_add_u32 s89, s89, s61
	s_bcnt1_i32_b64 s61, s[22:23]
	s_add_u32 s89, s89, s61
	s_cmp_ge_u32 s89, s91
	s_cselect_b32 s33, s57, s33
	s_cmp_eq_u32 s89, s91
	s_cbranch_scc1 .Lref_e6
	s_or_b32 s57, s33, 0x8
	v_cmp_ge_u32_e64 s[8:9], v216, s57
	v_cmp_ge_u32_e64 s[12:13], v217, s57
	v_cmp_ge_u32_e64 s[14:15], v218, s57
	v_cmp_ge_u32_e64 s[16:17], v219, s57
	v_cmp_ge_u32_e64 s[18:19], v220, s57
	v_cmp_ge_u32_e64 s[22:23], v221, s57
	s_bcnt1_i32_b64 s89, s[8:9]
	s_bcnt1_i32_b64 s61, s[12:13]
	s_add_u32 s89, s89, s61
	s_bcnt1_i32_b64 s61, s[14:15]
	s_add_u32 s89, s89, s61
	s_bcnt1_i32_b64 s61, s[16:17]
	s_add_u32 s89, s89, s61
	s_bcnt1_i32_b64 s61, s[18:19]
	s_add_u32 s89, s89, s61
	s_bcnt1_i32_b64 s61, s[22:23]
	s_add_u32 s89, s89, s61
	s_cmp_ge_u32 s89, s91
	s_cselect_b32 s33, s57, s33
	s_cmp_eq_u32 s89, s91
	s_cbranch_scc1 .Lref_e6
	s_or_b32 s57, s33, 0x4
	v_cmp_ge_u32_e64 s[8:9], v216, s57
	v_cmp_ge_u32_e64 s[12:13], v217, s57
	v_cmp_ge_u32_e64 s[14:15], v218, s57
	v_cmp_ge_u32_e64 s[16:17], v219, s57
	v_cmp_ge_u32_e64 s[18:19], v220, s57
	v_cmp_ge_u32_e64 s[22:23], v221, s57
	s_bcnt1_i32_b64 s89, s[8:9]
	s_bcnt1_i32_b64 s61, s[12:13]
	s_add_u32 s89, s89, s61
	s_bcnt1_i32_b64 s61, s[14:15]
	s_add_u32 s89, s89, s61
	s_bcnt1_i32_b64 s61, s[16:17]
	s_add_u32 s89, s89, s61
	s_bcnt1_i32_b64 s61, s[18:19]
	s_add_u32 s89, s89, s61
	s_bcnt1_i32_b64 s61, s[22:23]
	s_add_u32 s89, s89, s61
	s_cmp_ge_u32 s89, s91
	s_cselect_b32 s33, s57, s33
	s_cmp_eq_u32 s89, s91
	s_cbranch_scc1 .Lref_e6
	s_or_b32 s57, s33, 0x2
	v_cmp_ge_u32_e64 s[8:9], v216, s57
	v_cmp_ge_u32_e64 s[12:13], v217, s57
	v_cmp_ge_u32_e64 s[14:15], v218, s57
	v_cmp_ge_u32_e64 s[16:17], v219, s57
	v_cmp_ge_u32_e64 s[18:19], v220, s57
	v_cmp_ge_u32_e64 s[22:23], v221, s57
	s_bcnt1_i32_b64 s89, s[8:9]
	s_bcnt1_i32_b64 s61, s[12:13]
	s_add_u32 s89, s89, s61
	s_bcnt1_i32_b64 s61, s[14:15]
	s_add_u32 s89, s89, s61
	s_bcnt1_i32_b64 s61, s[16:17]
	s_add_u32 s89, s89, s61
	s_bcnt1_i32_b64 s61, s[18:19]
	s_add_u32 s89, s89, s61
	s_bcnt1_i32_b64 s61, s[22:23]
	s_add_u32 s89, s89, s61
	s_cmp_ge_u32 s89, s91
	s_cselect_b32 s33, s57, s33
	s_cmp_eq_u32 s89, s91
	s_cbranch_scc1 .Lref_e6
	s_or_b32 s57, s33, 0x1
	v_cmp_ge_u32_e64 s[8:9], v216, s57
	v_cmp_ge_u32_e64 s[12:13], v217, s57
	v_cmp_ge_u32_e64 s[14:15], v218, s57
	v_cmp_ge_u32_e64 s[16:17], v219, s57
	v_cmp_ge_u32_e64 s[18:19], v220, s57
	v_cmp_ge_u32_e64 s[22:23], v221, s57
	s_bcnt1_i32_b64 s89, s[8:9]
	s_bcnt1_i32_b64 s61, s[12:13]
	s_add_u32 s89, s89, s61
	s_bcnt1_i32_b64 s61, s[14:15]
	s_add_u32 s89, s89, s61
	s_bcnt1_i32_b64 s61, s[16:17]
	s_add_u32 s89, s89, s61
	s_bcnt1_i32_b64 s61, s[18:19]
	s_add_u32 s89, s89, s61
	s_bcnt1_i32_b64 s61, s[22:23]
	s_add_u32 s89, s89, s61
	s_cmp_ge_u32 s89, s91
	s_cselect_b32 s33, s57, s33
	s_cmp_eq_u32 s89, s91
	s_cbranch_scc1 .Lref_e6
	v_cmp_gt_u32_e64 s[8:9], v216, s33
	v_cmp_gt_u32_e64 s[12:13], v217, s33
	v_cmp_gt_u32_e64 s[14:15], v218, s33
	v_cmp_gt_u32_e64 s[16:17], v219, s33
	v_cmp_gt_u32_e64 s[18:19], v220, s33
	v_cmp_gt_u32_e64 s[22:23], v221, s33
	s_bcnt1_i32_b64 s89, s[8:9]
	s_bcnt1_i32_b64 s61, s[12:13]
	s_add_u32 s89, s89, s61
	s_bcnt1_i32_b64 s61, s[14:15]
	s_add_u32 s89, s89, s61
	s_bcnt1_i32_b64 s61, s[16:17]
	s_add_u32 s89, s89, s61
	s_bcnt1_i32_b64 s61, s[18:19]
	s_add_u32 s89, s89, s61
	s_bcnt1_i32_b64 s61, s[22:23]
	s_add_u32 s89, s89, s61
	s_sub_u32 s91, s91, s89
	v_cmp_eq_u32_e64 s[8:9], v216, s33
	v_cmp_eq_u32_e64 s[12:13], v217, s33
	v_cmp_eq_u32_e64 s[14:15], v218, s33
	v_cmp_eq_u32_e64 s[16:17], v219, s33
	v_cmp_eq_u32_e64 s[18:19], v220, s33
	v_cmp_eq_u32_e64 s[22:23], v221, s33
	s_bcnt1_i32_b64 s89, s[8:9]
	s_bcnt1_i32_b64 s61, s[12:13]
	s_add_u32 s89, s89, s61
	s_bcnt1_i32_b64 s61, s[14:15]
	s_add_u32 s89, s89, s61
	s_bcnt1_i32_b64 s61, s[16:17]
	s_add_u32 s89, s89, s61
	s_bcnt1_i32_b64 s61, s[18:19]
	s_add_u32 s89, s89, s61
	s_bcnt1_i32_b64 s61, s[22:23]
	s_add_u32 s89, s89, s61
	s_add_u32 s57, s33, 1
	s_cmp_eq_u32 s91, s89
	s_cselect_b32 s57, s33, s57
	s_cselect_b32 s60, 1, 0
	s_branch .Lref_emit6

.Lref_v5:
	ds_read_u16 v224, v245
	ds_read_u16 v225, v245 offset:128
	ds_read_u16 v226, v245 offset:256
	ds_read_u16 v227, v245 offset:384
	ds_read_u16 v228, v245 offset:512
	v_cmp_gt_u32_e64 s[8:9], s93, v145
	v_add_u32_e32 v241, 64, v145
	v_cmp_gt_u32_e64 s[12:13], s93, v241
	v_add_u32_e32 v241, 128, v145
	v_cmp_gt_u32_e64 s[14:15], s93, v241
	v_add_u32_e32 v241, 192, v145
	v_cmp_gt_u32_e64 s[16:17], s93, v241
	v_add_u32_e32 v241, 256, v145
	v_cmp_gt_u32_e64 s[18:19], s93, v241
	s_waitcnt lgkmcnt(0)
	v_cndmask_b32_e64 v248, 0, v224, s[8:9]
	v_cndmask_b32_e64 v249, 0, v225, s[12:13]
	v_cndmask_b32_e64 v250, 0, v226, s[14:15]
	v_cndmask_b32_e64 v251, 0, v227, s[16:17]
	v_cndmask_b32_e64 v252, 0, v228, s[18:19]
	v_lshl_add_u32 v248, v248, 2, s89
	v_lshl_add_u32 v249, v249, 2, s89
	v_lshl_add_u32 v250, v250, 2, s89
	v_lshl_add_u32 v251, v251, 2, s89
	v_lshl_add_u32 v252, v252, 2, s89
	ds_read_b32 v216, v248
	ds_read_b32 v217, v249
	ds_read_b32 v218, v250
	ds_read_b32 v219, v251
	ds_read_b32 v220, v252
	s_waitcnt lgkmcnt(0)
	v_cndmask_b32_e64 v216, 0, v216, s[8:9]
	v_cndmask_b32_e64 v217, 0, v217, s[12:13]
	v_cndmask_b32_e64 v218, 0, v218, s[14:15]
	v_cndmask_b32_e64 v219, 0, v219, s[16:17]
	v_cndmask_b32_e64 v220, 0, v220, s[18:19]
	s_or_b32 s57, s33, 0x100000
	v_cmp_ge_u32_e64 s[8:9], v216, s57
	v_cmp_ge_u32_e64 s[12:13], v217, s57
	v_cmp_ge_u32_e64 s[14:15], v218, s57
	v_cmp_ge_u32_e64 s[16:17], v219, s57
	v_cmp_ge_u32_e64 s[18:19], v220, s57
	s_bcnt1_i32_b64 s89, s[8:9]
	s_bcnt1_i32_b64 s61, s[12:13]
	s_add_u32 s89, s89, s61
	s_bcnt1_i32_b64 s61, s[14:15]
	s_add_u32 s89, s89, s61
	s_bcnt1_i32_b64 s61, s[16:17]
	s_add_u32 s89, s89, s61
	s_bcnt1_i32_b64 s61, s[18:19]
	s_add_u32 s89, s89, s61
	s_cmp_ge_u32 s89, s91
	s_cselect_b32 s33, s57, s33
	s_cmp_eq_u32 s89, s91
	s_cbranch_scc1 .Lref_e5
	s_or_b32 s57, s33, 0x80000
	v_cmp_ge_u32_e64 s[8:9], v216, s57
	v_cmp_ge_u32_e64 s[12:13], v217, s57
	v_cmp_ge_u32_e64 s[14:15], v218, s57
	v_cmp_ge_u32_e64 s[16:17], v219, s57
	v_cmp_ge_u32_e64 s[18:19], v220, s57
	s_bcnt1_i32_b64 s89, s[8:9]
	s_bcnt1_i32_b64 s61, s[12:13]
	s_add_u32 s89, s89, s61
	s_bcnt1_i32_b64 s61, s[14:15]
	s_add_u32 s89, s89, s61
	s_bcnt1_i32_b64 s61, s[16:17]
	s_add_u32 s89, s89, s61
	s_bcnt1_i32_b64 s61, s[18:19]
	s_add_u32 s89, s89, s61
	s_cmp_ge_u32 s89, s91
	s_cselect_b32 s33, s57, s33
	s_cmp_eq_u32 s89, s91
	s_cbranch_scc1 .Lref_e5
	s_or_b32 s57, s33, 0x40000
	v_cmp_ge_u32_e64 s[8:9], v216, s57
	v_cmp_ge_u32_e64 s[12:13], v217, s57
	v_cmp_ge_u32_e64 s[14:15], v218, s57
	v_cmp_ge_u32_e64 s[16:17], v219, s57
	v_cmp_ge_u32_e64 s[18:19], v220, s57
	s_bcnt1_i32_b64 s89, s[8:9]
	s_bcnt1_i32_b64 s61, s[12:13]
	s_add_u32 s89, s89, s61
	s_bcnt1_i32_b64 s61, s[14:15]
	s_add_u32 s89, s89, s61
	s_bcnt1_i32_b64 s61, s[16:17]
	s_add_u32 s89, s89, s61
	s_bcnt1_i32_b64 s61, s[18:19]
	s_add_u32 s89, s89, s61
	s_cmp_ge_u32 s89, s91
	s_cselect_b32 s33, s57, s33
	s_cmp_eq_u32 s89, s91
	s_cbranch_scc1 .Lref_e5
	s_or_b32 s57, s33, 0x20000
	v_cmp_ge_u32_e64 s[8:9], v216, s57
	v_cmp_ge_u32_e64 s[12:13], v217, s57
	v_cmp_ge_u32_e64 s[14:15], v218, s57
	v_cmp_ge_u32_e64 s[16:17], v219, s57
	v_cmp_ge_u32_e64 s[18:19], v220, s57
	s_bcnt1_i32_b64 s89, s[8:9]
	s_bcnt1_i32_b64 s61, s[12:13]
	s_add_u32 s89, s89, s61
	s_bcnt1_i32_b64 s61, s[14:15]
	s_add_u32 s89, s89, s61
	s_bcnt1_i32_b64 s61, s[16:17]
	s_add_u32 s89, s89, s61
	s_bcnt1_i32_b64 s61, s[18:19]
	s_add_u32 s89, s89, s61
	s_cmp_ge_u32 s89, s91
	s_cselect_b32 s33, s57, s33
	s_cmp_eq_u32 s89, s91
	s_cbranch_scc1 .Lref_e5
	s_or_b32 s57, s33, 0x10000
	v_cmp_ge_u32_e64 s[8:9], v216, s57
	v_cmp_ge_u32_e64 s[12:13], v217, s57
	v_cmp_ge_u32_e64 s[14:15], v218, s57
	v_cmp_ge_u32_e64 s[16:17], v219, s57
	v_cmp_ge_u32_e64 s[18:19], v220, s57
	s_bcnt1_i32_b64 s89, s[8:9]
	s_bcnt1_i32_b64 s61, s[12:13]
	s_add_u32 s89, s89, s61
	s_bcnt1_i32_b64 s61, s[14:15]
	s_add_u32 s89, s89, s61
	s_bcnt1_i32_b64 s61, s[16:17]
	s_add_u32 s89, s89, s61
	s_bcnt1_i32_b64 s61, s[18:19]
	s_add_u32 s89, s89, s61
	s_cmp_ge_u32 s89, s91
	s_cselect_b32 s33, s57, s33
	s_cmp_eq_u32 s89, s91
	s_cbranch_scc1 .Lref_e5
	s_or_b32 s57, s33, 0x8000
	v_cmp_ge_u32_e64 s[8:9], v216, s57
	v_cmp_ge_u32_e64 s[12:13], v217, s57
	v_cmp_ge_u32_e64 s[14:15], v218, s57
	v_cmp_ge_u32_e64 s[16:17], v219, s57
	v_cmp_ge_u32_e64 s[18:19], v220, s57
	s_bcnt1_i32_b64 s89, s[8:9]
	s_bcnt1_i32_b64 s61, s[12:13]
	s_add_u32 s89, s89, s61
	s_bcnt1_i32_b64 s61, s[14:15]
	s_add_u32 s89, s89, s61
	s_bcnt1_i32_b64 s61, s[16:17]
	s_add_u32 s89, s89, s61
	s_bcnt1_i32_b64 s61, s[18:19]
	s_add_u32 s89, s89, s61
	s_cmp_ge_u32 s89, s91
	s_cselect_b32 s33, s57, s33
	s_cmp_eq_u32 s89, s91
	s_cbranch_scc1 .Lref_e5
	s_or_b32 s57, s33, 0x4000
	v_cmp_ge_u32_e64 s[8:9], v216, s57
	v_cmp_ge_u32_e64 s[12:13], v217, s57
	v_cmp_ge_u32_e64 s[14:15], v218, s57
	v_cmp_ge_u32_e64 s[16:17], v219, s57
	v_cmp_ge_u32_e64 s[18:19], v220, s57
	s_bcnt1_i32_b64 s89, s[8:9]
	s_bcnt1_i32_b64 s61, s[12:13]
	s_add_u32 s89, s89, s61
	s_bcnt1_i32_b64 s61, s[14:15]
	s_add_u32 s89, s89, s61
	s_bcnt1_i32_b64 s61, s[16:17]
	s_add_u32 s89, s89, s61
	s_bcnt1_i32_b64 s61, s[18:19]
	s_add_u32 s89, s89, s61
	s_cmp_ge_u32 s89, s91
	s_cselect_b32 s33, s57, s33
	s_cmp_eq_u32 s89, s91
	s_cbranch_scc1 .Lref_e5
	s_or_b32 s57, s33, 0x2000
	v_cmp_ge_u32_e64 s[8:9], v216, s57
	v_cmp_ge_u32_e64 s[12:13], v217, s57
	v_cmp_ge_u32_e64 s[14:15], v218, s57
	v_cmp_ge_u32_e64 s[16:17], v219, s57
	v_cmp_ge_u32_e64 s[18:19], v220, s57
	s_bcnt1_i32_b64 s89, s[8:9]
	s_bcnt1_i32_b64 s61, s[12:13]
	s_add_u32 s89, s89, s61
	s_bcnt1_i32_b64 s61, s[14:15]
	s_add_u32 s89, s89, s61
	s_bcnt1_i32_b64 s61, s[16:17]
	s_add_u32 s89, s89, s61
	s_bcnt1_i32_b64 s61, s[18:19]
	s_add_u32 s89, s89, s61
	s_cmp_ge_u32 s89, s91
	s_cselect_b32 s33, s57, s33
	s_cmp_eq_u32 s89, s91
	s_cbranch_scc1 .Lref_e5
	s_or_b32 s57, s33, 0x1000
	v_cmp_ge_u32_e64 s[8:9], v216, s57
	v_cmp_ge_u32_e64 s[12:13], v217, s57
	v_cmp_ge_u32_e64 s[14:15], v218, s57
	v_cmp_ge_u32_e64 s[16:17], v219, s57
	v_cmp_ge_u32_e64 s[18:19], v220, s57
	s_bcnt1_i32_b64 s89, s[8:9]
	s_bcnt1_i32_b64 s61, s[12:13]
	s_add_u32 s89, s89, s61
	s_bcnt1_i32_b64 s61, s[14:15]
	s_add_u32 s89, s89, s61
	s_bcnt1_i32_b64 s61, s[16:17]
	s_add_u32 s89, s89, s61
	s_bcnt1_i32_b64 s61, s[18:19]
	s_add_u32 s89, s89, s61
	s_cmp_ge_u32 s89, s91
	s_cselect_b32 s33, s57, s33
	s_cmp_eq_u32 s89, s91
	s_cbranch_scc1 .Lref_e5
	s_or_b32 s57, s33, 0x800
	v_cmp_ge_u32_e64 s[8:9], v216, s57
	v_cmp_ge_u32_e64 s[12:13], v217, s57
	v_cmp_ge_u32_e64 s[14:15], v218, s57
	v_cmp_ge_u32_e64 s[16:17], v219, s57
	v_cmp_ge_u32_e64 s[18:19], v220, s57
	s_bcnt1_i32_b64 s89, s[8:9]
	s_bcnt1_i32_b64 s61, s[12:13]
	s_add_u32 s89, s89, s61
	s_bcnt1_i32_b64 s61, s[14:15]
	s_add_u32 s89, s89, s61
	s_bcnt1_i32_b64 s61, s[16:17]
	s_add_u32 s89, s89, s61
	s_bcnt1_i32_b64 s61, s[18:19]
	s_add_u32 s89, s89, s61
	s_cmp_ge_u32 s89, s91
	s_cselect_b32 s33, s57, s33
	s_cmp_eq_u32 s89, s91
	s_cbranch_scc1 .Lref_e5
	s_or_b32 s57, s33, 0x400
	v_cmp_ge_u32_e64 s[8:9], v216, s57
	v_cmp_ge_u32_e64 s[12:13], v217, s57
	v_cmp_ge_u32_e64 s[14:15], v218, s57
	v_cmp_ge_u32_e64 s[16:17], v219, s57
	v_cmp_ge_u32_e64 s[18:19], v220, s57
	s_bcnt1_i32_b64 s89, s[8:9]
	s_bcnt1_i32_b64 s61, s[12:13]
	s_add_u32 s89, s89, s61
	s_bcnt1_i32_b64 s61, s[14:15]
	s_add_u32 s89, s89, s61
	s_bcnt1_i32_b64 s61, s[16:17]
	s_add_u32 s89, s89, s61
	s_bcnt1_i32_b64 s61, s[18:19]
	s_add_u32 s89, s89, s61
	s_cmp_ge_u32 s89, s91
	s_cselect_b32 s33, s57, s33
	s_cmp_eq_u32 s89, s91
	s_cbranch_scc1 .Lref_e5
	s_or_b32 s57, s33, 0x200
	v_cmp_ge_u32_e64 s[8:9], v216, s57
	v_cmp_ge_u32_e64 s[12:13], v217, s57
	v_cmp_ge_u32_e64 s[14:15], v218, s57
	v_cmp_ge_u32_e64 s[16:17], v219, s57
	v_cmp_ge_u32_e64 s[18:19], v220, s57
	s_bcnt1_i32_b64 s89, s[8:9]
	s_bcnt1_i32_b64 s61, s[12:13]
	s_add_u32 s89, s89, s61
	s_bcnt1_i32_b64 s61, s[14:15]
	s_add_u32 s89, s89, s61
	s_bcnt1_i32_b64 s61, s[16:17]
	s_add_u32 s89, s89, s61
	s_bcnt1_i32_b64 s61, s[18:19]
	s_add_u32 s89, s89, s61
	s_cmp_ge_u32 s89, s91
	s_cselect_b32 s33, s57, s33
	s_cmp_eq_u32 s89, s91
	s_cbranch_scc1 .Lref_e5
	s_or_b32 s57, s33, 0x100
	v_cmp_ge_u32_e64 s[8:9], v216, s57
	v_cmp_ge_u32_e64 s[12:13], v217, s57
	v_cmp_ge_u32_e64 s[14:15], v218, s57
	v_cmp_ge_u32_e64 s[16:17], v219, s57
	v_cmp_ge_u32_e64 s[18:19], v220, s57
	s_bcnt1_i32_b64 s89, s[8:9]
	s_bcnt1_i32_b64 s61, s[12:13]
	s_add_u32 s89, s89, s61
	s_bcnt1_i32_b64 s61, s[14:15]
	s_add_u32 s89, s89, s61
	s_bcnt1_i32_b64 s61, s[16:17]
	s_add_u32 s89, s89, s61
	s_bcnt1_i32_b64 s61, s[18:19]
	s_add_u32 s89, s89, s61
	s_cmp_ge_u32 s89, s91
	s_cselect_b32 s33, s57, s33
	s_cmp_eq_u32 s89, s91
	s_cbranch_scc1 .Lref_e5
	s_or_b32 s57, s33, 0x80
	v_cmp_ge_u32_e64 s[8:9], v216, s57
	v_cmp_ge_u32_e64 s[12:13], v217, s57
	v_cmp_ge_u32_e64 s[14:15], v218, s57
	v_cmp_ge_u32_e64 s[16:17], v219, s57
	v_cmp_ge_u32_e64 s[18:19], v220, s57
	s_bcnt1_i32_b64 s89, s[8:9]
	s_bcnt1_i32_b64 s61, s[12:13]
	s_add_u32 s89, s89, s61
	s_bcnt1_i32_b64 s61, s[14:15]
	s_add_u32 s89, s89, s61
	s_bcnt1_i32_b64 s61, s[16:17]
	s_add_u32 s89, s89, s61
	s_bcnt1_i32_b64 s61, s[18:19]
	s_add_u32 s89, s89, s61
	s_cmp_ge_u32 s89, s91
	s_cselect_b32 s33, s57, s33
	s_cmp_eq_u32 s89, s91
	s_cbranch_scc1 .Lref_e5
	s_or_b32 s57, s33, 0x40
	v_cmp_ge_u32_e64 s[8:9], v216, s57
	v_cmp_ge_u32_e64 s[12:13], v217, s57
	v_cmp_ge_u32_e64 s[14:15], v218, s57
	v_cmp_ge_u32_e64 s[16:17], v219, s57
	v_cmp_ge_u32_e64 s[18:19], v220, s57
	s_bcnt1_i32_b64 s89, s[8:9]
	s_bcnt1_i32_b64 s61, s[12:13]
	s_add_u32 s89, s89, s61
	s_bcnt1_i32_b64 s61, s[14:15]
	s_add_u32 s89, s89, s61
	s_bcnt1_i32_b64 s61, s[16:17]
	s_add_u32 s89, s89, s61
	s_bcnt1_i32_b64 s61, s[18:19]
	s_add_u32 s89, s89, s61
	s_cmp_ge_u32 s89, s91
	s_cselect_b32 s33, s57, s33
	s_cmp_eq_u32 s89, s91
	s_cbranch_scc1 .Lref_e5
	s_or_b32 s57, s33, 0x20
	v_cmp_ge_u32_e64 s[8:9], v216, s57
	v_cmp_ge_u32_e64 s[12:13], v217, s57
	v_cmp_ge_u32_e64 s[14:15], v218, s57
	v_cmp_ge_u32_e64 s[16:17], v219, s57
	v_cmp_ge_u32_e64 s[18:19], v220, s57
	s_bcnt1_i32_b64 s89, s[8:9]
	s_bcnt1_i32_b64 s61, s[12:13]
	s_add_u32 s89, s89, s61
	s_bcnt1_i32_b64 s61, s[14:15]
	s_add_u32 s89, s89, s61
	s_bcnt1_i32_b64 s61, s[16:17]
	s_add_u32 s89, s89, s61
	s_bcnt1_i32_b64 s61, s[18:19]
	s_add_u32 s89, s89, s61
	s_cmp_ge_u32 s89, s91
	s_cselect_b32 s33, s57, s33
	s_cmp_eq_u32 s89, s91
	s_cbranch_scc1 .Lref_e5
	s_or_b32 s57, s33, 0x10
	v_cmp_ge_u32_e64 s[8:9], v216, s57
	v_cmp_ge_u32_e64 s[12:13], v217, s57
	v_cmp_ge_u32_e64 s[14:15], v218, s57
	v_cmp_ge_u32_e64 s[16:17], v219, s57
	v_cmp_ge_u32_e64 s[18:19], v220, s57
	s_bcnt1_i32_b64 s89, s[8:9]
	s_bcnt1_i32_b64 s61, s[12:13]
	s_add_u32 s89, s89, s61
	s_bcnt1_i32_b64 s61, s[14:15]
	s_add_u32 s89, s89, s61
	s_bcnt1_i32_b64 s61, s[16:17]
	s_add_u32 s89, s89, s61
	s_bcnt1_i32_b64 s61, s[18:19]
	s_add_u32 s89, s89, s61
	s_cmp_ge_u32 s89, s91
	s_cselect_b32 s33, s57, s33
	s_cmp_eq_u32 s89, s91
	s_cbranch_scc1 .Lref_e5
	s_or_b32 s57, s33, 0x8
	v_cmp_ge_u32_e64 s[8:9], v216, s57
	v_cmp_ge_u32_e64 s[12:13], v217, s57
	v_cmp_ge_u32_e64 s[14:15], v218, s57
	v_cmp_ge_u32_e64 s[16:17], v219, s57
	v_cmp_ge_u32_e64 s[18:19], v220, s57
	s_bcnt1_i32_b64 s89, s[8:9]
	s_bcnt1_i32_b64 s61, s[12:13]
	s_add_u32 s89, s89, s61
	s_bcnt1_i32_b64 s61, s[14:15]
	s_add_u32 s89, s89, s61
	s_bcnt1_i32_b64 s61, s[16:17]
	s_add_u32 s89, s89, s61
	s_bcnt1_i32_b64 s61, s[18:19]
	s_add_u32 s89, s89, s61
	s_cmp_ge_u32 s89, s91
	s_cselect_b32 s33, s57, s33
	s_cmp_eq_u32 s89, s91
	s_cbranch_scc1 .Lref_e5
	s_or_b32 s57, s33, 0x4
	v_cmp_ge_u32_e64 s[8:9], v216, s57
	v_cmp_ge_u32_e64 s[12:13], v217, s57
	v_cmp_ge_u32_e64 s[14:15], v218, s57
	v_cmp_ge_u32_e64 s[16:17], v219, s57
	v_cmp_ge_u32_e64 s[18:19], v220, s57
	s_bcnt1_i32_b64 s89, s[8:9]
	s_bcnt1_i32_b64 s61, s[12:13]
	s_add_u32 s89, s89, s61
	s_bcnt1_i32_b64 s61, s[14:15]
	s_add_u32 s89, s89, s61
	s_bcnt1_i32_b64 s61, s[16:17]
	s_add_u32 s89, s89, s61
	s_bcnt1_i32_b64 s61, s[18:19]
	s_add_u32 s89, s89, s61
	s_cmp_ge_u32 s89, s91
	s_cselect_b32 s33, s57, s33
	s_cmp_eq_u32 s89, s91
	s_cbranch_scc1 .Lref_e5
	s_or_b32 s57, s33, 0x2
	v_cmp_ge_u32_e64 s[8:9], v216, s57
	v_cmp_ge_u32_e64 s[12:13], v217, s57
	v_cmp_ge_u32_e64 s[14:15], v218, s57
	v_cmp_ge_u32_e64 s[16:17], v219, s57
	v_cmp_ge_u32_e64 s[18:19], v220, s57
	s_bcnt1_i32_b64 s89, s[8:9]
	s_bcnt1_i32_b64 s61, s[12:13]
	s_add_u32 s89, s89, s61
	s_bcnt1_i32_b64 s61, s[14:15]
	s_add_u32 s89, s89, s61
	s_bcnt1_i32_b64 s61, s[16:17]
	s_add_u32 s89, s89, s61
	s_bcnt1_i32_b64 s61, s[18:19]
	s_add_u32 s89, s89, s61
	s_cmp_ge_u32 s89, s91
	s_cselect_b32 s33, s57, s33
	s_cmp_eq_u32 s89, s91
	s_cbranch_scc1 .Lref_e5
	s_or_b32 s57, s33, 0x1
	v_cmp_ge_u32_e64 s[8:9], v216, s57
	v_cmp_ge_u32_e64 s[12:13], v217, s57
	v_cmp_ge_u32_e64 s[14:15], v218, s57
	v_cmp_ge_u32_e64 s[16:17], v219, s57
	v_cmp_ge_u32_e64 s[18:19], v220, s57
	s_bcnt1_i32_b64 s89, s[8:9]
	s_bcnt1_i32_b64 s61, s[12:13]
	s_add_u32 s89, s89, s61
	s_bcnt1_i32_b64 s61, s[14:15]
	s_add_u32 s89, s89, s61
	s_bcnt1_i32_b64 s61, s[16:17]
	s_add_u32 s89, s89, s61
	s_bcnt1_i32_b64 s61, s[18:19]
	s_add_u32 s89, s89, s61
	s_cmp_ge_u32 s89, s91
	s_cselect_b32 s33, s57, s33
	s_cmp_eq_u32 s89, s91
	s_cbranch_scc1 .Lref_e5
	v_cmp_gt_u32_e64 s[8:9], v216, s33
	v_cmp_gt_u32_e64 s[12:13], v217, s33
	v_cmp_gt_u32_e64 s[14:15], v218, s33
	v_cmp_gt_u32_e64 s[16:17], v219, s33
	v_cmp_gt_u32_e64 s[18:19], v220, s33
	s_bcnt1_i32_b64 s89, s[8:9]
	s_bcnt1_i32_b64 s61, s[12:13]
	s_add_u32 s89, s89, s61
	s_bcnt1_i32_b64 s61, s[14:15]
	s_add_u32 s89, s89, s61
	s_bcnt1_i32_b64 s61, s[16:17]
	s_add_u32 s89, s89, s61
	s_bcnt1_i32_b64 s61, s[18:19]
	s_add_u32 s89, s89, s61
	s_sub_u32 s91, s91, s89
	v_cmp_eq_u32_e64 s[8:9], v216, s33
	v_cmp_eq_u32_e64 s[12:13], v217, s33
	v_cmp_eq_u32_e64 s[14:15], v218, s33
	v_cmp_eq_u32_e64 s[16:17], v219, s33
	v_cmp_eq_u32_e64 s[18:19], v220, s33
	s_bcnt1_i32_b64 s89, s[8:9]
	s_bcnt1_i32_b64 s61, s[12:13]
	s_add_u32 s89, s89, s61
	s_bcnt1_i32_b64 s61, s[14:15]
	s_add_u32 s89, s89, s61
	s_bcnt1_i32_b64 s61, s[16:17]
	s_add_u32 s89, s89, s61
	s_bcnt1_i32_b64 s61, s[18:19]
	s_add_u32 s89, s89, s61
	s_add_u32 s57, s33, 1
	s_cmp_eq_u32 s91, s89
	s_cselect_b32 s57, s33, s57
	s_cselect_b32 s60, 1, 0
	s_branch .Lref_emit5

.Lref_v4:
	ds_read_u16 v224, v245
	ds_read_u16 v225, v245 offset:128
	ds_read_u16 v226, v245 offset:256
	ds_read_u16 v227, v245 offset:384
	v_cmp_gt_u32_e64 s[8:9], s93, v145
	v_add_u32_e32 v241, 64, v145
	v_cmp_gt_u32_e64 s[12:13], s93, v241
	v_add_u32_e32 v241, 128, v145
	v_cmp_gt_u32_e64 s[14:15], s93, v241
	v_add_u32_e32 v241, 192, v145
	v_cmp_gt_u32_e64 s[16:17], s93, v241
	s_waitcnt lgkmcnt(0)
	v_cndmask_b32_e64 v248, 0, v224, s[8:9]
	v_cndmask_b32_e64 v249, 0, v225, s[12:13]
	v_cndmask_b32_e64 v250, 0, v226, s[14:15]
	v_cndmask_b32_e64 v251, 0, v227, s[16:17]
	v_lshl_add_u32 v248, v248, 2, s89
	v_lshl_add_u32 v249, v249, 2, s89
	v_lshl_add_u32 v250, v250, 2, s89
	v_lshl_add_u32 v251, v251, 2, s89
	ds_read_b32 v216, v248
	ds_read_b32 v217, v249
	ds_read_b32 v218, v250
	ds_read_b32 v219, v251
	s_waitcnt lgkmcnt(0)
	v_cndmask_b32_e64 v216, 0, v216, s[8:9]
	v_cndmask_b32_e64 v217, 0, v217, s[12:13]
	v_cndmask_b32_e64 v218, 0, v218, s[14:15]
	v_cndmask_b32_e64 v219, 0, v219, s[16:17]
	s_or_b32 s57, s33, 0x100000
	v_cmp_ge_u32_e64 s[8:9], v216, s57
	v_cmp_ge_u32_e64 s[12:13], v217, s57
	v_cmp_ge_u32_e64 s[14:15], v218, s57
	v_cmp_ge_u32_e64 s[16:17], v219, s57
	s_bcnt1_i32_b64 s89, s[8:9]
	s_bcnt1_i32_b64 s61, s[12:13]
	s_add_u32 s89, s89, s61
	s_bcnt1_i32_b64 s61, s[14:15]
	s_add_u32 s89, s89, s61
	s_bcnt1_i32_b64 s61, s[16:17]
	s_add_u32 s89, s89, s61
	s_cmp_ge_u32 s89, s91
	s_cselect_b32 s33, s57, s33
	s_cmp_eq_u32 s89, s91
	s_cbranch_scc1 .Lref_e4
	s_or_b32 s57, s33, 0x80000
	v_cmp_ge_u32_e64 s[8:9], v216, s57
	v_cmp_ge_u32_e64 s[12:13], v217, s57
	v_cmp_ge_u32_e64 s[14:15], v218, s57
	v_cmp_ge_u32_e64 s[16:17], v219, s57
	s_bcnt1_i32_b64 s89, s[8:9]
	s_bcnt1_i32_b64 s61, s[12:13]
	s_add_u32 s89, s89, s61
	s_bcnt1_i32_b64 s61, s[14:15]
	s_add_u32 s89, s89, s61
	s_bcnt1_i32_b64 s61, s[16:17]
	s_add_u32 s89, s89, s61
	s_cmp_ge_u32 s89, s91
	s_cselect_b32 s33, s57, s33
	s_cmp_eq_u32 s89, s91
	s_cbranch_scc1 .Lref_e4
	s_or_b32 s57, s33, 0x40000
	v_cmp_ge_u32_e64 s[8:9], v216, s57
	v_cmp_ge_u32_e64 s[12:13], v217, s57
	v_cmp_ge_u32_e64 s[14:15], v218, s57
	v_cmp_ge_u32_e64 s[16:17], v219, s57
	s_bcnt1_i32_b64 s89, s[8:9]
	s_bcnt1_i32_b64 s61, s[12:13]
	s_add_u32 s89, s89, s61
	s_bcnt1_i32_b64 s61, s[14:15]
	s_add_u32 s89, s89, s61
	s_bcnt1_i32_b64 s61, s[16:17]
	s_add_u32 s89, s89, s61
	s_cmp_ge_u32 s89, s91
	s_cselect_b32 s33, s57, s33
	s_cmp_eq_u32 s89, s91
	s_cbranch_scc1 .Lref_e4
	s_or_b32 s57, s33, 0x20000
	v_cmp_ge_u32_e64 s[8:9], v216, s57
	v_cmp_ge_u32_e64 s[12:13], v217, s57
	v_cmp_ge_u32_e64 s[14:15], v218, s57
	v_cmp_ge_u32_e64 s[16:17], v219, s57
	s_bcnt1_i32_b64 s89, s[8:9]
	s_bcnt1_i32_b64 s61, s[12:13]
	s_add_u32 s89, s89, s61
	s_bcnt1_i32_b64 s61, s[14:15]
	s_add_u32 s89, s89, s61
	s_bcnt1_i32_b64 s61, s[16:17]
	s_add_u32 s89, s89, s61
	s_cmp_ge_u32 s89, s91
	s_cselect_b32 s33, s57, s33
	s_cmp_eq_u32 s89, s91
	s_cbranch_scc1 .Lref_e4
	s_or_b32 s57, s33, 0x10000
	v_cmp_ge_u32_e64 s[8:9], v216, s57
	v_cmp_ge_u32_e64 s[12:13], v217, s57
	v_cmp_ge_u32_e64 s[14:15], v218, s57
	v_cmp_ge_u32_e64 s[16:17], v219, s57
	s_bcnt1_i32_b64 s89, s[8:9]
	s_bcnt1_i32_b64 s61, s[12:13]
	s_add_u32 s89, s89, s61
	s_bcnt1_i32_b64 s61, s[14:15]
	s_add_u32 s89, s89, s61
	s_bcnt1_i32_b64 s61, s[16:17]
	s_add_u32 s89, s89, s61
	s_cmp_ge_u32 s89, s91
	s_cselect_b32 s33, s57, s33
	s_cmp_eq_u32 s89, s91
	s_cbranch_scc1 .Lref_e4
	s_or_b32 s57, s33, 0x8000
	v_cmp_ge_u32_e64 s[8:9], v216, s57
	v_cmp_ge_u32_e64 s[12:13], v217, s57
	v_cmp_ge_u32_e64 s[14:15], v218, s57
	v_cmp_ge_u32_e64 s[16:17], v219, s57
	s_bcnt1_i32_b64 s89, s[8:9]
	s_bcnt1_i32_b64 s61, s[12:13]
	s_add_u32 s89, s89, s61
	s_bcnt1_i32_b64 s61, s[14:15]
	s_add_u32 s89, s89, s61
	s_bcnt1_i32_b64 s61, s[16:17]
	s_add_u32 s89, s89, s61
	s_cmp_ge_u32 s89, s91
	s_cselect_b32 s33, s57, s33
	s_cmp_eq_u32 s89, s91
	s_cbranch_scc1 .Lref_e4
	s_or_b32 s57, s33, 0x4000
	v_cmp_ge_u32_e64 s[8:9], v216, s57
	v_cmp_ge_u32_e64 s[12:13], v217, s57
	v_cmp_ge_u32_e64 s[14:15], v218, s57
	v_cmp_ge_u32_e64 s[16:17], v219, s57
	s_bcnt1_i32_b64 s89, s[8:9]
	s_bcnt1_i32_b64 s61, s[12:13]
	s_add_u32 s89, s89, s61
	s_bcnt1_i32_b64 s61, s[14:15]
	s_add_u32 s89, s89, s61
	s_bcnt1_i32_b64 s61, s[16:17]
	s_add_u32 s89, s89, s61
	s_cmp_ge_u32 s89, s91
	s_cselect_b32 s33, s57, s33
	s_cmp_eq_u32 s89, s91
	s_cbranch_scc1 .Lref_e4
	s_or_b32 s57, s33, 0x2000
	v_cmp_ge_u32_e64 s[8:9], v216, s57
	v_cmp_ge_u32_e64 s[12:13], v217, s57
	v_cmp_ge_u32_e64 s[14:15], v218, s57
	v_cmp_ge_u32_e64 s[16:17], v219, s57
	s_bcnt1_i32_b64 s89, s[8:9]
	s_bcnt1_i32_b64 s61, s[12:13]
	s_add_u32 s89, s89, s61
	s_bcnt1_i32_b64 s61, s[14:15]
	s_add_u32 s89, s89, s61
	s_bcnt1_i32_b64 s61, s[16:17]
	s_add_u32 s89, s89, s61
	s_cmp_ge_u32 s89, s91
	s_cselect_b32 s33, s57, s33
	s_cmp_eq_u32 s89, s91
	s_cbranch_scc1 .Lref_e4
	s_or_b32 s57, s33, 0x1000
	v_cmp_ge_u32_e64 s[8:9], v216, s57
	v_cmp_ge_u32_e64 s[12:13], v217, s57
	v_cmp_ge_u32_e64 s[14:15], v218, s57
	v_cmp_ge_u32_e64 s[16:17], v219, s57
	s_bcnt1_i32_b64 s89, s[8:9]
	s_bcnt1_i32_b64 s61, s[12:13]
	s_add_u32 s89, s89, s61
	s_bcnt1_i32_b64 s61, s[14:15]
	s_add_u32 s89, s89, s61
	s_bcnt1_i32_b64 s61, s[16:17]
	s_add_u32 s89, s89, s61
	s_cmp_ge_u32 s89, s91
	s_cselect_b32 s33, s57, s33
	s_cmp_eq_u32 s89, s91
	s_cbranch_scc1 .Lref_e4
	s_or_b32 s57, s33, 0x800
	v_cmp_ge_u32_e64 s[8:9], v216, s57
	v_cmp_ge_u32_e64 s[12:13], v217, s57
	v_cmp_ge_u32_e64 s[14:15], v218, s57
	v_cmp_ge_u32_e64 s[16:17], v219, s57
	s_bcnt1_i32_b64 s89, s[8:9]
	s_bcnt1_i32_b64 s61, s[12:13]
	s_add_u32 s89, s89, s61
	s_bcnt1_i32_b64 s61, s[14:15]
	s_add_u32 s89, s89, s61
	s_bcnt1_i32_b64 s61, s[16:17]
	s_add_u32 s89, s89, s61
	s_cmp_ge_u32 s89, s91
	s_cselect_b32 s33, s57, s33
	s_cmp_eq_u32 s89, s91
	s_cbranch_scc1 .Lref_e4
	s_or_b32 s57, s33, 0x400
	v_cmp_ge_u32_e64 s[8:9], v216, s57
	v_cmp_ge_u32_e64 s[12:13], v217, s57
	v_cmp_ge_u32_e64 s[14:15], v218, s57
	v_cmp_ge_u32_e64 s[16:17], v219, s57
	s_bcnt1_i32_b64 s89, s[8:9]
	s_bcnt1_i32_b64 s61, s[12:13]
	s_add_u32 s89, s89, s61
	s_bcnt1_i32_b64 s61, s[14:15]
	s_add_u32 s89, s89, s61
	s_bcnt1_i32_b64 s61, s[16:17]
	s_add_u32 s89, s89, s61
	s_cmp_ge_u32 s89, s91
	s_cselect_b32 s33, s57, s33
	s_cmp_eq_u32 s89, s91
	s_cbranch_scc1 .Lref_e4
	s_or_b32 s57, s33, 0x200
	v_cmp_ge_u32_e64 s[8:9], v216, s57
	v_cmp_ge_u32_e64 s[12:13], v217, s57
	v_cmp_ge_u32_e64 s[14:15], v218, s57
	v_cmp_ge_u32_e64 s[16:17], v219, s57
	s_bcnt1_i32_b64 s89, s[8:9]
	s_bcnt1_i32_b64 s61, s[12:13]
	s_add_u32 s89, s89, s61
	s_bcnt1_i32_b64 s61, s[14:15]
	s_add_u32 s89, s89, s61
	s_bcnt1_i32_b64 s61, s[16:17]
	s_add_u32 s89, s89, s61
	s_cmp_ge_u32 s89, s91
	s_cselect_b32 s33, s57, s33
	s_cmp_eq_u32 s89, s91
	s_cbranch_scc1 .Lref_e4
	s_or_b32 s57, s33, 0x100
	v_cmp_ge_u32_e64 s[8:9], v216, s57
	v_cmp_ge_u32_e64 s[12:13], v217, s57
	v_cmp_ge_u32_e64 s[14:15], v218, s57
	v_cmp_ge_u32_e64 s[16:17], v219, s57
	s_bcnt1_i32_b64 s89, s[8:9]
	s_bcnt1_i32_b64 s61, s[12:13]
	s_add_u32 s89, s89, s61
	s_bcnt1_i32_b64 s61, s[14:15]
	s_add_u32 s89, s89, s61
	s_bcnt1_i32_b64 s61, s[16:17]
	s_add_u32 s89, s89, s61
	s_cmp_ge_u32 s89, s91
	s_cselect_b32 s33, s57, s33
	s_cmp_eq_u32 s89, s91
	s_cbranch_scc1 .Lref_e4
	s_or_b32 s57, s33, 0x80
	v_cmp_ge_u32_e64 s[8:9], v216, s57
	v_cmp_ge_u32_e64 s[12:13], v217, s57
	v_cmp_ge_u32_e64 s[14:15], v218, s57
	v_cmp_ge_u32_e64 s[16:17], v219, s57
	s_bcnt1_i32_b64 s89, s[8:9]
	s_bcnt1_i32_b64 s61, s[12:13]
	s_add_u32 s89, s89, s61
	s_bcnt1_i32_b64 s61, s[14:15]
	s_add_u32 s89, s89, s61
	s_bcnt1_i32_b64 s61, s[16:17]
	s_add_u32 s89, s89, s61
	s_cmp_ge_u32 s89, s91
	s_cselect_b32 s33, s57, s33
	s_cmp_eq_u32 s89, s91
	s_cbranch_scc1 .Lref_e4
	s_or_b32 s57, s33, 0x40
	v_cmp_ge_u32_e64 s[8:9], v216, s57
	v_cmp_ge_u32_e64 s[12:13], v217, s57
	v_cmp_ge_u32_e64 s[14:15], v218, s57
	v_cmp_ge_u32_e64 s[16:17], v219, s57
	s_bcnt1_i32_b64 s89, s[8:9]
	s_bcnt1_i32_b64 s61, s[12:13]
	s_add_u32 s89, s89, s61
	s_bcnt1_i32_b64 s61, s[14:15]
	s_add_u32 s89, s89, s61
	s_bcnt1_i32_b64 s61, s[16:17]
	s_add_u32 s89, s89, s61
	s_cmp_ge_u32 s89, s91
	s_cselect_b32 s33, s57, s33
	s_cmp_eq_u32 s89, s91
	s_cbranch_scc1 .Lref_e4
	s_or_b32 s57, s33, 0x20
	v_cmp_ge_u32_e64 s[8:9], v216, s57
	v_cmp_ge_u32_e64 s[12:13], v217, s57
	v_cmp_ge_u32_e64 s[14:15], v218, s57
	v_cmp_ge_u32_e64 s[16:17], v219, s57
	s_bcnt1_i32_b64 s89, s[8:9]
	s_bcnt1_i32_b64 s61, s[12:13]
	s_add_u32 s89, s89, s61
	s_bcnt1_i32_b64 s61, s[14:15]
	s_add_u32 s89, s89, s61
	s_bcnt1_i32_b64 s61, s[16:17]
	s_add_u32 s89, s89, s61
	s_cmp_ge_u32 s89, s91
	s_cselect_b32 s33, s57, s33
	s_cmp_eq_u32 s89, s91
	s_cbranch_scc1 .Lref_e4
	s_or_b32 s57, s33, 0x10
	v_cmp_ge_u32_e64 s[8:9], v216, s57
	v_cmp_ge_u32_e64 s[12:13], v217, s57
	v_cmp_ge_u32_e64 s[14:15], v218, s57
	v_cmp_ge_u32_e64 s[16:17], v219, s57
	s_bcnt1_i32_b64 s89, s[8:9]
	s_bcnt1_i32_b64 s61, s[12:13]
	s_add_u32 s89, s89, s61
	s_bcnt1_i32_b64 s61, s[14:15]
	s_add_u32 s89, s89, s61
	s_bcnt1_i32_b64 s61, s[16:17]
	s_add_u32 s89, s89, s61
	s_cmp_ge_u32 s89, s91
	s_cselect_b32 s33, s57, s33
	s_cmp_eq_u32 s89, s91
	s_cbranch_scc1 .Lref_e4
	s_or_b32 s57, s33, 0x8
	v_cmp_ge_u32_e64 s[8:9], v216, s57
	v_cmp_ge_u32_e64 s[12:13], v217, s57
	v_cmp_ge_u32_e64 s[14:15], v218, s57
	v_cmp_ge_u32_e64 s[16:17], v219, s57
	s_bcnt1_i32_b64 s89, s[8:9]
	s_bcnt1_i32_b64 s61, s[12:13]
	s_add_u32 s89, s89, s61
	s_bcnt1_i32_b64 s61, s[14:15]
	s_add_u32 s89, s89, s61
	s_bcnt1_i32_b64 s61, s[16:17]
	s_add_u32 s89, s89, s61
	s_cmp_ge_u32 s89, s91
	s_cselect_b32 s33, s57, s33
	s_cmp_eq_u32 s89, s91
	s_cbranch_scc1 .Lref_e4
	s_or_b32 s57, s33, 0x4
	v_cmp_ge_u32_e64 s[8:9], v216, s57
	v_cmp_ge_u32_e64 s[12:13], v217, s57
	v_cmp_ge_u32_e64 s[14:15], v218, s57
	v_cmp_ge_u32_e64 s[16:17], v219, s57
	s_bcnt1_i32_b64 s89, s[8:9]
	s_bcnt1_i32_b64 s61, s[12:13]
	s_add_u32 s89, s89, s61
	s_bcnt1_i32_b64 s61, s[14:15]
	s_add_u32 s89, s89, s61
	s_bcnt1_i32_b64 s61, s[16:17]
	s_add_u32 s89, s89, s61
	s_cmp_ge_u32 s89, s91
	s_cselect_b32 s33, s57, s33
	s_cmp_eq_u32 s89, s91
	s_cbranch_scc1 .Lref_e4
	s_or_b32 s57, s33, 0x2
	v_cmp_ge_u32_e64 s[8:9], v216, s57
	v_cmp_ge_u32_e64 s[12:13], v217, s57
	v_cmp_ge_u32_e64 s[14:15], v218, s57
	v_cmp_ge_u32_e64 s[16:17], v219, s57
	s_bcnt1_i32_b64 s89, s[8:9]
	s_bcnt1_i32_b64 s61, s[12:13]
	s_add_u32 s89, s89, s61
	s_bcnt1_i32_b64 s61, s[14:15]
	s_add_u32 s89, s89, s61
	s_bcnt1_i32_b64 s61, s[16:17]
	s_add_u32 s89, s89, s61
	s_cmp_ge_u32 s89, s91
	s_cselect_b32 s33, s57, s33
	s_cmp_eq_u32 s89, s91
	s_cbranch_scc1 .Lref_e4
	s_or_b32 s57, s33, 0x1
	v_cmp_ge_u32_e64 s[8:9], v216, s57
	v_cmp_ge_u32_e64 s[12:13], v217, s57
	v_cmp_ge_u32_e64 s[14:15], v218, s57
	v_cmp_ge_u32_e64 s[16:17], v219, s57
	s_bcnt1_i32_b64 s89, s[8:9]
	s_bcnt1_i32_b64 s61, s[12:13]
	s_add_u32 s89, s89, s61
	s_bcnt1_i32_b64 s61, s[14:15]
	s_add_u32 s89, s89, s61
	s_bcnt1_i32_b64 s61, s[16:17]
	s_add_u32 s89, s89, s61
	s_cmp_ge_u32 s89, s91
	s_cselect_b32 s33, s57, s33
	s_cmp_eq_u32 s89, s91
	s_cbranch_scc1 .Lref_e4
	v_cmp_gt_u32_e64 s[8:9], v216, s33
	v_cmp_gt_u32_e64 s[12:13], v217, s33
	v_cmp_gt_u32_e64 s[14:15], v218, s33
	v_cmp_gt_u32_e64 s[16:17], v219, s33
	s_bcnt1_i32_b64 s89, s[8:9]
	s_bcnt1_i32_b64 s61, s[12:13]
	s_add_u32 s89, s89, s61
	s_bcnt1_i32_b64 s61, s[14:15]
	s_add_u32 s89, s89, s61
	s_bcnt1_i32_b64 s61, s[16:17]
	s_add_u32 s89, s89, s61
	s_sub_u32 s91, s91, s89
	v_cmp_eq_u32_e64 s[8:9], v216, s33
	v_cmp_eq_u32_e64 s[12:13], v217, s33
	v_cmp_eq_u32_e64 s[14:15], v218, s33
	v_cmp_eq_u32_e64 s[16:17], v219, s33
	s_bcnt1_i32_b64 s89, s[8:9]
	s_bcnt1_i32_b64 s61, s[12:13]
	s_add_u32 s89, s89, s61
	s_bcnt1_i32_b64 s61, s[14:15]
	s_add_u32 s89, s89, s61
	s_bcnt1_i32_b64 s61, s[16:17]
	s_add_u32 s89, s89, s61
	s_add_u32 s57, s33, 1
	s_cmp_eq_u32 s91, s89
	s_cselect_b32 s57, s33, s57
	s_cselect_b32 s60, 1, 0
	s_branch .Lref_emit4

.Lref_v3:
	ds_read_u16 v224, v245
	ds_read_u16 v225, v245 offset:128
	ds_read_u16 v226, v245 offset:256
	v_cmp_gt_u32_e64 s[8:9], s93, v145
	v_add_u32_e32 v241, 64, v145
	v_cmp_gt_u32_e64 s[12:13], s93, v241
	v_add_u32_e32 v241, 128, v145
	v_cmp_gt_u32_e64 s[14:15], s93, v241
	s_waitcnt lgkmcnt(0)
	v_cndmask_b32_e64 v248, 0, v224, s[8:9]
	v_cndmask_b32_e64 v249, 0, v225, s[12:13]
	v_cndmask_b32_e64 v250, 0, v226, s[14:15]
	v_lshl_add_u32 v248, v248, 2, s89
	v_lshl_add_u32 v249, v249, 2, s89
	v_lshl_add_u32 v250, v250, 2, s89
	ds_read_b32 v216, v248
	ds_read_b32 v217, v249
	ds_read_b32 v218, v250
	s_waitcnt lgkmcnt(0)
	v_cndmask_b32_e64 v216, 0, v216, s[8:9]
	v_cndmask_b32_e64 v217, 0, v217, s[12:13]
	v_cndmask_b32_e64 v218, 0, v218, s[14:15]
	s_or_b32 s57, s33, 0x100000
	v_cmp_ge_u32_e64 s[8:9], v216, s57
	v_cmp_ge_u32_e64 s[12:13], v217, s57
	v_cmp_ge_u32_e64 s[14:15], v218, s57
	s_bcnt1_i32_b64 s89, s[8:9]
	s_bcnt1_i32_b64 s61, s[12:13]
	s_add_u32 s89, s89, s61
	s_bcnt1_i32_b64 s61, s[14:15]
	s_add_u32 s89, s89, s61
	s_cmp_ge_u32 s89, s91
	s_cselect_b32 s33, s57, s33
	s_cmp_eq_u32 s89, s91
	s_cbranch_scc1 .Lref_e3
	s_or_b32 s57, s33, 0x80000
	v_cmp_ge_u32_e64 s[8:9], v216, s57
	v_cmp_ge_u32_e64 s[12:13], v217, s57
	v_cmp_ge_u32_e64 s[14:15], v218, s57
	s_bcnt1_i32_b64 s89, s[8:9]
	s_bcnt1_i32_b64 s61, s[12:13]
	s_add_u32 s89, s89, s61
	s_bcnt1_i32_b64 s61, s[14:15]
	s_add_u32 s89, s89, s61
	s_cmp_ge_u32 s89, s91
	s_cselect_b32 s33, s57, s33
	s_cmp_eq_u32 s89, s91
	s_cbranch_scc1 .Lref_e3
	s_or_b32 s57, s33, 0x40000
	v_cmp_ge_u32_e64 s[8:9], v216, s57
	v_cmp_ge_u32_e64 s[12:13], v217, s57
	v_cmp_ge_u32_e64 s[14:15], v218, s57
	s_bcnt1_i32_b64 s89, s[8:9]
	s_bcnt1_i32_b64 s61, s[12:13]
	s_add_u32 s89, s89, s61
	s_bcnt1_i32_b64 s61, s[14:15]
	s_add_u32 s89, s89, s61
	s_cmp_ge_u32 s89, s91
	s_cselect_b32 s33, s57, s33
	s_cmp_eq_u32 s89, s91
	s_cbranch_scc1 .Lref_e3
	s_or_b32 s57, s33, 0x20000
	v_cmp_ge_u32_e64 s[8:9], v216, s57
	v_cmp_ge_u32_e64 s[12:13], v217, s57
	v_cmp_ge_u32_e64 s[14:15], v218, s57
	s_bcnt1_i32_b64 s89, s[8:9]
	s_bcnt1_i32_b64 s61, s[12:13]
	s_add_u32 s89, s89, s61
	s_bcnt1_i32_b64 s61, s[14:15]
	s_add_u32 s89, s89, s61
	s_cmp_ge_u32 s89, s91
	s_cselect_b32 s33, s57, s33
	s_cmp_eq_u32 s89, s91
	s_cbranch_scc1 .Lref_e3
	s_or_b32 s57, s33, 0x10000
	v_cmp_ge_u32_e64 s[8:9], v216, s57
	v_cmp_ge_u32_e64 s[12:13], v217, s57
	v_cmp_ge_u32_e64 s[14:15], v218, s57
	s_bcnt1_i32_b64 s89, s[8:9]
	s_bcnt1_i32_b64 s61, s[12:13]
	s_add_u32 s89, s89, s61
	s_bcnt1_i32_b64 s61, s[14:15]
	s_add_u32 s89, s89, s61
	s_cmp_ge_u32 s89, s91
	s_cselect_b32 s33, s57, s33
	s_cmp_eq_u32 s89, s91
	s_cbranch_scc1 .Lref_e3
	s_or_b32 s57, s33, 0x8000
	v_cmp_ge_u32_e64 s[8:9], v216, s57
	v_cmp_ge_u32_e64 s[12:13], v217, s57
	v_cmp_ge_u32_e64 s[14:15], v218, s57
	s_bcnt1_i32_b64 s89, s[8:9]
	s_bcnt1_i32_b64 s61, s[12:13]
	s_add_u32 s89, s89, s61
	s_bcnt1_i32_b64 s61, s[14:15]
	s_add_u32 s89, s89, s61
	s_cmp_ge_u32 s89, s91
	s_cselect_b32 s33, s57, s33
	s_cmp_eq_u32 s89, s91
	s_cbranch_scc1 .Lref_e3
	s_or_b32 s57, s33, 0x4000
	v_cmp_ge_u32_e64 s[8:9], v216, s57
	v_cmp_ge_u32_e64 s[12:13], v217, s57
	v_cmp_ge_u32_e64 s[14:15], v218, s57
	s_bcnt1_i32_b64 s89, s[8:9]
	s_bcnt1_i32_b64 s61, s[12:13]
	s_add_u32 s89, s89, s61
	s_bcnt1_i32_b64 s61, s[14:15]
	s_add_u32 s89, s89, s61
	s_cmp_ge_u32 s89, s91
	s_cselect_b32 s33, s57, s33
	s_cmp_eq_u32 s89, s91
	s_cbranch_scc1 .Lref_e3
	s_or_b32 s57, s33, 0x2000
	v_cmp_ge_u32_e64 s[8:9], v216, s57
	v_cmp_ge_u32_e64 s[12:13], v217, s57
	v_cmp_ge_u32_e64 s[14:15], v218, s57
	s_bcnt1_i32_b64 s89, s[8:9]
	s_bcnt1_i32_b64 s61, s[12:13]
	s_add_u32 s89, s89, s61
	s_bcnt1_i32_b64 s61, s[14:15]
	s_add_u32 s89, s89, s61
	s_cmp_ge_u32 s89, s91
	s_cselect_b32 s33, s57, s33
	s_cmp_eq_u32 s89, s91
	s_cbranch_scc1 .Lref_e3
	s_or_b32 s57, s33, 0x1000
	v_cmp_ge_u32_e64 s[8:9], v216, s57
	v_cmp_ge_u32_e64 s[12:13], v217, s57
	v_cmp_ge_u32_e64 s[14:15], v218, s57
	s_bcnt1_i32_b64 s89, s[8:9]
	s_bcnt1_i32_b64 s61, s[12:13]
	s_add_u32 s89, s89, s61
	s_bcnt1_i32_b64 s61, s[14:15]
	s_add_u32 s89, s89, s61
	s_cmp_ge_u32 s89, s91
	s_cselect_b32 s33, s57, s33
	s_cmp_eq_u32 s89, s91
	s_cbranch_scc1 .Lref_e3
	s_or_b32 s57, s33, 0x800
	v_cmp_ge_u32_e64 s[8:9], v216, s57
	v_cmp_ge_u32_e64 s[12:13], v217, s57
	v_cmp_ge_u32_e64 s[14:15], v218, s57
	s_bcnt1_i32_b64 s89, s[8:9]
	s_bcnt1_i32_b64 s61, s[12:13]
	s_add_u32 s89, s89, s61
	s_bcnt1_i32_b64 s61, s[14:15]
	s_add_u32 s89, s89, s61
	s_cmp_ge_u32 s89, s91
	s_cselect_b32 s33, s57, s33
	s_cmp_eq_u32 s89, s91
	s_cbranch_scc1 .Lref_e3
	s_or_b32 s57, s33, 0x400
	v_cmp_ge_u32_e64 s[8:9], v216, s57
	v_cmp_ge_u32_e64 s[12:13], v217, s57
	v_cmp_ge_u32_e64 s[14:15], v218, s57
	s_bcnt1_i32_b64 s89, s[8:9]
	s_bcnt1_i32_b64 s61, s[12:13]
	s_add_u32 s89, s89, s61
	s_bcnt1_i32_b64 s61, s[14:15]
	s_add_u32 s89, s89, s61
	s_cmp_ge_u32 s89, s91
	s_cselect_b32 s33, s57, s33
	s_cmp_eq_u32 s89, s91
	s_cbranch_scc1 .Lref_e3
	s_or_b32 s57, s33, 0x200
	v_cmp_ge_u32_e64 s[8:9], v216, s57
	v_cmp_ge_u32_e64 s[12:13], v217, s57
	v_cmp_ge_u32_e64 s[14:15], v218, s57
	s_bcnt1_i32_b64 s89, s[8:9]
	s_bcnt1_i32_b64 s61, s[12:13]
	s_add_u32 s89, s89, s61
	s_bcnt1_i32_b64 s61, s[14:15]
	s_add_u32 s89, s89, s61
	s_cmp_ge_u32 s89, s91
	s_cselect_b32 s33, s57, s33
	s_cmp_eq_u32 s89, s91
	s_cbranch_scc1 .Lref_e3
	s_or_b32 s57, s33, 0x100
	v_cmp_ge_u32_e64 s[8:9], v216, s57
	v_cmp_ge_u32_e64 s[12:13], v217, s57
	v_cmp_ge_u32_e64 s[14:15], v218, s57
	s_bcnt1_i32_b64 s89, s[8:9]
	s_bcnt1_i32_b64 s61, s[12:13]
	s_add_u32 s89, s89, s61
	s_bcnt1_i32_b64 s61, s[14:15]
	s_add_u32 s89, s89, s61
	s_cmp_ge_u32 s89, s91
	s_cselect_b32 s33, s57, s33
	s_cmp_eq_u32 s89, s91
	s_cbranch_scc1 .Lref_e3
	s_or_b32 s57, s33, 0x80
	v_cmp_ge_u32_e64 s[8:9], v216, s57
	v_cmp_ge_u32_e64 s[12:13], v217, s57
	v_cmp_ge_u32_e64 s[14:15], v218, s57
	s_bcnt1_i32_b64 s89, s[8:9]
	s_bcnt1_i32_b64 s61, s[12:13]
	s_add_u32 s89, s89, s61
	s_bcnt1_i32_b64 s61, s[14:15]
	s_add_u32 s89, s89, s61
	s_cmp_ge_u32 s89, s91
	s_cselect_b32 s33, s57, s33
	s_cmp_eq_u32 s89, s91
	s_cbranch_scc1 .Lref_e3
	s_or_b32 s57, s33, 0x40
	v_cmp_ge_u32_e64 s[8:9], v216, s57
	v_cmp_ge_u32_e64 s[12:13], v217, s57
	v_cmp_ge_u32_e64 s[14:15], v218, s57
	s_bcnt1_i32_b64 s89, s[8:9]
	s_bcnt1_i32_b64 s61, s[12:13]
	s_add_u32 s89, s89, s61
	s_bcnt1_i32_b64 s61, s[14:15]
	s_add_u32 s89, s89, s61
	s_cmp_ge_u32 s89, s91
	s_cselect_b32 s33, s57, s33
	s_cmp_eq_u32 s89, s91
	s_cbranch_scc1 .Lref_e3
	s_or_b32 s57, s33, 0x20
	v_cmp_ge_u32_e64 s[8:9], v216, s57
	v_cmp_ge_u32_e64 s[12:13], v217, s57
	v_cmp_ge_u32_e64 s[14:15], v218, s57
	s_bcnt1_i32_b64 s89, s[8:9]
	s_bcnt1_i32_b64 s61, s[12:13]
	s_add_u32 s89, s89, s61
	s_bcnt1_i32_b64 s61, s[14:15]
	s_add_u32 s89, s89, s61
	s_cmp_ge_u32 s89, s91
	s_cselect_b32 s33, s57, s33
	s_cmp_eq_u32 s89, s91
	s_cbranch_scc1 .Lref_e3
	s_or_b32 s57, s33, 0x10
	v_cmp_ge_u32_e64 s[8:9], v216, s57
	v_cmp_ge_u32_e64 s[12:13], v217, s57
	v_cmp_ge_u32_e64 s[14:15], v218, s57
	s_bcnt1_i32_b64 s89, s[8:9]
	s_bcnt1_i32_b64 s61, s[12:13]
	s_add_u32 s89, s89, s61
	s_bcnt1_i32_b64 s61, s[14:15]
	s_add_u32 s89, s89, s61
	s_cmp_ge_u32 s89, s91
	s_cselect_b32 s33, s57, s33
	s_cmp_eq_u32 s89, s91
	s_cbranch_scc1 .Lref_e3
	s_or_b32 s57, s33, 0x8
	v_cmp_ge_u32_e64 s[8:9], v216, s57
	v_cmp_ge_u32_e64 s[12:13], v217, s57
	v_cmp_ge_u32_e64 s[14:15], v218, s57
	s_bcnt1_i32_b64 s89, s[8:9]
	s_bcnt1_i32_b64 s61, s[12:13]
	s_add_u32 s89, s89, s61
	s_bcnt1_i32_b64 s61, s[14:15]
	s_add_u32 s89, s89, s61
	s_cmp_ge_u32 s89, s91
	s_cselect_b32 s33, s57, s33
	s_cmp_eq_u32 s89, s91
	s_cbranch_scc1 .Lref_e3
	s_or_b32 s57, s33, 0x4
	v_cmp_ge_u32_e64 s[8:9], v216, s57
	v_cmp_ge_u32_e64 s[12:13], v217, s57
	v_cmp_ge_u32_e64 s[14:15], v218, s57
	s_bcnt1_i32_b64 s89, s[8:9]
	s_bcnt1_i32_b64 s61, s[12:13]
	s_add_u32 s89, s89, s61
	s_bcnt1_i32_b64 s61, s[14:15]
	s_add_u32 s89, s89, s61
	s_cmp_ge_u32 s89, s91
	s_cselect_b32 s33, s57, s33
	s_cmp_eq_u32 s89, s91
	s_cbranch_scc1 .Lref_e3
	s_or_b32 s57, s33, 0x2
	v_cmp_ge_u32_e64 s[8:9], v216, s57
	v_cmp_ge_u32_e64 s[12:13], v217, s57
	v_cmp_ge_u32_e64 s[14:15], v218, s57
	s_bcnt1_i32_b64 s89, s[8:9]
	s_bcnt1_i32_b64 s61, s[12:13]
	s_add_u32 s89, s89, s61
	s_bcnt1_i32_b64 s61, s[14:15]
	s_add_u32 s89, s89, s61
	s_cmp_ge_u32 s89, s91
	s_cselect_b32 s33, s57, s33
	s_cmp_eq_u32 s89, s91
	s_cbranch_scc1 .Lref_e3
	s_or_b32 s57, s33, 0x1
	v_cmp_ge_u32_e64 s[8:9], v216, s57
	v_cmp_ge_u32_e64 s[12:13], v217, s57
	v_cmp_ge_u32_e64 s[14:15], v218, s57
	s_bcnt1_i32_b64 s89, s[8:9]
	s_bcnt1_i32_b64 s61, s[12:13]
	s_add_u32 s89, s89, s61
	s_bcnt1_i32_b64 s61, s[14:15]
	s_add_u32 s89, s89, s61
	s_cmp_ge_u32 s89, s91
	s_cselect_b32 s33, s57, s33
	s_cmp_eq_u32 s89, s91
	s_cbranch_scc1 .Lref_e3
	v_cmp_gt_u32_e64 s[8:9], v216, s33
	v_cmp_gt_u32_e64 s[12:13], v217, s33
	v_cmp_gt_u32_e64 s[14:15], v218, s33
	s_bcnt1_i32_b64 s89, s[8:9]
	s_bcnt1_i32_b64 s61, s[12:13]
	s_add_u32 s89, s89, s61
	s_bcnt1_i32_b64 s61, s[14:15]
	s_add_u32 s89, s89, s61
	s_sub_u32 s91, s91, s89
	v_cmp_eq_u32_e64 s[8:9], v216, s33
	v_cmp_eq_u32_e64 s[12:13], v217, s33
	v_cmp_eq_u32_e64 s[14:15], v218, s33
	s_bcnt1_i32_b64 s89, s[8:9]
	s_bcnt1_i32_b64 s61, s[12:13]
	s_add_u32 s89, s89, s61
	s_bcnt1_i32_b64 s61, s[14:15]
	s_add_u32 s89, s89, s61
	s_add_u32 s57, s33, 1
	s_cmp_eq_u32 s91, s89
	s_cselect_b32 s57, s33, s57
	s_cselect_b32 s60, 1, 0
	s_branch .Lref_emit3

.Lref_v2:
	ds_read_u16 v224, v245
	ds_read_u16 v225, v245 offset:128
	v_cmp_gt_u32_e64 s[8:9], s93, v145
	v_add_u32_e32 v241, 64, v145
	v_cmp_gt_u32_e64 s[12:13], s93, v241
	s_waitcnt lgkmcnt(0)
	v_cndmask_b32_e64 v248, 0, v224, s[8:9]
	v_cndmask_b32_e64 v249, 0, v225, s[12:13]
	v_lshl_add_u32 v248, v248, 2, s89
	v_lshl_add_u32 v249, v249, 2, s89
	ds_read_b32 v216, v248
	ds_read_b32 v217, v249
	s_waitcnt lgkmcnt(0)
	v_cndmask_b32_e64 v216, 0, v216, s[8:9]
	v_cndmask_b32_e64 v217, 0, v217, s[12:13]
	s_or_b32 s57, s33, 0x100000
	v_cmp_ge_u32_e64 s[8:9], v216, s57
	v_cmp_ge_u32_e64 s[12:13], v217, s57
	s_bcnt1_i32_b64 s89, s[8:9]
	s_bcnt1_i32_b64 s61, s[12:13]
	s_add_u32 s89, s89, s61
	s_cmp_ge_u32 s89, s91
	s_cselect_b32 s33, s57, s33
	s_cmp_eq_u32 s89, s91
	s_cbranch_scc1 .Lref_e2
	s_or_b32 s57, s33, 0x80000
	v_cmp_ge_u32_e64 s[8:9], v216, s57
	v_cmp_ge_u32_e64 s[12:13], v217, s57
	s_bcnt1_i32_b64 s89, s[8:9]
	s_bcnt1_i32_b64 s61, s[12:13]
	s_add_u32 s89, s89, s61
	s_cmp_ge_u32 s89, s91
	s_cselect_b32 s33, s57, s33
	s_cmp_eq_u32 s89, s91
	s_cbranch_scc1 .Lref_e2
	s_or_b32 s57, s33, 0x40000
	v_cmp_ge_u32_e64 s[8:9], v216, s57
	v_cmp_ge_u32_e64 s[12:13], v217, s57
	s_bcnt1_i32_b64 s89, s[8:9]
	s_bcnt1_i32_b64 s61, s[12:13]
	s_add_u32 s89, s89, s61
	s_cmp_ge_u32 s89, s91
	s_cselect_b32 s33, s57, s33
	s_cmp_eq_u32 s89, s91
	s_cbranch_scc1 .Lref_e2
	s_or_b32 s57, s33, 0x20000
	v_cmp_ge_u32_e64 s[8:9], v216, s57
	v_cmp_ge_u32_e64 s[12:13], v217, s57
	s_bcnt1_i32_b64 s89, s[8:9]
	s_bcnt1_i32_b64 s61, s[12:13]
	s_add_u32 s89, s89, s61
	s_cmp_ge_u32 s89, s91
	s_cselect_b32 s33, s57, s33
	s_cmp_eq_u32 s89, s91
	s_cbranch_scc1 .Lref_e2
	s_or_b32 s57, s33, 0x10000
	v_cmp_ge_u32_e64 s[8:9], v216, s57
	v_cmp_ge_u32_e64 s[12:13], v217, s57
	s_bcnt1_i32_b64 s89, s[8:9]
	s_bcnt1_i32_b64 s61, s[12:13]
	s_add_u32 s89, s89, s61
	s_cmp_ge_u32 s89, s91
	s_cselect_b32 s33, s57, s33
	s_cmp_eq_u32 s89, s91
	s_cbranch_scc1 .Lref_e2
	s_or_b32 s57, s33, 0x8000
	v_cmp_ge_u32_e64 s[8:9], v216, s57
	v_cmp_ge_u32_e64 s[12:13], v217, s57
	s_bcnt1_i32_b64 s89, s[8:9]
	s_bcnt1_i32_b64 s61, s[12:13]
	s_add_u32 s89, s89, s61
	s_cmp_ge_u32 s89, s91
	s_cselect_b32 s33, s57, s33
	s_cmp_eq_u32 s89, s91
	s_cbranch_scc1 .Lref_e2
	s_or_b32 s57, s33, 0x4000
	v_cmp_ge_u32_e64 s[8:9], v216, s57
	v_cmp_ge_u32_e64 s[12:13], v217, s57
	s_bcnt1_i32_b64 s89, s[8:9]
	s_bcnt1_i32_b64 s61, s[12:13]
	s_add_u32 s89, s89, s61
	s_cmp_ge_u32 s89, s91
	s_cselect_b32 s33, s57, s33
	s_cmp_eq_u32 s89, s91
	s_cbranch_scc1 .Lref_e2
	s_or_b32 s57, s33, 0x2000
	v_cmp_ge_u32_e64 s[8:9], v216, s57
	v_cmp_ge_u32_e64 s[12:13], v217, s57
	s_bcnt1_i32_b64 s89, s[8:9]
	s_bcnt1_i32_b64 s61, s[12:13]
	s_add_u32 s89, s89, s61
	s_cmp_ge_u32 s89, s91
	s_cselect_b32 s33, s57, s33
	s_cmp_eq_u32 s89, s91
	s_cbranch_scc1 .Lref_e2
	s_or_b32 s57, s33, 0x1000
	v_cmp_ge_u32_e64 s[8:9], v216, s57
	v_cmp_ge_u32_e64 s[12:13], v217, s57
	s_bcnt1_i32_b64 s89, s[8:9]
	s_bcnt1_i32_b64 s61, s[12:13]
	s_add_u32 s89, s89, s61
	s_cmp_ge_u32 s89, s91
	s_cselect_b32 s33, s57, s33
	s_cmp_eq_u32 s89, s91
	s_cbranch_scc1 .Lref_e2
	s_or_b32 s57, s33, 0x800
	v_cmp_ge_u32_e64 s[8:9], v216, s57
	v_cmp_ge_u32_e64 s[12:13], v217, s57
	s_bcnt1_i32_b64 s89, s[8:9]
	s_bcnt1_i32_b64 s61, s[12:13]
	s_add_u32 s89, s89, s61
	s_cmp_ge_u32 s89, s91
	s_cselect_b32 s33, s57, s33
	s_cmp_eq_u32 s89, s91
	s_cbranch_scc1 .Lref_e2
	s_or_b32 s57, s33, 0x400
	v_cmp_ge_u32_e64 s[8:9], v216, s57
	v_cmp_ge_u32_e64 s[12:13], v217, s57
	s_bcnt1_i32_b64 s89, s[8:9]
	s_bcnt1_i32_b64 s61, s[12:13]
	s_add_u32 s89, s89, s61
	s_cmp_ge_u32 s89, s91
	s_cselect_b32 s33, s57, s33
	s_cmp_eq_u32 s89, s91
	s_cbranch_scc1 .Lref_e2
	s_or_b32 s57, s33, 0x200
	v_cmp_ge_u32_e64 s[8:9], v216, s57
	v_cmp_ge_u32_e64 s[12:13], v217, s57
	s_bcnt1_i32_b64 s89, s[8:9]
	s_bcnt1_i32_b64 s61, s[12:13]
	s_add_u32 s89, s89, s61
	s_cmp_ge_u32 s89, s91
	s_cselect_b32 s33, s57, s33
	s_cmp_eq_u32 s89, s91
	s_cbranch_scc1 .Lref_e2
	s_or_b32 s57, s33, 0x100
	v_cmp_ge_u32_e64 s[8:9], v216, s57
	v_cmp_ge_u32_e64 s[12:13], v217, s57
	s_bcnt1_i32_b64 s89, s[8:9]
	s_bcnt1_i32_b64 s61, s[12:13]
	s_add_u32 s89, s89, s61
	s_cmp_ge_u32 s89, s91
	s_cselect_b32 s33, s57, s33
	s_cmp_eq_u32 s89, s91
	s_cbranch_scc1 .Lref_e2
	s_or_b32 s57, s33, 0x80
	v_cmp_ge_u32_e64 s[8:9], v216, s57
	v_cmp_ge_u32_e64 s[12:13], v217, s57
	s_bcnt1_i32_b64 s89, s[8:9]
	s_bcnt1_i32_b64 s61, s[12:13]
	s_add_u32 s89, s89, s61
	s_cmp_ge_u32 s89, s91
	s_cselect_b32 s33, s57, s33
	s_cmp_eq_u32 s89, s91
	s_cbranch_scc1 .Lref_e2
	s_or_b32 s57, s33, 0x40
	v_cmp_ge_u32_e64 s[8:9], v216, s57
	v_cmp_ge_u32_e64 s[12:13], v217, s57
	s_bcnt1_i32_b64 s89, s[8:9]
	s_bcnt1_i32_b64 s61, s[12:13]
	s_add_u32 s89, s89, s61
	s_cmp_ge_u32 s89, s91
	s_cselect_b32 s33, s57, s33
	s_cmp_eq_u32 s89, s91
	s_cbranch_scc1 .Lref_e2
	s_or_b32 s57, s33, 0x20
	v_cmp_ge_u32_e64 s[8:9], v216, s57
	v_cmp_ge_u32_e64 s[12:13], v217, s57
	s_bcnt1_i32_b64 s89, s[8:9]
	s_bcnt1_i32_b64 s61, s[12:13]
	s_add_u32 s89, s89, s61
	s_cmp_ge_u32 s89, s91
	s_cselect_b32 s33, s57, s33
	s_cmp_eq_u32 s89, s91
	s_cbranch_scc1 .Lref_e2
	s_or_b32 s57, s33, 0x10
	v_cmp_ge_u32_e64 s[8:9], v216, s57
	v_cmp_ge_u32_e64 s[12:13], v217, s57
	s_bcnt1_i32_b64 s89, s[8:9]
	s_bcnt1_i32_b64 s61, s[12:13]
	s_add_u32 s89, s89, s61
	s_cmp_ge_u32 s89, s91
	s_cselect_b32 s33, s57, s33
	s_cmp_eq_u32 s89, s91
	s_cbranch_scc1 .Lref_e2
	s_or_b32 s57, s33, 0x8
	v_cmp_ge_u32_e64 s[8:9], v216, s57
	v_cmp_ge_u32_e64 s[12:13], v217, s57
	s_bcnt1_i32_b64 s89, s[8:9]
	s_bcnt1_i32_b64 s61, s[12:13]
	s_add_u32 s89, s89, s61
	s_cmp_ge_u32 s89, s91
	s_cselect_b32 s33, s57, s33
	s_cmp_eq_u32 s89, s91
	s_cbranch_scc1 .Lref_e2
	s_or_b32 s57, s33, 0x4
	v_cmp_ge_u32_e64 s[8:9], v216, s57
	v_cmp_ge_u32_e64 s[12:13], v217, s57
	s_bcnt1_i32_b64 s89, s[8:9]
	s_bcnt1_i32_b64 s61, s[12:13]
	s_add_u32 s89, s89, s61
	s_cmp_ge_u32 s89, s91
	s_cselect_b32 s33, s57, s33
	s_cmp_eq_u32 s89, s91
	s_cbranch_scc1 .Lref_e2
	s_or_b32 s57, s33, 0x2
	v_cmp_ge_u32_e64 s[8:9], v216, s57
	v_cmp_ge_u32_e64 s[12:13], v217, s57
	s_bcnt1_i32_b64 s89, s[8:9]
	s_bcnt1_i32_b64 s61, s[12:13]
	s_add_u32 s89, s89, s61
	s_cmp_ge_u32 s89, s91
	s_cselect_b32 s33, s57, s33
	s_cmp_eq_u32 s89, s91
	s_cbranch_scc1 .Lref_e2
	s_or_b32 s57, s33, 0x1
	v_cmp_ge_u32_e64 s[8:9], v216, s57
	v_cmp_ge_u32_e64 s[12:13], v217, s57
	s_bcnt1_i32_b64 s89, s[8:9]
	s_bcnt1_i32_b64 s61, s[12:13]
	s_add_u32 s89, s89, s61
	s_cmp_ge_u32 s89, s91
	s_cselect_b32 s33, s57, s33
	s_cmp_eq_u32 s89, s91
	s_cbranch_scc1 .Lref_e2
	v_cmp_gt_u32_e64 s[8:9], v216, s33
	v_cmp_gt_u32_e64 s[12:13], v217, s33
	s_bcnt1_i32_b64 s89, s[8:9]
	s_bcnt1_i32_b64 s61, s[12:13]
	s_add_u32 s89, s89, s61
	s_sub_u32 s91, s91, s89
	v_cmp_eq_u32_e64 s[8:9], v216, s33
	v_cmp_eq_u32_e64 s[12:13], v217, s33
	s_bcnt1_i32_b64 s89, s[8:9]
	s_bcnt1_i32_b64 s61, s[12:13]
	s_add_u32 s89, s89, s61
	s_add_u32 s57, s33, 1
	s_cmp_eq_u32 s91, s89
	s_cselect_b32 s57, s33, s57
	s_cselect_b32 s60, 1, 0
	s_branch .Lref_emit2

.Lref_v1:
	ds_read_u16 v224, v245
	v_cmp_gt_u32_e64 s[8:9], s93, v145
	s_waitcnt lgkmcnt(0)
	v_cndmask_b32_e64 v248, 0, v224, s[8:9]
	v_lshl_add_u32 v248, v248, 2, s89
	ds_read_b32 v216, v248
	s_waitcnt lgkmcnt(0)
	v_cndmask_b32_e64 v216, 0, v216, s[8:9]
	s_or_b32 s57, s33, 0x100000
	v_cmp_ge_u32_e64 s[8:9], v216, s57
	s_bcnt1_i32_b64 s89, s[8:9]
	s_cmp_ge_u32 s89, s91
	s_cselect_b32 s33, s57, s33
	s_cmp_eq_u32 s89, s91
	s_cbranch_scc1 .Lref_e1
	s_or_b32 s57, s33, 0x80000
	v_cmp_ge_u32_e64 s[8:9], v216, s57
	s_bcnt1_i32_b64 s89, s[8:9]
	s_cmp_ge_u32 s89, s91
	s_cselect_b32 s33, s57, s33
	s_cmp_eq_u32 s89, s91
	s_cbranch_scc1 .Lref_e1
	s_or_b32 s57, s33, 0x40000
	v_cmp_ge_u32_e64 s[8:9], v216, s57
	s_bcnt1_i32_b64 s89, s[8:9]
	s_cmp_ge_u32 s89, s91
	s_cselect_b32 s33, s57, s33
	s_cmp_eq_u32 s89, s91
	s_cbranch_scc1 .Lref_e1
	s_or_b32 s57, s33, 0x20000
	v_cmp_ge_u32_e64 s[8:9], v216, s57
	s_bcnt1_i32_b64 s89, s[8:9]
	s_cmp_ge_u32 s89, s91
	s_cselect_b32 s33, s57, s33
	s_cmp_eq_u32 s89, s91
	s_cbranch_scc1 .Lref_e1
	s_or_b32 s57, s33, 0x10000
	v_cmp_ge_u32_e64 s[8:9], v216, s57
	s_bcnt1_i32_b64 s89, s[8:9]
	s_cmp_ge_u32 s89, s91
	s_cselect_b32 s33, s57, s33
	s_cmp_eq_u32 s89, s91
	s_cbranch_scc1 .Lref_e1
	s_or_b32 s57, s33, 0x8000
	v_cmp_ge_u32_e64 s[8:9], v216, s57
	s_bcnt1_i32_b64 s89, s[8:9]
	s_cmp_ge_u32 s89, s91
	s_cselect_b32 s33, s57, s33
	s_cmp_eq_u32 s89, s91
	s_cbranch_scc1 .Lref_e1
	s_or_b32 s57, s33, 0x4000
	v_cmp_ge_u32_e64 s[8:9], v216, s57
	s_bcnt1_i32_b64 s89, s[8:9]
	s_cmp_ge_u32 s89, s91
	s_cselect_b32 s33, s57, s33
	s_cmp_eq_u32 s89, s91
	s_cbranch_scc1 .Lref_e1
	s_or_b32 s57, s33, 0x2000
	v_cmp_ge_u32_e64 s[8:9], v216, s57
	s_bcnt1_i32_b64 s89, s[8:9]
	s_cmp_ge_u32 s89, s91
	s_cselect_b32 s33, s57, s33
	s_cmp_eq_u32 s89, s91
	s_cbranch_scc1 .Lref_e1
	s_or_b32 s57, s33, 0x1000
	v_cmp_ge_u32_e64 s[8:9], v216, s57
	s_bcnt1_i32_b64 s89, s[8:9]
	s_cmp_ge_u32 s89, s91
	s_cselect_b32 s33, s57, s33
	s_cmp_eq_u32 s89, s91
	s_cbranch_scc1 .Lref_e1
	s_or_b32 s57, s33, 0x800
	v_cmp_ge_u32_e64 s[8:9], v216, s57
	s_bcnt1_i32_b64 s89, s[8:9]
	s_cmp_ge_u32 s89, s91
	s_cselect_b32 s33, s57, s33
	s_cmp_eq_u32 s89, s91
	s_cbranch_scc1 .Lref_e1
	s_or_b32 s57, s33, 0x400
	v_cmp_ge_u32_e64 s[8:9], v216, s57
	s_bcnt1_i32_b64 s89, s[8:9]
	s_cmp_ge_u32 s89, s91
	s_cselect_b32 s33, s57, s33
	s_cmp_eq_u32 s89, s91
	s_cbranch_scc1 .Lref_e1
	s_or_b32 s57, s33, 0x200
	v_cmp_ge_u32_e64 s[8:9], v216, s57
	s_bcnt1_i32_b64 s89, s[8:9]
	s_cmp_ge_u32 s89, s91
	s_cselect_b32 s33, s57, s33
	s_cmp_eq_u32 s89, s91
	s_cbranch_scc1 .Lref_e1
	s_or_b32 s57, s33, 0x100
	v_cmp_ge_u32_e64 s[8:9], v216, s57
	s_bcnt1_i32_b64 s89, s[8:9]
	s_cmp_ge_u32 s89, s91
	s_cselect_b32 s33, s57, s33
	s_cmp_eq_u32 s89, s91
	s_cbranch_scc1 .Lref_e1
	s_or_b32 s57, s33, 0x80
	v_cmp_ge_u32_e64 s[8:9], v216, s57
	s_bcnt1_i32_b64 s89, s[8:9]
	s_cmp_ge_u32 s89, s91
	s_cselect_b32 s33, s57, s33
	s_cmp_eq_u32 s89, s91
	s_cbranch_scc1 .Lref_e1
	s_or_b32 s57, s33, 0x40
	v_cmp_ge_u32_e64 s[8:9], v216, s57
	s_bcnt1_i32_b64 s89, s[8:9]
	s_cmp_ge_u32 s89, s91
	s_cselect_b32 s33, s57, s33
	s_cmp_eq_u32 s89, s91
	s_cbranch_scc1 .Lref_e1
	s_or_b32 s57, s33, 0x20
	v_cmp_ge_u32_e64 s[8:9], v216, s57
	s_bcnt1_i32_b64 s89, s[8:9]
	s_cmp_ge_u32 s89, s91
	s_cselect_b32 s33, s57, s33
	s_cmp_eq_u32 s89, s91
	s_cbranch_scc1 .Lref_e1
	s_or_b32 s57, s33, 0x10
	v_cmp_ge_u32_e64 s[8:9], v216, s57
	s_bcnt1_i32_b64 s89, s[8:9]
	s_cmp_ge_u32 s89, s91
	s_cselect_b32 s33, s57, s33
	s_cmp_eq_u32 s89, s91
	s_cbranch_scc1 .Lref_e1
	s_or_b32 s57, s33, 0x8
	v_cmp_ge_u32_e64 s[8:9], v216, s57
	s_bcnt1_i32_b64 s89, s[8:9]
	s_cmp_ge_u32 s89, s91
	s_cselect_b32 s33, s57, s33
	s_cmp_eq_u32 s89, s91
	s_cbranch_scc1 .Lref_e1
	s_or_b32 s57, s33, 0x4
	v_cmp_ge_u32_e64 s[8:9], v216, s57
	s_bcnt1_i32_b64 s89, s[8:9]
	s_cmp_ge_u32 s89, s91
	s_cselect_b32 s33, s57, s33
	s_cmp_eq_u32 s89, s91
	s_cbranch_scc1 .Lref_e1
	s_or_b32 s57, s33, 0x2
	v_cmp_ge_u32_e64 s[8:9], v216, s57
	s_bcnt1_i32_b64 s89, s[8:9]
	s_cmp_ge_u32 s89, s91
	s_cselect_b32 s33, s57, s33
	s_cmp_eq_u32 s89, s91
	s_cbranch_scc1 .Lref_e1
	s_or_b32 s57, s33, 0x1
	v_cmp_ge_u32_e64 s[8:9], v216, s57
	s_bcnt1_i32_b64 s89, s[8:9]
	s_cmp_ge_u32 s89, s91
	s_cselect_b32 s33, s57, s33
	s_cmp_eq_u32 s89, s91
	s_cbranch_scc1 .Lref_e1
	v_cmp_gt_u32_e64 s[8:9], v216, s33
	s_bcnt1_i32_b64 s89, s[8:9]
	s_sub_u32 s91, s91, s89
	v_cmp_eq_u32_e64 s[8:9], v216, s33
	s_bcnt1_i32_b64 s89, s[8:9]
	s_add_u32 s57, s33, 1
	s_cmp_eq_u32 s91, s89
	s_cselect_b32 s57, s33, s57
	s_cselect_b32 s60, 1, 0
	s_branch .Lref_emit1

.LBB0_975:
	s_or_b64 exec, exec, s[4:5]
	v_mov_b32_e32 v15, v202
	s_add_u32 s62, s28, 0x14000000
	s_waitcnt lgkmcnt(0)
	s_barrier
	s_nop 0
	s_nop 0
	s_nop 0
	s_nop 0
	s_nop 0
	s_nop 0
	s_nop 0
	s_nop 0
	s_nop 0
	s_nop 0
	s_nop 0
	s_nop 0
	s_addc_u32 s63, s29, 0
	v_readfirstlane_b32 s4, v15
	s_ashr_i32 s4, s4, 6
	s_and_b64 s[6:7], s[46:47], exec
	s_cselect_b32 s5, 8, 1
	v_cvt_f32_ubyte0_e32 v1, s5
	v_rcp_iflag_f32_e32 v1, v1
	s_add_i32 s8, s5, -1
	s_and_b64 s[6:7], s[46:47], exec
	s_cselect_b32 s24, 3, 0
	v_mul_f32_e32 v1, 0x4f7ffffe, v1
	v_cvt_u32_f32_e32 v1, v1
	s_sub_i32 s9, 0, s5
	s_abs_i32 s7, s30
	s_lshr_b32 s6, s2, s24
	v_readfirstlane_b32 s10, v1
	s_mul_i32 s9, s9, s10
	s_mul_hi_u32 s9, s10, s9
	s_add_i32 s10, s10, s9
	s_mul_hi_u32 s9, s7, s10
	s_mul_i32 s10, s9, s5
	s_sub_i32 s7, s7, s10
	s_lshl_b32 s6, s6, 3
	s_ashr_i32 s68, s30, 31
	s_add_i32 s10, s9, 1
	s_sub_i32 s11, s7, s5
	s_cmp_ge_u32 s7, s5
	s_cselect_b32 s9, s10, s9
	s_cselect_b32 s7, s11, s7
	s_add_i32 s10, s9, 1
	s_cmp_ge_u32 s7, s5
	s_cselect_b32 s7, s10, s9
	s_xor_b32 s7, s7, s68
	s_sub_i32 s7, s7, s68
	s_lshl_b32 s25, s7, 3
	s_abs_i32 s7, s25
	v_cvt_f32_u32_e32 v1, s7
	s_add_i32 s40, s4, s6
	s_sub_i32 s6, s25, s40
	s_and_b32 s41, s8, s2
	v_rcp_iflag_f32_e32 v1, v1
	s_add_i32 s8, s6, 0x1fff
	s_sub_i32 s6, 0xffffe001, s6
	s_xor_b32 s9, s8, s25
	v_mul_f32_e32 v1, 0x4f7ffffe, v1
	v_cvt_u32_f32_e32 v1, v1
	s_max_i32 s6, s8, s6
	s_sub_i32 s8, 0, s7
	s_ashr_i32 s9, s9, 31
	v_readfirstlane_b32 s10, v1
	s_mul_i32 s8, s8, s10
	s_mul_hi_u32 s8, s10, s8
	s_add_i32 s10, s10, s8
	s_mul_hi_u32 s8, s6, s10
	s_mul_i32 s10, s8, s7
	s_sub_i32 s6, s6, s10
	s_add_i32 s10, s8, 1
	s_sub_i32 s11, s6, s7
	s_cmp_ge_u32 s6, s7
	s_cselect_b32 s8, s10, s8
	s_cselect_b32 s6, s11, s6
	s_add_i32 s10, s8, 1
	s_cmp_ge_u32 s6, s7
	s_cselect_b32 s6, s10, s8
	s_sub_i32 s5, s5, s41
	s_xor_b32 s6, s6, s9
	s_add_i32 s5, s5, 15
	s_sub_i32 s42, s6, s9
	s_lshr_b32 s5, s5, s24
	s_mul_i32 s43, s42, s5
	s_cmp_lt_i32 s43, 1
	s_mov_b32 s9, 0
	s_cbranch_scc1 .LBB0_980
	s_lshl_b32 s5, s4, 14
	s_lshl_b32 s4, s4, 10
	s_add_i32 s47, s4, 0
	s_lshr_b32 s8, s41, 2
	s_add_i32 s46, s5, 0
	s_add_i32 s47, s47, 0x20000
	s_and_b32 s10, s41, 3
	s_lshl_b64 s[4:5], s[8:9], 13
	s_ashr_i32 s6, s40, 31
	s_add_u32 s4, s4, s40
	s_addc_u32 s5, s5, s6
	s_lshl_b64 s[6:7], s[4:5], 9
	v_and_b32_e32 v14, 63, v15
	s_add_u32 s6, s44, s6
	s_addc_u32 s7, s45, s7
	v_lshlrev_b32_e32 v42, 3, v14
	global_load_dwordx2 v[2:3], v42, s[6:7]
	v_and_b32_e32 v17, 15, v15
	v_bfe_u32 v4, v15, 4, 2
	v_bfe_u32 v6, v15, 2, 2
	v_and_b32_e32 v1, 7, v15
	v_lshlrev_b32_e32 v34, 3, v15
	v_mov_b32_e32 v7, 0x1000
	v_lshrrev_b32_e32 v9, 3, v15
	v_or_b32_e32 v12, 16, v17
	v_lshl_or_b32 v6, v4, 2, v6
	v_bfe_u32 v5, v15, 3, 1
	v_and_b32_e32 v10, 1, v15
	v_bitop3_b32 v13, v4, v1, 4 bitop3:0x36
	v_bitop3_b32 v16, v4, v15, 7 bitop3:0x78
	v_and_or_b32 v7, v34, 24, v7
	v_xor_b32_e32 v9, v9, v15
	v_mul_u32_u24_e32 v21, 0x40004, v14
	v_lshrrev_b32_e32 v22, 3, v12
	v_lshlrev_b32_e32 v24, 4, v6
	v_lshlrev_b32_e32 v6, 7, v6
	s_cmpk_gt_i32 s40, 0xff
	s_movk_i32 s6, 0x60
	v_lshlrev_b32_e32 v12, 7, v12
	v_xor_b32_e32 v23, v13, v5
	v_xor_b32_e32 v5, v16, v5
	v_and_or_b32 v9, v9, 6, v10
	v_or_b32_e32 v60, 0x10000, v21
	v_or_b32_e32 v61, 0x30002, v21
	v_xor_b32_e32 v10, v13, v22
	v_xor_b32_e32 v13, v16, v22
	v_or_b32_e32 v16, 0x800, v6
	v_or_b32_e32 v6, v6, v7
	s_cselect_b64 vcc, -1, 0
	v_lshlrev_b32_e32 v11, 6, v15
	s_waitcnt vmcnt(2)
	v_lshlrev_b32_e32 v52, 4, v9
	v_add_u32_e32 v9, s47, v42
	v_lshl_or_b32 v37, v10, 4, v12
	v_bitop3_b32 v10, v24, v16, s6 bitop3:0xce
	v_bitop3_b32 v39, v24, v6, s6 bitop3:0xce
	s_mul_hi_u32 s6, s4, 0x1200
	s_mulk_i32 s5, 0x1200
	s_mulk_i32 s4, 0x1200
	s_add_i32 s6, s6, s5
	v_mov_b32_e32 v43, 0
	s_add_u32 s4, s38, s4
	v_mov_b32_e32 v8, 0x60
	v_lshlrev_b32_e32 v19, 7, v17
	s_addc_u32 s5, s39, s6
	v_lshl_or_b32 v35, v23, 4, v19
	v_lshl_or_b32 v36, v5, 4, v19
	v_and_b32_e32 v5, 0x60, v24
	v_bitop3_b32 v19, v24, 64, v8 bitop3:0x6c
	v_bitop3_b32 v8, v24, 32, v8 bitop3:0x6c
	v_bfe_u32 v18, v15, 3, 3
	v_lshl_or_b32 v38, v13, 4, v12
	v_or_b32_e32 v12, v19, v16
	v_or_b32_e32 v13, v8, v16
	v_or_b32_e32 v41, v8, v6
	v_or_b32_e32 v8, v5, v16
	s_waitcnt vmcnt(1)
	v_or_b32_e32 v56, v6, v5
	v_lshlrev_b32_e32 v16, 3, v4
	v_and_b32_e32 v4, 48, v15
	v_mov_b32_e32 v5, v43
	v_lshlrev_b32_e32 v63, 6, v18
	v_bitop3_b32 v20, v18, v15, 7 bitop3:0x78
	v_or_b32_e32 v40, v19, v6
	v_add_u32_e32 v57, v10, v7
	v_add_u32_e32 v58, v12, v7
	v_add_u32_e32 v59, v13, v7
	v_add_u32_e32 v90, v8, v7
	v_add_u32_e32 v18, s47, v63
	v_mov_b32_e32 v19, v43
	v_lshlrev_b32_e32 v44, 4, v20
	v_mov_b32_e32 v45, v43
	s_mov_b32 m0, s46
	v_mov_b32_e32 v53, v43
	v_mov_b32_e32 v64, 9
	v_xor_b32_e32 v50, 16, v44
	v_mov_b32_e32 v51, v43
	v_xor_b32_e32 v48, 32, v44
	s_waitcnt vmcnt(0)
	v_cndmask_b32_e32 v2, v60, v2, vcc
	v_cndmask_b32_e32 v3, v61, v3, vcc
	ds_write_b64 v9, v[2:3]
	v_and_b32_e32 v2, 0xc0, v11
	v_lshlrev_b32_e32 v62, 1, v2
	v_lshl_or_b32 v2, s10, 9, v62
	v_mov_b32_e32 v3, v43
	v_lshl_add_u64 v[2:3], s[4:5], 0, v[2:3]
	s_lshl_b64 s[4:5], s[8:9], 22
	s_add_u32 s6, s80, s4
	v_lshl_add_u64 v[2:3], v[2:3], 0, v[4:5]
	s_addc_u32 s7, s81, s5
	global_load_dwordx4 v[10:13], v[2:3], off
	global_load_dwordx4 v[6:9], v[2:3], off offset:64
	s_waitcnt lgkmcnt(0)
	s_add_u32 s4, s37, s4
	ds_read_b128 v[30:33], v18
	ds_read_b128 v[22:25], v18 offset:16
	ds_read_b128 v[2:5], v18 offset:32
	ds_read_b128 v[26:29], v18 offset:48
	s_addc_u32 s5, s79, s5
	s_lshl_b32 s8, s10, 7
	s_add_u32 s4, s4, s8
	s_addc_u32 s5, s5, 0
	s_waitcnt lgkmcnt(3)
	v_lshlrev_b32_e32 v18, 9, v30
	s_add_u32 s6, s6, s8
	v_and_b32_e32 v18, 0x1fffe00, v18
	s_addc_u32 s7, s7, 0
	v_lshl_add_u64 v[20:21], s[4:5], 0, v[18:19]
	s_add_i32 s48, s46, 0x1000
	v_lshl_add_u64 v[20:21], v[20:21], 0, v[44:45]
	v_lshl_add_u64 v[18:19], s[6:7], 0, v[18:19]
	global_load_lds_dwordx4 v[20:21], off
	v_lshl_add_u64 v[18:19], v[18:19], 0, v[52:53]
	s_mov_b32 m0, s48
	s_add_i32 s49, s46, 0x400
	global_load_lds_dwordx4 v[18:19], off
	v_lshlrev_b32_sdwa v18, v64, v30 dst_sel:DWORD dst_unused:UNUSED_PAD src0_sel:DWORD src1_sel:WORD_1
	v_mov_b32_e32 v19, v43
	v_lshl_add_u64 v[20:21], s[4:5], 0, v[18:19]
	v_lshl_add_u64 v[20:21], v[20:21], 0, v[50:51]
	s_mov_b32 m0, s49
	v_lshl_add_u64 v[18:19], s[6:7], 0, v[18:19]
	s_add_i32 s50, s46, 0x1400
	global_load_lds_dwordx4 v[20:21], off
	v_lshl_add_u64 v[18:19], v[18:19], 0, v[52:53]
	s_mov_b32 m0, s50
	v_mov_b32_e32 v49, v43
	global_load_lds_dwordx4 v[18:19], off
	v_lshlrev_b32_e32 v18, 9, v31
	v_and_b32_e32 v18, 0x1fffe00, v18
	v_mov_b32_e32 v19, v43
	v_lshl_add_u64 v[20:21], s[4:5], 0, v[18:19]
	s_add_i32 s51, s46, 0x800
	v_lshl_add_u64 v[20:21], v[20:21], 0, v[48:49]
	s_mov_b32 m0, s51
	v_lshl_add_u64 v[18:19], s[6:7], 0, v[18:19]
	s_add_i32 s52, s46, 0x1800
	global_load_lds_dwordx4 v[20:21], off
	v_lshl_add_u64 v[18:19], v[18:19], 0, v[52:53]
	s_mov_b32 m0, s52
	v_xor_b32_e32 v46, 48, v44
	global_load_lds_dwordx4 v[18:19], off
	v_lshlrev_b32_sdwa v18, v64, v31 dst_sel:DWORD dst_unused:UNUSED_PAD src0_sel:DWORD src1_sel:WORD_1
	v_mov_b32_e32 v19, v43
	v_lshl_add_u64 v[20:21], s[4:5], 0, v[18:19]
	v_mov_b32_e32 v47, v43
	s_add_i32 s53, s46, 0xc00
	v_lshl_add_u64 v[20:21], v[20:21], 0, v[46:47]
	s_mov_b32 m0, s53
	v_lshl_add_u64 v[18:19], s[6:7], 0, v[18:19]
	s_add_i32 s54, s46, 0x1c00
	global_load_lds_dwordx4 v[20:21], off
	v_lshl_add_u64 v[18:19], v[18:19], 0, v[52:53]
	s_mov_b32 m0, s54
	v_cmp_gt_u32_e64 s[4:5], 4, v17
	global_load_lds_dwordx4 v[18:19], off
	v_and_b32_e32 v17, 0x80, v34
	v_bfe_u32 v15, v15, 5, 1
	v_or_b32_e32 v19, 32, v17
	v_or_b32_e32 v20, 64, v17
	v_or_b32_e32 v21, 0x60, v17
	v_or_b32_e32 v30, 6, v15
	v_or_b32_e32 v82, v17, v30
	v_or_b32_e32 v84, v19, v30
	v_or_b32_e32 v86, v20, v30
	v_or_b32_e32 v88, v21, v30
	v_or_b32_e32 v30, 10, v15
	v_or_b32_e32 v18, 2, v15
	v_or_b32_e32 v98, v17, v30
	v_or_b32_e32 v100, v19, v30
	v_or_b32_e32 v102, v20, v30
	v_or_b32_e32 v104, v21, v30
	v_or_b32_e32 v30, 14, v15
	v_or_b32_e32 v66, v17, v18
	v_or_b32_e32 v68, v19, v18
	v_or_b32_e32 v70, v20, v18
	v_or_b32_e32 v72, v21, v18
	v_or_b32_e32 v18, 4, v15
	v_or_b32_e32 v106, v17, v30
	v_or_b32_e32 v108, v19, v30
	v_or_b32_e32 v110, v20, v30
	v_or_b32_e32 v112, v21, v30
	v_or_b32_e32 v30, 18, v15
	v_or_b32_e32 v81, v17, v18
	v_or_b32_e32 v83, v19, v18
	v_or_b32_e32 v85, v20, v18
	v_or_b32_e32 v87, v21, v18
	v_or_b32_e32 v18, 8, v15
	v_or_b32_e32 v114, v17, v30
	v_or_b32_e32 v116, v19, v30
	v_or_b32_e32 v118, v20, v30
	v_or_b32_e32 v120, v21, v30
	v_or_b32_e32 v30, 22, v15
	v_lshl_add_u64 v[54:55], s[44:45], 0, v[42:43]
	v_or_b32_e32 v97, v17, v18
	v_or_b32_e32 v99, v19, v18
	v_or_b32_e32 v101, v20, v18
	v_or_b32_e32 v103, v21, v18
	v_or_b32_e32 v18, 12, v15
	v_or_b32_e32 v122, v17, v30
	v_or_b32_e32 v124, v19, v30
	v_or_b32_e32 v126, v20, v30
	v_or_b32_e32 v128, v21, v30
	v_or_b32_e32 v30, 26, v15
	s_abs_i32 s45, s42
	v_or_b32_e32 v105, v17, v18
	v_or_b32_e32 v107, v19, v18
	v_or_b32_e32 v109, v20, v18
	v_or_b32_e32 v111, v21, v18
	v_or_b32_e32 v18, 16, v15
	v_or_b32_e32 v130, v17, v30
	v_or_b32_e32 v132, v19, v30
	v_or_b32_e32 v134, v20, v30
	v_or_b32_e32 v136, v21, v30
	v_cvt_f32_u32_e32 v30, s45
	v_or_b32_e32 v113, v17, v18
	v_or_b32_e32 v115, v19, v18
	v_or_b32_e32 v117, v20, v18
	v_or_b32_e32 v119, v21, v18
	v_or_b32_e32 v18, 20, v15
	v_or_b32_e32 v121, v17, v18
	v_or_b32_e32 v123, v19, v18
	v_or_b32_e32 v125, v20, v18
	v_or_b32_e32 v127, v21, v18
	v_or_b32_e32 v18, 24, v15
	v_or_b32_e32 v65, v17, v15
	v_or_b32_e32 v67, v19, v15
	v_or_b32_e32 v69, v20, v15
	v_or_b32_e32 v71, v21, v15
	v_or_b32_e32 v129, v17, v18
	v_or_b32_e32 v131, v19, v18
	v_or_b32_e32 v133, v20, v18
	v_or_b32_e32 v135, v21, v18
	v_or_b32_e32 v18, 28, v15
	v_or_b32_e32 v15, 30, v15
	v_or_b32_e32 v137, v17, v18
	v_or_b32_e32 v138, v17, v15
	v_rcp_iflag_f32_e32 v17, v30
	s_sub_i32 s8, 0, s45
	s_add_i32 s44, s46, 0x2000
	v_lshlrev_b32_e32 v1, 2, v14
	v_mul_f32_e32 v17, 0x4f7ffffe, v17
	v_cvt_u32_f32_e32 v17, v17
	s_waitcnt vmcnt(0)
	v_cndmask_b32_e64 v9, 0, v9, s[4:5]
	v_cndmask_b32_e64 v8, 0, v8, s[4:5]
	v_cndmask_b32_e64 v7, 0, v7, s[4:5]
	v_readfirstlane_b32 s10, v17
	s_mul_i32 s8, s8, s10
	s_mul_hi_u32 s8, s10, s8
	v_cndmask_b32_e64 v6, 0, v6, s[4:5]
	v_cndmask_b32_e64 v13, 0, v13, s[4:5]
	v_cndmask_b32_e64 v12, 0, v12, s[4:5]
	v_cndmask_b32_e64 v11, 0, v11, s[4:5]
	v_cndmask_b32_e64 v10, 0, v10, s[4:5]
	v_cmp_gt_u32_e64 s[6:7], 16, v14
	v_add_u32_e32 v73, s46, v56
	v_add_u32_e32 v74, s46, v90
	v_add_u32_e32 v75, s46, v41
	v_add_u32_e32 v76, s46, v59
	v_add_u32_e32 v77, s46, v40
	v_add_u32_e32 v78, s46, v58
	v_add_u32_e32 v79, s46, v39
	v_add_u32_e32 v80, s46, v57
	v_add_u32_e32 v89, s44, v56
	v_add_u32_e32 v90, s44, v90
	v_add_u32_e32 v91, s44, v41
	v_add_u32_e32 v92, s44, v59
	v_add_u32_e32 v93, s44, v40
	v_add_u32_e32 v94, s44, v58
	v_add_u32_e32 v95, s44, v39
	v_add_u32_e32 v96, s44, v57
	v_or_b32_e32 v139, v19, v18
	v_or_b32_e32 v140, v19, v15
	v_or_b32_e32 v141, v20, v18
	v_or_b32_e32 v142, v20, v15
	v_or_b32_e32 v143, v21, v18
	v_or_b32_e32 v144, v21, v15
	s_ashr_i32 s55, s42, 31
	s_add_i32 s56, s10, s8
	s_sub_i32 s57, 0, s42
	v_lshlrev_b32_e32 v56, 1, v16
	s_add_i32 s58, s46, 0x3000
	s_add_i32 s59, s46, 0x2400
	s_add_i32 s60, s46, 0x3400
	s_add_i32 s61, s46, 0x2800
	s_add_i32 s64, s46, 0x3800
	s_add_i32 s65, s46, 0x2c00
	s_add_i32 s66, s46, 0x3c00
	v_add_u32_e32 v145, s46, v36
	v_add_u32_e32 v149, s46, v35
	v_add_u32_e32 v151, s46, v38
	v_add_u32_e32 v153, s46, v37
	v_lshlrev_b32_e32 v58, 1, v14
	s_movk_i32 s67, 0x7fff
	s_mov_b32 s69, 0
	s_mov_b32 s70, 0
	s_branch .LBB0_978
